# poolfold rewritten: pool_w block staged to LDS by DMA, PB*scale in registers, per-accumulator fma chains from broadcast ds_read_b128
# speedup vs baseline: 1.0465x; 1.0155x over previous
.LBB0_621:
	v_readlane_b32 s14, v255, 15
	v_lshlrev_b32_e32 v170, 4, v246
	v_lshrrev_b32_e32 v171, 5, v246
	v_lshlrev_b32_e32 v171, 8, v171
	s_mov_b32 m0, s14
	v_add_u32_e32 v171, s14, v171
	v_readfirstlane_b32 s14, v28
	v_readfirstlane_b32 s15, v29
	s_add_u32 s14, s14, s97
	s_addc_u32 s15, s15, 0
	s_nop 4
	global_load_lds_dwordx4 v170, s[14:15]
	s_add_i32 m0, m0, 0x400
	v_add_u32_e32 v170, 0x400, v170
	global_load_lds_dwordx4 v170, s[14:15]
	s_add_i32 m0, m0, 0x400
	v_add_u32_e32 v170, 0x400, v170
	global_load_lds_dwordx4 v170, s[14:15]
	s_add_i32 m0, m0, 0x400
	v_add_u32_e32 v170, 0x400, v170
	global_load_lds_dwordx4 v170, s[14:15]
	s_add_i32 m0, m0, 0x400
	v_add_u32_e32 v170, 0x400, v170
	global_load_lds_dwordx4 v170, s[14:15]
	s_add_i32 m0, m0, 0x400
	v_add_u32_e32 v170, 0x400, v170
	global_load_lds_dwordx4 v170, s[14:15]
	s_add_i32 m0, m0, 0x400
	v_add_u32_e32 v170, 0x400, v170
	global_load_lds_dwordx4 v170, s[14:15]
	s_add_i32 m0, m0, 0x400
	v_add_u32_e32 v170, 0x400, v170
	global_load_lds_dwordx4 v170, s[14:15]
	s_add_i32 m0, m0, 0x400
	v_add_u32_e32 v170, 0x400, v170
	global_load_lds_dwordx4 v170, s[14:15]
	s_add_i32 m0, m0, 0x400
	v_add_u32_e32 v170, 0x400, v170
	global_load_lds_dwordx4 v170, s[14:15]
	s_add_i32 m0, m0, 0x400
	v_add_u32_e32 v170, 0x400, v170
	global_load_lds_dwordx4 v170, s[14:15]
	s_add_i32 m0, m0, 0x400
	v_add_u32_e32 v170, 0x400, v170
	global_load_lds_dwordx4 v170, s[14:15]
	s_add_i32 m0, m0, 0x400
	v_add_u32_e32 v170, 0x400, v170
	global_load_lds_dwordx4 v170, s[14:15]
	s_add_i32 m0, m0, 0x400
	v_add_u32_e32 v170, 0x400, v170
	global_load_lds_dwordx4 v170, s[14:15]
	s_add_i32 m0, m0, 0x400
	v_add_u32_e32 v170, 0x400, v170
	global_load_lds_dwordx4 v170, s[14:15]
	s_add_i32 m0, m0, 0x400
	v_add_u32_e32 v170, 0x400, v170
	global_load_lds_dwordx4 v170, s[14:15]
	s_mov_b32 s14, s8
	s_mov_b32 s15, s18
	global_load_dword v200, v[80:81], off
	v_lshl_add_u64 v[80:81], v[80:81], 0, s[20:21]
	global_load_dword v174, v97, s[14:15] offset:0
	global_load_dword v201, v[80:81], off
	v_lshl_add_u64 v[80:81], v[80:81], 0, s[20:21]
	global_load_dword v175, v97, s[14:15] offset:4
	global_load_dword v202, v[80:81], off
	v_lshl_add_u64 v[80:81], v[80:81], 0, s[20:21]
	global_load_dword v176, v97, s[14:15] offset:8
	global_load_dword v203, v[80:81], off
	v_lshl_add_u64 v[80:81], v[80:81], 0, s[20:21]
	global_load_dword v177, v97, s[14:15] offset:12
	global_load_dword v204, v[80:81], off
	v_lshl_add_u64 v[80:81], v[80:81], 0, s[20:21]
	global_load_dword v178, v97, s[14:15] offset:16
	global_load_dword v205, v[80:81], off
	v_lshl_add_u64 v[80:81], v[80:81], 0, s[20:21]
	global_load_dword v179, v97, s[14:15] offset:20
	global_load_dword v206, v[80:81], off
	v_lshl_add_u64 v[80:81], v[80:81], 0, s[20:21]
	global_load_dword v180, v97, s[14:15] offset:24
	global_load_dword v207, v[80:81], off
	v_lshl_add_u64 v[80:81], v[80:81], 0, s[20:21]
	global_load_dword v181, v97, s[14:15] offset:28
	global_load_dword v208, v[80:81], off
	v_lshl_add_u64 v[80:81], v[80:81], 0, s[20:21]
	global_load_dword v182, v97, s[14:15] offset:32
	global_load_dword v209, v[80:81], off
	v_lshl_add_u64 v[80:81], v[80:81], 0, s[20:21]
	global_load_dword v183, v97, s[14:15] offset:36
	global_load_dword v210, v[80:81], off
	v_lshl_add_u64 v[80:81], v[80:81], 0, s[20:21]
	global_load_dword v184, v97, s[14:15] offset:40
	global_load_dword v211, v[80:81], off
	v_lshl_add_u64 v[80:81], v[80:81], 0, s[20:21]
	global_load_dword v185, v97, s[14:15] offset:44
	global_load_dword v212, v[80:81], off
	v_lshl_add_u64 v[80:81], v[80:81], 0, s[20:21]
	global_load_dword v186, v97, s[14:15] offset:48
	global_load_dword v213, v[80:81], off
	v_lshl_add_u64 v[80:81], v[80:81], 0, s[20:21]
	global_load_dword v187, v97, s[14:15] offset:52
	global_load_dword v214, v[80:81], off
	v_lshl_add_u64 v[80:81], v[80:81], 0, s[20:21]
	global_load_dword v188, v97, s[14:15] offset:56
	global_load_dword v215, v[80:81], off
	v_lshl_add_u64 v[80:81], v[80:81], 0, s[20:21]
	global_load_dword v189, v97, s[14:15] offset:60
	s_waitcnt vmcnt(30)
	global_load_dword v216, v[80:81], off
	v_lshl_add_u64 v[80:81], v[80:81], 0, s[20:21]
	global_load_dword v190, v97, s[14:15] offset:64
	global_load_dword v217, v[80:81], off
	v_lshl_add_u64 v[80:81], v[80:81], 0, s[20:21]
	global_load_dword v191, v97, s[14:15] offset:68
	global_load_dword v218, v[80:81], off
	v_lshl_add_u64 v[80:81], v[80:81], 0, s[20:21]
	global_load_dword v192, v97, s[14:15] offset:72
	global_load_dword v219, v[80:81], off
	v_lshl_add_u64 v[80:81], v[80:81], 0, s[20:21]
	global_load_dword v193, v97, s[14:15] offset:76
	global_load_dword v220, v[80:81], off
	v_lshl_add_u64 v[80:81], v[80:81], 0, s[20:21]
	global_load_dword v194, v97, s[14:15] offset:80
	global_load_dword v221, v[80:81], off
	v_lshl_add_u64 v[80:81], v[80:81], 0, s[20:21]
	global_load_dword v195, v97, s[14:15] offset:84
	global_load_dword v222, v[80:81], off
	v_lshl_add_u64 v[80:81], v[80:81], 0, s[20:21]
	global_load_dword v196, v97, s[14:15] offset:88
	global_load_dword v223, v[80:81], off
	v_lshl_add_u64 v[80:81], v[80:81], 0, s[20:21]
	global_load_dword v197, v97, s[14:15] offset:92
	global_load_dword v224, v[80:81], off
	v_lshl_add_u64 v[80:81], v[80:81], 0, s[20:21]
	global_load_dword v232, v97, s[14:15] offset:96
	global_load_dword v225, v[80:81], off
	v_lshl_add_u64 v[80:81], v[80:81], 0, s[20:21]
	global_load_dword v233, v97, s[14:15] offset:100
	global_load_dword v226, v[80:81], off
	v_lshl_add_u64 v[80:81], v[80:81], 0, s[20:21]
	global_load_dword v234, v97, s[14:15] offset:104
	global_load_dword v227, v[80:81], off
	v_lshl_add_u64 v[80:81], v[80:81], 0, s[20:21]
	global_load_dword v235, v97, s[14:15] offset:108
	global_load_dword v228, v[80:81], off
	v_lshl_add_u64 v[80:81], v[80:81], 0, s[20:21]
	global_load_dword v236, v97, s[14:15] offset:112
	global_load_dword v229, v[80:81], off
	v_lshl_add_u64 v[80:81], v[80:81], 0, s[20:21]
	global_load_dword v237, v97, s[14:15] offset:116
	global_load_dword v230, v[80:81], off
	v_lshl_add_u64 v[80:81], v[80:81], 0, s[20:21]
	global_load_dword v238, v97, s[14:15] offset:120
	global_load_dword v231, v[80:81], off
	v_lshl_add_u64 v[80:81], v[80:81], 0, s[20:21]
	global_load_dword v239, v97, s[14:15] offset:124
	s_waitcnt vmcnt(0)
	v_mul_f32_e32 v200, v200, v174
	v_mul_f32_e32 v201, v201, v175
	v_mul_f32_e32 v202, v202, v176
	v_mul_f32_e32 v203, v203, v177
	v_mul_f32_e32 v204, v204, v178
	v_mul_f32_e32 v205, v205, v179
	v_mul_f32_e32 v206, v206, v180
	v_mul_f32_e32 v207, v207, v181
	v_mul_f32_e32 v208, v208, v182
	v_mul_f32_e32 v209, v209, v183
	v_mul_f32_e32 v210, v210, v184
	v_mul_f32_e32 v211, v211, v185
	v_mul_f32_e32 v212, v212, v186
	v_mul_f32_e32 v213, v213, v187
	v_mul_f32_e32 v214, v214, v188
	v_mul_f32_e32 v215, v215, v189
	v_mul_f32_e32 v216, v216, v190
	v_mul_f32_e32 v217, v217, v191
	v_mul_f32_e32 v218, v218, v192
	v_mul_f32_e32 v219, v219, v193
	v_mul_f32_e32 v220, v220, v194
	v_mul_f32_e32 v221, v221, v195
	v_mul_f32_e32 v222, v222, v196
	v_mul_f32_e32 v223, v223, v197
	v_mul_f32_e32 v224, v224, v232
	v_mul_f32_e32 v225, v225, v233
	v_mul_f32_e32 v226, v226, v234
	v_mul_f32_e32 v227, v227, v235
	v_mul_f32_e32 v228, v228, v236
	v_mul_f32_e32 v229, v229, v237
	v_mul_f32_e32 v230, v230, v238
	v_mul_f32_e32 v231, v231, v239
	ds_read_b128 v[174:177], v171 offset:0
	ds_read_b128 v[178:181], v171 offset:16
	ds_read_b128 v[182:185], v171 offset:32
	ds_read_b128 v[186:189], v171 offset:48
	ds_read_b128 v[190:193], v171 offset:64
	ds_read_b128 v[194:197], v171 offset:80
	ds_read_b128 v[232:235], v171 offset:96
	ds_read_b128 v[236:239], v171 offset:112
	s_waitcnt lgkmcnt(4)
	v_fmac_f32_e32 v82, v200, v174
	v_fmac_f32_e32 v82, v201, v175
	v_fmac_f32_e32 v82, v202, v176
	v_fmac_f32_e32 v82, v203, v177
	v_fmac_f32_e32 v82, v204, v178
	v_fmac_f32_e32 v82, v205, v179
	v_fmac_f32_e32 v82, v206, v180
	v_fmac_f32_e32 v82, v207, v181
	v_fmac_f32_e32 v82, v208, v182
	v_fmac_f32_e32 v82, v209, v183
	v_fmac_f32_e32 v82, v210, v184
	v_fmac_f32_e32 v82, v211, v185
	v_fmac_f32_e32 v82, v212, v186
	v_fmac_f32_e32 v82, v213, v187
	v_fmac_f32_e32 v82, v214, v188
	v_fmac_f32_e32 v82, v215, v189
	ds_read_b128 v[174:177], v171 offset:512
	ds_read_b128 v[178:181], v171 offset:528
	ds_read_b128 v[182:185], v171 offset:544
	ds_read_b128 v[186:189], v171 offset:560
	s_waitcnt lgkmcnt(4)
	v_fmac_f32_e32 v82, v216, v190
	v_fmac_f32_e32 v82, v217, v191
	v_fmac_f32_e32 v82, v218, v192
	v_fmac_f32_e32 v82, v219, v193
	v_fmac_f32_e32 v82, v220, v194
	v_fmac_f32_e32 v82, v221, v195
	v_fmac_f32_e32 v82, v222, v196
	v_fmac_f32_e32 v82, v223, v197
	v_fmac_f32_e32 v82, v224, v232
	v_fmac_f32_e32 v82, v225, v233
	v_fmac_f32_e32 v82, v226, v234
	v_fmac_f32_e32 v82, v227, v235
	v_fmac_f32_e32 v82, v228, v236
	v_fmac_f32_e32 v82, v229, v237
	v_fmac_f32_e32 v82, v230, v238
	v_fmac_f32_e32 v82, v231, v239
	ds_read_b128 v[190:193], v171 offset:576
	ds_read_b128 v[194:197], v171 offset:592
	ds_read_b128 v[232:235], v171 offset:608
	ds_read_b128 v[236:239], v171 offset:624
	s_waitcnt lgkmcnt(4)
	v_fmac_f32_e32 v83, v200, v174
	v_fmac_f32_e32 v83, v201, v175
	v_fmac_f32_e32 v83, v202, v176
	v_fmac_f32_e32 v83, v203, v177
	v_fmac_f32_e32 v83, v204, v178
	v_fmac_f32_e32 v83, v205, v179
	v_fmac_f32_e32 v83, v206, v180
	v_fmac_f32_e32 v83, v207, v181
	v_fmac_f32_e32 v83, v208, v182
	v_fmac_f32_e32 v83, v209, v183
	v_fmac_f32_e32 v83, v210, v184
	v_fmac_f32_e32 v83, v211, v185
	v_fmac_f32_e32 v83, v212, v186
	v_fmac_f32_e32 v83, v213, v187
	v_fmac_f32_e32 v83, v214, v188
	v_fmac_f32_e32 v83, v215, v189
	ds_read_b128 v[174:177], v171 offset:1024
	ds_read_b128 v[178:181], v171 offset:1040
	ds_read_b128 v[182:185], v171 offset:1056
	ds_read_b128 v[186:189], v171 offset:1072
	s_waitcnt lgkmcnt(4)
	v_fmac_f32_e32 v83, v216, v190
	v_fmac_f32_e32 v83, v217, v191
	v_fmac_f32_e32 v83, v218, v192
	v_fmac_f32_e32 v83, v219, v193
	v_fmac_f32_e32 v83, v220, v194
	v_fmac_f32_e32 v83, v221, v195
	v_fmac_f32_e32 v83, v222, v196
	v_fmac_f32_e32 v83, v223, v197
	v_fmac_f32_e32 v83, v224, v232
	v_fmac_f32_e32 v83, v225, v233
	v_fmac_f32_e32 v83, v226, v234
	v_fmac_f32_e32 v83, v227, v235
	v_fmac_f32_e32 v83, v228, v236
	v_fmac_f32_e32 v83, v229, v237
	v_fmac_f32_e32 v83, v230, v238
	v_fmac_f32_e32 v83, v231, v239
	ds_read_b128 v[190:193], v171 offset:1088
	ds_read_b128 v[194:197], v171 offset:1104
	ds_read_b128 v[232:235], v171 offset:1120
	ds_read_b128 v[236:239], v171 offset:1136
	s_waitcnt lgkmcnt(4)
	v_fmac_f32_e32 v86, v200, v174
	v_fmac_f32_e32 v86, v201, v175
	v_fmac_f32_e32 v86, v202, v176
	v_fmac_f32_e32 v86, v203, v177
	v_fmac_f32_e32 v86, v204, v178
	v_fmac_f32_e32 v86, v205, v179
	v_fmac_f32_e32 v86, v206, v180
	v_fmac_f32_e32 v86, v207, v181
	v_fmac_f32_e32 v86, v208, v182
	v_fmac_f32_e32 v86, v209, v183
	v_fmac_f32_e32 v86, v210, v184
	v_fmac_f32_e32 v86, v211, v185
	v_fmac_f32_e32 v86, v212, v186
	v_fmac_f32_e32 v86, v213, v187
	v_fmac_f32_e32 v86, v214, v188
	v_fmac_f32_e32 v86, v215, v189
	ds_read_b128 v[174:177], v171 offset:1536
	ds_read_b128 v[178:181], v171 offset:1552
	ds_read_b128 v[182:185], v171 offset:1568
	ds_read_b128 v[186:189], v171 offset:1584
	s_waitcnt lgkmcnt(4)
	v_fmac_f32_e32 v86, v216, v190
	v_fmac_f32_e32 v86, v217, v191
	v_fmac_f32_e32 v86, v218, v192
	v_fmac_f32_e32 v86, v219, v193
	v_fmac_f32_e32 v86, v220, v194
	v_fmac_f32_e32 v86, v221, v195
	v_fmac_f32_e32 v86, v222, v196
	v_fmac_f32_e32 v86, v223, v197
	v_fmac_f32_e32 v86, v224, v232
	v_fmac_f32_e32 v86, v225, v233
	v_fmac_f32_e32 v86, v226, v234
	v_fmac_f32_e32 v86, v227, v235
	v_fmac_f32_e32 v86, v228, v236
	v_fmac_f32_e32 v86, v229, v237
	v_fmac_f32_e32 v86, v230, v238
	v_fmac_f32_e32 v86, v231, v239
	ds_read_b128 v[190:193], v171 offset:1600
	ds_read_b128 v[194:197], v171 offset:1616
	ds_read_b128 v[232:235], v171 offset:1632
	ds_read_b128 v[236:239], v171 offset:1648
	s_waitcnt lgkmcnt(4)
	v_fmac_f32_e32 v87, v200, v174
	v_fmac_f32_e32 v87, v201, v175
	v_fmac_f32_e32 v87, v202, v176
	v_fmac_f32_e32 v87, v203, v177
	v_fmac_f32_e32 v87, v204, v178
	v_fmac_f32_e32 v87, v205, v179
	v_fmac_f32_e32 v87, v206, v180
	v_fmac_f32_e32 v87, v207, v181
	v_fmac_f32_e32 v87, v208, v182
	v_fmac_f32_e32 v87, v209, v183
	v_fmac_f32_e32 v87, v210, v184
	v_fmac_f32_e32 v87, v211, v185
	v_fmac_f32_e32 v87, v212, v186
	v_fmac_f32_e32 v87, v213, v187
	v_fmac_f32_e32 v87, v214, v188
	v_fmac_f32_e32 v87, v215, v189
	ds_read_b128 v[174:177], v171 offset:2048
	ds_read_b128 v[178:181], v171 offset:2064
	ds_read_b128 v[182:185], v171 offset:2080
	ds_read_b128 v[186:189], v171 offset:2096
	s_waitcnt lgkmcnt(4)
	v_fmac_f32_e32 v87, v216, v190
	v_fmac_f32_e32 v87, v217, v191
	v_fmac_f32_e32 v87, v218, v192
	v_fmac_f32_e32 v87, v219, v193
	v_fmac_f32_e32 v87, v220, v194
	v_fmac_f32_e32 v87, v221, v195
	v_fmac_f32_e32 v87, v222, v196
	v_fmac_f32_e32 v87, v223, v197
	v_fmac_f32_e32 v87, v224, v232
	v_fmac_f32_e32 v87, v225, v233
	v_fmac_f32_e32 v87, v226, v234
	v_fmac_f32_e32 v87, v227, v235
	v_fmac_f32_e32 v87, v228, v236
	v_fmac_f32_e32 v87, v229, v237
	v_fmac_f32_e32 v87, v230, v238
	v_fmac_f32_e32 v87, v231, v239
	ds_read_b128 v[190:193], v171 offset:2112
	ds_read_b128 v[194:197], v171 offset:2128
	ds_read_b128 v[232:235], v171 offset:2144
	ds_read_b128 v[236:239], v171 offset:2160
	s_waitcnt lgkmcnt(4)
	v_fmac_f32_e32 v84, v200, v174
	v_fmac_f32_e32 v84, v201, v175
	v_fmac_f32_e32 v84, v202, v176
	v_fmac_f32_e32 v84, v203, v177
	v_fmac_f32_e32 v84, v204, v178
	v_fmac_f32_e32 v84, v205, v179
	v_fmac_f32_e32 v84, v206, v180
	v_fmac_f32_e32 v84, v207, v181
	v_fmac_f32_e32 v84, v208, v182
	v_fmac_f32_e32 v84, v209, v183
	v_fmac_f32_e32 v84, v210, v184
	v_fmac_f32_e32 v84, v211, v185
	v_fmac_f32_e32 v84, v212, v186
	v_fmac_f32_e32 v84, v213, v187
	v_fmac_f32_e32 v84, v214, v188
	v_fmac_f32_e32 v84, v215, v189
	ds_read_b128 v[174:177], v171 offset:2560
	ds_read_b128 v[178:181], v171 offset:2576
	ds_read_b128 v[182:185], v171 offset:2592
	ds_read_b128 v[186:189], v171 offset:2608
	s_waitcnt lgkmcnt(4)
	v_fmac_f32_e32 v84, v216, v190
	v_fmac_f32_e32 v84, v217, v191
	v_fmac_f32_e32 v84, v218, v192
	v_fmac_f32_e32 v84, v219, v193
	v_fmac_f32_e32 v84, v220, v194
	v_fmac_f32_e32 v84, v221, v195
	v_fmac_f32_e32 v84, v222, v196
	v_fmac_f32_e32 v84, v223, v197
	v_fmac_f32_e32 v84, v224, v232
	v_fmac_f32_e32 v84, v225, v233
	v_fmac_f32_e32 v84, v226, v234
	v_fmac_f32_e32 v84, v227, v235
	v_fmac_f32_e32 v84, v228, v236
	v_fmac_f32_e32 v84, v229, v237
	v_fmac_f32_e32 v84, v230, v238
	v_fmac_f32_e32 v84, v231, v239
	ds_read_b128 v[190:193], v171 offset:2624
	ds_read_b128 v[194:197], v171 offset:2640
	ds_read_b128 v[232:235], v171 offset:2656
	ds_read_b128 v[236:239], v171 offset:2672
	s_waitcnt lgkmcnt(4)
	v_fmac_f32_e32 v85, v200, v174
	v_fmac_f32_e32 v85, v201, v175
	v_fmac_f32_e32 v85, v202, v176
	v_fmac_f32_e32 v85, v203, v177
	v_fmac_f32_e32 v85, v204, v178
	v_fmac_f32_e32 v85, v205, v179
	v_fmac_f32_e32 v85, v206, v180
	v_fmac_f32_e32 v85, v207, v181
	v_fmac_f32_e32 v85, v208, v182
	v_fmac_f32_e32 v85, v209, v183
	v_fmac_f32_e32 v85, v210, v184
	v_fmac_f32_e32 v85, v211, v185
	v_fmac_f32_e32 v85, v212, v186
	v_fmac_f32_e32 v85, v213, v187
	v_fmac_f32_e32 v85, v214, v188
	v_fmac_f32_e32 v85, v215, v189
	ds_read_b128 v[174:177], v171 offset:3072
	ds_read_b128 v[178:181], v171 offset:3088
	ds_read_b128 v[182:185], v171 offset:3104
	ds_read_b128 v[186:189], v171 offset:3120
	s_waitcnt lgkmcnt(4)
	v_fmac_f32_e32 v85, v216, v190
	v_fmac_f32_e32 v85, v217, v191
	v_fmac_f32_e32 v85, v218, v192
	v_fmac_f32_e32 v85, v219, v193
	v_fmac_f32_e32 v85, v220, v194
	v_fmac_f32_e32 v85, v221, v195
	v_fmac_f32_e32 v85, v222, v196
	v_fmac_f32_e32 v85, v223, v197
	v_fmac_f32_e32 v85, v224, v232
	v_fmac_f32_e32 v85, v225, v233
	v_fmac_f32_e32 v85, v226, v234
	v_fmac_f32_e32 v85, v227, v235
	v_fmac_f32_e32 v85, v228, v236
	v_fmac_f32_e32 v85, v229, v237
	v_fmac_f32_e32 v85, v230, v238
	v_fmac_f32_e32 v85, v231, v239
	ds_read_b128 v[190:193], v171 offset:3136
	ds_read_b128 v[194:197], v171 offset:3152
	ds_read_b128 v[232:235], v171 offset:3168
	ds_read_b128 v[236:239], v171 offset:3184
	s_waitcnt lgkmcnt(4)
	v_fmac_f32_e32 v90, v200, v174
	v_fmac_f32_e32 v90, v201, v175
	v_fmac_f32_e32 v90, v202, v176
	v_fmac_f32_e32 v90, v203, v177
	v_fmac_f32_e32 v90, v204, v178
	v_fmac_f32_e32 v90, v205, v179
	v_fmac_f32_e32 v90, v206, v180
	v_fmac_f32_e32 v90, v207, v181
	v_fmac_f32_e32 v90, v208, v182
	v_fmac_f32_e32 v90, v209, v183
	v_fmac_f32_e32 v90, v210, v184
	v_fmac_f32_e32 v90, v211, v185
	v_fmac_f32_e32 v90, v212, v186
	v_fmac_f32_e32 v90, v213, v187
	v_fmac_f32_e32 v90, v214, v188
	v_fmac_f32_e32 v90, v215, v189
	ds_read_b128 v[174:177], v171 offset:3584
	ds_read_b128 v[178:181], v171 offset:3600
	ds_read_b128 v[182:185], v171 offset:3616
	ds_read_b128 v[186:189], v171 offset:3632
	s_waitcnt lgkmcnt(4)
	v_fmac_f32_e32 v90, v216, v190
	v_fmac_f32_e32 v90, v217, v191
	v_fmac_f32_e32 v90, v218, v192
	v_fmac_f32_e32 v90, v219, v193
	v_fmac_f32_e32 v90, v220, v194
	v_fmac_f32_e32 v90, v221, v195
	v_fmac_f32_e32 v90, v222, v196
	v_fmac_f32_e32 v90, v223, v197
	v_fmac_f32_e32 v90, v224, v232
	v_fmac_f32_e32 v90, v225, v233
	v_fmac_f32_e32 v90, v226, v234
	v_fmac_f32_e32 v90, v227, v235
	v_fmac_f32_e32 v90, v228, v236
	v_fmac_f32_e32 v90, v229, v237
	v_fmac_f32_e32 v90, v230, v238
	v_fmac_f32_e32 v90, v231, v239
	ds_read_b128 v[190:193], v171 offset:3648
	ds_read_b128 v[194:197], v171 offset:3664
	ds_read_b128 v[232:235], v171 offset:3680
	ds_read_b128 v[236:239], v171 offset:3696
	s_waitcnt lgkmcnt(4)
	v_fmac_f32_e32 v91, v200, v174
	v_fmac_f32_e32 v91, v201, v175
	v_fmac_f32_e32 v91, v202, v176
	v_fmac_f32_e32 v91, v203, v177
	v_fmac_f32_e32 v91, v204, v178
	v_fmac_f32_e32 v91, v205, v179
	v_fmac_f32_e32 v91, v206, v180
	v_fmac_f32_e32 v91, v207, v181
	v_fmac_f32_e32 v91, v208, v182
	v_fmac_f32_e32 v91, v209, v183
	v_fmac_f32_e32 v91, v210, v184
	v_fmac_f32_e32 v91, v211, v185
	v_fmac_f32_e32 v91, v212, v186
	v_fmac_f32_e32 v91, v213, v187
	v_fmac_f32_e32 v91, v214, v188
	v_fmac_f32_e32 v91, v215, v189
	ds_read_b128 v[174:177], v171 offset:4096
	ds_read_b128 v[178:181], v171 offset:4112
	ds_read_b128 v[182:185], v171 offset:4128
	ds_read_b128 v[186:189], v171 offset:4144
	s_waitcnt lgkmcnt(4)
	v_fmac_f32_e32 v91, v216, v190
	v_fmac_f32_e32 v91, v217, v191
	v_fmac_f32_e32 v91, v218, v192
	v_fmac_f32_e32 v91, v219, v193
	v_fmac_f32_e32 v91, v220, v194
	v_fmac_f32_e32 v91, v221, v195
	v_fmac_f32_e32 v91, v222, v196
	v_fmac_f32_e32 v91, v223, v197
	v_fmac_f32_e32 v91, v224, v232
	v_fmac_f32_e32 v91, v225, v233
	v_fmac_f32_e32 v91, v226, v234
	v_fmac_f32_e32 v91, v227, v235
	v_fmac_f32_e32 v91, v228, v236
	v_fmac_f32_e32 v91, v229, v237
	v_fmac_f32_e32 v91, v230, v238
	v_fmac_f32_e32 v91, v231, v239
	ds_read_b128 v[190:193], v171 offset:4160
	ds_read_b128 v[194:197], v171 offset:4176
	ds_read_b128 v[232:235], v171 offset:4192
	ds_read_b128 v[236:239], v171 offset:4208
	s_waitcnt lgkmcnt(4)
	v_fmac_f32_e32 v88, v200, v174
	v_fmac_f32_e32 v88, v201, v175
	v_fmac_f32_e32 v88, v202, v176
	v_fmac_f32_e32 v88, v203, v177
	v_fmac_f32_e32 v88, v204, v178
	v_fmac_f32_e32 v88, v205, v179
	v_fmac_f32_e32 v88, v206, v180
	v_fmac_f32_e32 v88, v207, v181
	v_fmac_f32_e32 v88, v208, v182
	v_fmac_f32_e32 v88, v209, v183
	v_fmac_f32_e32 v88, v210, v184
	v_fmac_f32_e32 v88, v211, v185
	v_fmac_f32_e32 v88, v212, v186
	v_fmac_f32_e32 v88, v213, v187
	v_fmac_f32_e32 v88, v214, v188
	v_fmac_f32_e32 v88, v215, v189
	ds_read_b128 v[174:177], v171 offset:4608
	ds_read_b128 v[178:181], v171 offset:4624
	ds_read_b128 v[182:185], v171 offset:4640
	ds_read_b128 v[186:189], v171 offset:4656
	s_waitcnt lgkmcnt(4)
	v_fmac_f32_e32 v88, v216, v190
	v_fmac_f32_e32 v88, v217, v191
	v_fmac_f32_e32 v88, v218, v192
	v_fmac_f32_e32 v88, v219, v193
	v_fmac_f32_e32 v88, v220, v194
	v_fmac_f32_e32 v88, v221, v195
	v_fmac_f32_e32 v88, v222, v196
	v_fmac_f32_e32 v88, v223, v197
	v_fmac_f32_e32 v88, v224, v232
	v_fmac_f32_e32 v88, v225, v233
	v_fmac_f32_e32 v88, v226, v234
	v_fmac_f32_e32 v88, v227, v235
	v_fmac_f32_e32 v88, v228, v236
	v_fmac_f32_e32 v88, v229, v237
	v_fmac_f32_e32 v88, v230, v238
	v_fmac_f32_e32 v88, v231, v239
	ds_read_b128 v[190:193], v171 offset:4672
	ds_read_b128 v[194:197], v171 offset:4688
	ds_read_b128 v[232:235], v171 offset:4704
	ds_read_b128 v[236:239], v171 offset:4720
	s_waitcnt lgkmcnt(4)
	v_fmac_f32_e32 v89, v200, v174
	v_fmac_f32_e32 v89, v201, v175
	v_fmac_f32_e32 v89, v202, v176
	v_fmac_f32_e32 v89, v203, v177
	v_fmac_f32_e32 v89, v204, v178
	v_fmac_f32_e32 v89, v205, v179
	v_fmac_f32_e32 v89, v206, v180
	v_fmac_f32_e32 v89, v207, v181
	v_fmac_f32_e32 v89, v208, v182
	v_fmac_f32_e32 v89, v209, v183
	v_fmac_f32_e32 v89, v210, v184
	v_fmac_f32_e32 v89, v211, v185
	v_fmac_f32_e32 v89, v212, v186
	v_fmac_f32_e32 v89, v213, v187
	v_fmac_f32_e32 v89, v214, v188
	v_fmac_f32_e32 v89, v215, v189
	ds_read_b128 v[174:177], v171 offset:5120
	ds_read_b128 v[178:181], v171 offset:5136
	ds_read_b128 v[182:185], v171 offset:5152
	ds_read_b128 v[186:189], v171 offset:5168
	s_waitcnt lgkmcnt(4)
	v_fmac_f32_e32 v89, v216, v190
	v_fmac_f32_e32 v89, v217, v191
	v_fmac_f32_e32 v89, v218, v192
	v_fmac_f32_e32 v89, v219, v193
	v_fmac_f32_e32 v89, v220, v194
	v_fmac_f32_e32 v89, v221, v195
	v_fmac_f32_e32 v89, v222, v196
	v_fmac_f32_e32 v89, v223, v197
	v_fmac_f32_e32 v89, v224, v232
	v_fmac_f32_e32 v89, v225, v233
	v_fmac_f32_e32 v89, v226, v234
	v_fmac_f32_e32 v89, v227, v235
	v_fmac_f32_e32 v89, v228, v236
	v_fmac_f32_e32 v89, v229, v237
	v_fmac_f32_e32 v89, v230, v238
	v_fmac_f32_e32 v89, v231, v239
	ds_read_b128 v[190:193], v171 offset:5184
	ds_read_b128 v[194:197], v171 offset:5200
	ds_read_b128 v[232:235], v171 offset:5216
	ds_read_b128 v[236:239], v171 offset:5232
	s_waitcnt lgkmcnt(4)
	v_fmac_f32_e32 v94, v200, v174
	v_fmac_f32_e32 v94, v201, v175
	v_fmac_f32_e32 v94, v202, v176
	v_fmac_f32_e32 v94, v203, v177
	v_fmac_f32_e32 v94, v204, v178
	v_fmac_f32_e32 v94, v205, v179
	v_fmac_f32_e32 v94, v206, v180
	v_fmac_f32_e32 v94, v207, v181
	v_fmac_f32_e32 v94, v208, v182
	v_fmac_f32_e32 v94, v209, v183
	v_fmac_f32_e32 v94, v210, v184
	v_fmac_f32_e32 v94, v211, v185
	v_fmac_f32_e32 v94, v212, v186
	v_fmac_f32_e32 v94, v213, v187
	v_fmac_f32_e32 v94, v214, v188
	v_fmac_f32_e32 v94, v215, v189
	ds_read_b128 v[174:177], v171 offset:5632
	ds_read_b128 v[178:181], v171 offset:5648
	ds_read_b128 v[182:185], v171 offset:5664
	ds_read_b128 v[186:189], v171 offset:5680
	s_waitcnt lgkmcnt(4)
	v_fmac_f32_e32 v94, v216, v190
	v_fmac_f32_e32 v94, v217, v191
	v_fmac_f32_e32 v94, v218, v192
	v_fmac_f32_e32 v94, v219, v193
	v_fmac_f32_e32 v94, v220, v194
	v_fmac_f32_e32 v94, v221, v195
	v_fmac_f32_e32 v94, v222, v196
	v_fmac_f32_e32 v94, v223, v197
	v_fmac_f32_e32 v94, v224, v232
	v_fmac_f32_e32 v94, v225, v233
	v_fmac_f32_e32 v94, v226, v234
	v_fmac_f32_e32 v94, v227, v235
	v_fmac_f32_e32 v94, v228, v236
	v_fmac_f32_e32 v94, v229, v237
	v_fmac_f32_e32 v94, v230, v238
	v_fmac_f32_e32 v94, v231, v239
	ds_read_b128 v[190:193], v171 offset:5696
	ds_read_b128 v[194:197], v171 offset:5712
	ds_read_b128 v[232:235], v171 offset:5728
	ds_read_b128 v[236:239], v171 offset:5744
	s_waitcnt lgkmcnt(4)
	v_fmac_f32_e32 v95, v200, v174
	v_fmac_f32_e32 v95, v201, v175
	v_fmac_f32_e32 v95, v202, v176
	v_fmac_f32_e32 v95, v203, v177
	v_fmac_f32_e32 v95, v204, v178
	v_fmac_f32_e32 v95, v205, v179
	v_fmac_f32_e32 v95, v206, v180
	v_fmac_f32_e32 v95, v207, v181
	v_fmac_f32_e32 v95, v208, v182
	v_fmac_f32_e32 v95, v209, v183
	v_fmac_f32_e32 v95, v210, v184
	v_fmac_f32_e32 v95, v211, v185
	v_fmac_f32_e32 v95, v212, v186
	v_fmac_f32_e32 v95, v213, v187
	v_fmac_f32_e32 v95, v214, v188
	v_fmac_f32_e32 v95, v215, v189
	ds_read_b128 v[174:177], v171 offset:6144
	ds_read_b128 v[178:181], v171 offset:6160
	ds_read_b128 v[182:185], v171 offset:6176
	ds_read_b128 v[186:189], v171 offset:6192
	s_waitcnt lgkmcnt(4)
	v_fmac_f32_e32 v95, v216, v190
	v_fmac_f32_e32 v95, v217, v191
	v_fmac_f32_e32 v95, v218, v192
	v_fmac_f32_e32 v95, v219, v193
	v_fmac_f32_e32 v95, v220, v194
	v_fmac_f32_e32 v95, v221, v195
	v_fmac_f32_e32 v95, v222, v196
	v_fmac_f32_e32 v95, v223, v197
	v_fmac_f32_e32 v95, v224, v232
	v_fmac_f32_e32 v95, v225, v233
	v_fmac_f32_e32 v95, v226, v234
	v_fmac_f32_e32 v95, v227, v235
	v_fmac_f32_e32 v95, v228, v236
	v_fmac_f32_e32 v95, v229, v237
	v_fmac_f32_e32 v95, v230, v238
	v_fmac_f32_e32 v95, v231, v239
	ds_read_b128 v[190:193], v171 offset:6208
	ds_read_b128 v[194:197], v171 offset:6224
	ds_read_b128 v[232:235], v171 offset:6240
	ds_read_b128 v[236:239], v171 offset:6256
	s_waitcnt lgkmcnt(4)
	v_fmac_f32_e32 v92, v200, v174
	v_fmac_f32_e32 v92, v201, v175
	v_fmac_f32_e32 v92, v202, v176
	v_fmac_f32_e32 v92, v203, v177
	v_fmac_f32_e32 v92, v204, v178
	v_fmac_f32_e32 v92, v205, v179
	v_fmac_f32_e32 v92, v206, v180
	v_fmac_f32_e32 v92, v207, v181
	v_fmac_f32_e32 v92, v208, v182
	v_fmac_f32_e32 v92, v209, v183
	v_fmac_f32_e32 v92, v210, v184
	v_fmac_f32_e32 v92, v211, v185
	v_fmac_f32_e32 v92, v212, v186
	v_fmac_f32_e32 v92, v213, v187
	v_fmac_f32_e32 v92, v214, v188
	v_fmac_f32_e32 v92, v215, v189
	ds_read_b128 v[174:177], v171 offset:6656
	ds_read_b128 v[178:181], v171 offset:6672
	ds_read_b128 v[182:185], v171 offset:6688
	ds_read_b128 v[186:189], v171 offset:6704
	s_waitcnt lgkmcnt(4)
	v_fmac_f32_e32 v92, v216, v190
	v_fmac_f32_e32 v92, v217, v191
	v_fmac_f32_e32 v92, v218, v192
	v_fmac_f32_e32 v92, v219, v193
	v_fmac_f32_e32 v92, v220, v194
	v_fmac_f32_e32 v92, v221, v195
	v_fmac_f32_e32 v92, v222, v196
	v_fmac_f32_e32 v92, v223, v197
	v_fmac_f32_e32 v92, v224, v232
	v_fmac_f32_e32 v92, v225, v233
	v_fmac_f32_e32 v92, v226, v234
	v_fmac_f32_e32 v92, v227, v235
	v_fmac_f32_e32 v92, v228, v236
	v_fmac_f32_e32 v92, v229, v237
	v_fmac_f32_e32 v92, v230, v238
	v_fmac_f32_e32 v92, v231, v239
	ds_read_b128 v[190:193], v171 offset:6720
	ds_read_b128 v[194:197], v171 offset:6736
	ds_read_b128 v[232:235], v171 offset:6752
	ds_read_b128 v[236:239], v171 offset:6768
	s_waitcnt lgkmcnt(4)
	v_fmac_f32_e32 v93, v200, v174
	v_fmac_f32_e32 v93, v201, v175
	v_fmac_f32_e32 v93, v202, v176
	v_fmac_f32_e32 v93, v203, v177
	v_fmac_f32_e32 v93, v204, v178
	v_fmac_f32_e32 v93, v205, v179
	v_fmac_f32_e32 v93, v206, v180
	v_fmac_f32_e32 v93, v207, v181
	v_fmac_f32_e32 v93, v208, v182
	v_fmac_f32_e32 v93, v209, v183
	v_fmac_f32_e32 v93, v210, v184
	v_fmac_f32_e32 v93, v211, v185
	v_fmac_f32_e32 v93, v212, v186
	v_fmac_f32_e32 v93, v213, v187
	v_fmac_f32_e32 v93, v214, v188
	v_fmac_f32_e32 v93, v215, v189
	ds_read_b128 v[174:177], v171 offset:7168
	ds_read_b128 v[178:181], v171 offset:7184
	ds_read_b128 v[182:185], v171 offset:7200
	ds_read_b128 v[186:189], v171 offset:7216
	s_waitcnt lgkmcnt(4)
	v_fmac_f32_e32 v93, v216, v190
	v_fmac_f32_e32 v93, v217, v191
	v_fmac_f32_e32 v93, v218, v192
	v_fmac_f32_e32 v93, v219, v193
	v_fmac_f32_e32 v93, v220, v194
	v_fmac_f32_e32 v93, v221, v195
	v_fmac_f32_e32 v93, v222, v196
	v_fmac_f32_e32 v93, v223, v197
	v_fmac_f32_e32 v93, v224, v232
	v_fmac_f32_e32 v93, v225, v233
	v_fmac_f32_e32 v93, v226, v234
	v_fmac_f32_e32 v93, v227, v235
	v_fmac_f32_e32 v93, v228, v236
	v_fmac_f32_e32 v93, v229, v237
	v_fmac_f32_e32 v93, v230, v238
	v_fmac_f32_e32 v93, v231, v239
	ds_read_b128 v[190:193], v171 offset:7232
	ds_read_b128 v[194:197], v171 offset:7248
	ds_read_b128 v[232:235], v171 offset:7264
	ds_read_b128 v[236:239], v171 offset:7280
	s_waitcnt lgkmcnt(4)
	v_fmac_f32_e32 v100, v200, v174
	v_fmac_f32_e32 v100, v201, v175
	v_fmac_f32_e32 v100, v202, v176
	v_fmac_f32_e32 v100, v203, v177
	v_fmac_f32_e32 v100, v204, v178
	v_fmac_f32_e32 v100, v205, v179
	v_fmac_f32_e32 v100, v206, v180
	v_fmac_f32_e32 v100, v207, v181
	v_fmac_f32_e32 v100, v208, v182
	v_fmac_f32_e32 v100, v209, v183
	v_fmac_f32_e32 v100, v210, v184
	v_fmac_f32_e32 v100, v211, v185
	v_fmac_f32_e32 v100, v212, v186
	v_fmac_f32_e32 v100, v213, v187
	v_fmac_f32_e32 v100, v214, v188
	v_fmac_f32_e32 v100, v215, v189
	ds_read_b128 v[174:177], v171 offset:7680
	ds_read_b128 v[178:181], v171 offset:7696
	ds_read_b128 v[182:185], v171 offset:7712
	ds_read_b128 v[186:189], v171 offset:7728
	s_waitcnt lgkmcnt(4)
	v_fmac_f32_e32 v100, v216, v190
	v_fmac_f32_e32 v100, v217, v191
	v_fmac_f32_e32 v100, v218, v192
	v_fmac_f32_e32 v100, v219, v193
	v_fmac_f32_e32 v100, v220, v194
	v_fmac_f32_e32 v100, v221, v195
	v_fmac_f32_e32 v100, v222, v196
	v_fmac_f32_e32 v100, v223, v197
	v_fmac_f32_e32 v100, v224, v232
	v_fmac_f32_e32 v100, v225, v233
	v_fmac_f32_e32 v100, v226, v234
	v_fmac_f32_e32 v100, v227, v235
	v_fmac_f32_e32 v100, v228, v236
	v_fmac_f32_e32 v100, v229, v237
	v_fmac_f32_e32 v100, v230, v238
	v_fmac_f32_e32 v100, v231, v239
	ds_read_b128 v[190:193], v171 offset:7744
	ds_read_b128 v[194:197], v171 offset:7760
	ds_read_b128 v[232:235], v171 offset:7776
	ds_read_b128 v[236:239], v171 offset:7792
	s_waitcnt lgkmcnt(4)
	v_fmac_f32_e32 v101, v200, v174
	v_fmac_f32_e32 v101, v201, v175
	v_fmac_f32_e32 v101, v202, v176
	v_fmac_f32_e32 v101, v203, v177
	v_fmac_f32_e32 v101, v204, v178
	v_fmac_f32_e32 v101, v205, v179
	v_fmac_f32_e32 v101, v206, v180
	v_fmac_f32_e32 v101, v207, v181
	v_fmac_f32_e32 v101, v208, v182
	v_fmac_f32_e32 v101, v209, v183
	v_fmac_f32_e32 v101, v210, v184
	v_fmac_f32_e32 v101, v211, v185
	v_fmac_f32_e32 v101, v212, v186
	v_fmac_f32_e32 v101, v213, v187
	v_fmac_f32_e32 v101, v214, v188
	v_fmac_f32_e32 v101, v215, v189
	ds_read_b128 v[174:177], v171 offset:8192
	ds_read_b128 v[178:181], v171 offset:8208
	ds_read_b128 v[182:185], v171 offset:8224
	ds_read_b128 v[186:189], v171 offset:8240
	s_waitcnt lgkmcnt(4)
	v_fmac_f32_e32 v101, v216, v190
	v_fmac_f32_e32 v101, v217, v191
	v_fmac_f32_e32 v101, v218, v192
	v_fmac_f32_e32 v101, v219, v193
	v_fmac_f32_e32 v101, v220, v194
	v_fmac_f32_e32 v101, v221, v195
	v_fmac_f32_e32 v101, v222, v196
	v_fmac_f32_e32 v101, v223, v197
	v_fmac_f32_e32 v101, v224, v232
	v_fmac_f32_e32 v101, v225, v233
	v_fmac_f32_e32 v101, v226, v234
	v_fmac_f32_e32 v101, v227, v235
	v_fmac_f32_e32 v101, v228, v236
	v_fmac_f32_e32 v101, v229, v237
	v_fmac_f32_e32 v101, v230, v238
	v_fmac_f32_e32 v101, v231, v239
	ds_read_b128 v[190:193], v171 offset:8256
	ds_read_b128 v[194:197], v171 offset:8272
	ds_read_b128 v[232:235], v171 offset:8288
	ds_read_b128 v[236:239], v171 offset:8304
	s_waitcnt lgkmcnt(4)
	v_fmac_f32_e32 v98, v200, v174
	v_fmac_f32_e32 v98, v201, v175
	v_fmac_f32_e32 v98, v202, v176
	v_fmac_f32_e32 v98, v203, v177
	v_fmac_f32_e32 v98, v204, v178
	v_fmac_f32_e32 v98, v205, v179
	v_fmac_f32_e32 v98, v206, v180
	v_fmac_f32_e32 v98, v207, v181
	v_fmac_f32_e32 v98, v208, v182
	v_fmac_f32_e32 v98, v209, v183
	v_fmac_f32_e32 v98, v210, v184
	v_fmac_f32_e32 v98, v211, v185
	v_fmac_f32_e32 v98, v212, v186
	v_fmac_f32_e32 v98, v213, v187
	v_fmac_f32_e32 v98, v214, v188
	v_fmac_f32_e32 v98, v215, v189
	ds_read_b128 v[174:177], v171 offset:8704
	ds_read_b128 v[178:181], v171 offset:8720
	ds_read_b128 v[182:185], v171 offset:8736
	ds_read_b128 v[186:189], v171 offset:8752
	s_waitcnt lgkmcnt(4)
	v_fmac_f32_e32 v98, v216, v190
	v_fmac_f32_e32 v98, v217, v191
	v_fmac_f32_e32 v98, v218, v192
	v_fmac_f32_e32 v98, v219, v193
	v_fmac_f32_e32 v98, v220, v194
	v_fmac_f32_e32 v98, v221, v195
	v_fmac_f32_e32 v98, v222, v196
	v_fmac_f32_e32 v98, v223, v197
	v_fmac_f32_e32 v98, v224, v232
	v_fmac_f32_e32 v98, v225, v233
	v_fmac_f32_e32 v98, v226, v234
	v_fmac_f32_e32 v98, v227, v235
	v_fmac_f32_e32 v98, v228, v236
	v_fmac_f32_e32 v98, v229, v237
	v_fmac_f32_e32 v98, v230, v238
	v_fmac_f32_e32 v98, v231, v239
	ds_read_b128 v[190:193], v171 offset:8768
	ds_read_b128 v[194:197], v171 offset:8784
	ds_read_b128 v[232:235], v171 offset:8800
	ds_read_b128 v[236:239], v171 offset:8816
	s_waitcnt lgkmcnt(4)
	v_fmac_f32_e32 v99, v200, v174
	v_fmac_f32_e32 v99, v201, v175
	v_fmac_f32_e32 v99, v202, v176
	v_fmac_f32_e32 v99, v203, v177
	v_fmac_f32_e32 v99, v204, v178
	v_fmac_f32_e32 v99, v205, v179
	v_fmac_f32_e32 v99, v206, v180
	v_fmac_f32_e32 v99, v207, v181
	v_fmac_f32_e32 v99, v208, v182
	v_fmac_f32_e32 v99, v209, v183
	v_fmac_f32_e32 v99, v210, v184
	v_fmac_f32_e32 v99, v211, v185
	v_fmac_f32_e32 v99, v212, v186
	v_fmac_f32_e32 v99, v213, v187
	v_fmac_f32_e32 v99, v214, v188
	v_fmac_f32_e32 v99, v215, v189
	ds_read_b128 v[174:177], v171 offset:9216
	ds_read_b128 v[178:181], v171 offset:9232
	ds_read_b128 v[182:185], v171 offset:9248
	ds_read_b128 v[186:189], v171 offset:9264
	s_waitcnt lgkmcnt(4)
	v_fmac_f32_e32 v99, v216, v190
	v_fmac_f32_e32 v99, v217, v191
	v_fmac_f32_e32 v99, v218, v192
	v_fmac_f32_e32 v99, v219, v193
	v_fmac_f32_e32 v99, v220, v194
	v_fmac_f32_e32 v99, v221, v195
	v_fmac_f32_e32 v99, v222, v196
	v_fmac_f32_e32 v99, v223, v197
	v_fmac_f32_e32 v99, v224, v232
	v_fmac_f32_e32 v99, v225, v233
	v_fmac_f32_e32 v99, v226, v234
	v_fmac_f32_e32 v99, v227, v235
	v_fmac_f32_e32 v99, v228, v236
	v_fmac_f32_e32 v99, v229, v237
	v_fmac_f32_e32 v99, v230, v238
	v_fmac_f32_e32 v99, v231, v239
	ds_read_b128 v[190:193], v171 offset:9280
	ds_read_b128 v[194:197], v171 offset:9296
	ds_read_b128 v[232:235], v171 offset:9312
	ds_read_b128 v[236:239], v171 offset:9328
	s_waitcnt lgkmcnt(4)
	v_fmac_f32_e32 v104, v200, v174
	v_fmac_f32_e32 v104, v201, v175
	v_fmac_f32_e32 v104, v202, v176
	v_fmac_f32_e32 v104, v203, v177
	v_fmac_f32_e32 v104, v204, v178
	v_fmac_f32_e32 v104, v205, v179
	v_fmac_f32_e32 v104, v206, v180
	v_fmac_f32_e32 v104, v207, v181
	v_fmac_f32_e32 v104, v208, v182
	v_fmac_f32_e32 v104, v209, v183
	v_fmac_f32_e32 v104, v210, v184
	v_fmac_f32_e32 v104, v211, v185
	v_fmac_f32_e32 v104, v212, v186
	v_fmac_f32_e32 v104, v213, v187
	v_fmac_f32_e32 v104, v214, v188
	v_fmac_f32_e32 v104, v215, v189
	ds_read_b128 v[174:177], v171 offset:9728
	ds_read_b128 v[178:181], v171 offset:9744
	ds_read_b128 v[182:185], v171 offset:9760
	ds_read_b128 v[186:189], v171 offset:9776
	s_waitcnt lgkmcnt(4)
	v_fmac_f32_e32 v104, v216, v190
	v_fmac_f32_e32 v104, v217, v191
	v_fmac_f32_e32 v104, v218, v192
	v_fmac_f32_e32 v104, v219, v193
	v_fmac_f32_e32 v104, v220, v194
	v_fmac_f32_e32 v104, v221, v195
	v_fmac_f32_e32 v104, v222, v196
	v_fmac_f32_e32 v104, v223, v197
	v_fmac_f32_e32 v104, v224, v232
	v_fmac_f32_e32 v104, v225, v233
	v_fmac_f32_e32 v104, v226, v234
	v_fmac_f32_e32 v104, v227, v235
	v_fmac_f32_e32 v104, v228, v236
	v_fmac_f32_e32 v104, v229, v237
	v_fmac_f32_e32 v104, v230, v238
	v_fmac_f32_e32 v104, v231, v239
	ds_read_b128 v[190:193], v171 offset:9792
	ds_read_b128 v[194:197], v171 offset:9808
	ds_read_b128 v[232:235], v171 offset:9824
	ds_read_b128 v[236:239], v171 offset:9840
	s_waitcnt lgkmcnt(4)
	v_fmac_f32_e32 v105, v200, v174
	v_fmac_f32_e32 v105, v201, v175
	v_fmac_f32_e32 v105, v202, v176
	v_fmac_f32_e32 v105, v203, v177
	v_fmac_f32_e32 v105, v204, v178
	v_fmac_f32_e32 v105, v205, v179
	v_fmac_f32_e32 v105, v206, v180
	v_fmac_f32_e32 v105, v207, v181
	v_fmac_f32_e32 v105, v208, v182
	v_fmac_f32_e32 v105, v209, v183
	v_fmac_f32_e32 v105, v210, v184
	v_fmac_f32_e32 v105, v211, v185
	v_fmac_f32_e32 v105, v212, v186
	v_fmac_f32_e32 v105, v213, v187
	v_fmac_f32_e32 v105, v214, v188
	v_fmac_f32_e32 v105, v215, v189
	ds_read_b128 v[174:177], v171 offset:10240
	ds_read_b128 v[178:181], v171 offset:10256
	ds_read_b128 v[182:185], v171 offset:10272
	ds_read_b128 v[186:189], v171 offset:10288
	s_waitcnt lgkmcnt(4)
	v_fmac_f32_e32 v105, v216, v190
	v_fmac_f32_e32 v105, v217, v191
	v_fmac_f32_e32 v105, v218, v192
	v_fmac_f32_e32 v105, v219, v193
	v_fmac_f32_e32 v105, v220, v194
	v_fmac_f32_e32 v105, v221, v195
	v_fmac_f32_e32 v105, v222, v196
	v_fmac_f32_e32 v105, v223, v197
	v_fmac_f32_e32 v105, v224, v232
	v_fmac_f32_e32 v105, v225, v233
	v_fmac_f32_e32 v105, v226, v234
	v_fmac_f32_e32 v105, v227, v235
	v_fmac_f32_e32 v105, v228, v236
	v_fmac_f32_e32 v105, v229, v237
	v_fmac_f32_e32 v105, v230, v238
	v_fmac_f32_e32 v105, v231, v239
	ds_read_b128 v[190:193], v171 offset:10304
	ds_read_b128 v[194:197], v171 offset:10320
	ds_read_b128 v[232:235], v171 offset:10336
	ds_read_b128 v[236:239], v171 offset:10352
	s_waitcnt lgkmcnt(4)
	v_fmac_f32_e32 v102, v200, v174
	v_fmac_f32_e32 v102, v201, v175
	v_fmac_f32_e32 v102, v202, v176
	v_fmac_f32_e32 v102, v203, v177
	v_fmac_f32_e32 v102, v204, v178
	v_fmac_f32_e32 v102, v205, v179
	v_fmac_f32_e32 v102, v206, v180
	v_fmac_f32_e32 v102, v207, v181
	v_fmac_f32_e32 v102, v208, v182
	v_fmac_f32_e32 v102, v209, v183
	v_fmac_f32_e32 v102, v210, v184
	v_fmac_f32_e32 v102, v211, v185
	v_fmac_f32_e32 v102, v212, v186
	v_fmac_f32_e32 v102, v213, v187
	v_fmac_f32_e32 v102, v214, v188
	v_fmac_f32_e32 v102, v215, v189
	ds_read_b128 v[174:177], v171 offset:10752
	ds_read_b128 v[178:181], v171 offset:10768
	ds_read_b128 v[182:185], v171 offset:10784
	ds_read_b128 v[186:189], v171 offset:10800
	s_waitcnt lgkmcnt(4)
	v_fmac_f32_e32 v102, v216, v190
	v_fmac_f32_e32 v102, v217, v191
	v_fmac_f32_e32 v102, v218, v192
	v_fmac_f32_e32 v102, v219, v193
	v_fmac_f32_e32 v102, v220, v194
	v_fmac_f32_e32 v102, v221, v195
	v_fmac_f32_e32 v102, v222, v196
	v_fmac_f32_e32 v102, v223, v197
	v_fmac_f32_e32 v102, v224, v232
	v_fmac_f32_e32 v102, v225, v233
	v_fmac_f32_e32 v102, v226, v234
	v_fmac_f32_e32 v102, v227, v235
	v_fmac_f32_e32 v102, v228, v236
	v_fmac_f32_e32 v102, v229, v237
	v_fmac_f32_e32 v102, v230, v238
	v_fmac_f32_e32 v102, v231, v239
	ds_read_b128 v[190:193], v171 offset:10816
	ds_read_b128 v[194:197], v171 offset:10832
	ds_read_b128 v[232:235], v171 offset:10848
	ds_read_b128 v[236:239], v171 offset:10864
	s_waitcnt lgkmcnt(4)
	v_fmac_f32_e32 v103, v200, v174
	v_fmac_f32_e32 v103, v201, v175
	v_fmac_f32_e32 v103, v202, v176
	v_fmac_f32_e32 v103, v203, v177
	v_fmac_f32_e32 v103, v204, v178
	v_fmac_f32_e32 v103, v205, v179
	v_fmac_f32_e32 v103, v206, v180
	v_fmac_f32_e32 v103, v207, v181
	v_fmac_f32_e32 v103, v208, v182
	v_fmac_f32_e32 v103, v209, v183
	v_fmac_f32_e32 v103, v210, v184
	v_fmac_f32_e32 v103, v211, v185
	v_fmac_f32_e32 v103, v212, v186
	v_fmac_f32_e32 v103, v213, v187
	v_fmac_f32_e32 v103, v214, v188
	v_fmac_f32_e32 v103, v215, v189
	ds_read_b128 v[174:177], v171 offset:11264
	ds_read_b128 v[178:181], v171 offset:11280
	ds_read_b128 v[182:185], v171 offset:11296
	ds_read_b128 v[186:189], v171 offset:11312
	s_waitcnt lgkmcnt(4)
	v_fmac_f32_e32 v103, v216, v190
	v_fmac_f32_e32 v103, v217, v191
	v_fmac_f32_e32 v103, v218, v192
	v_fmac_f32_e32 v103, v219, v193
	v_fmac_f32_e32 v103, v220, v194
	v_fmac_f32_e32 v103, v221, v195
	v_fmac_f32_e32 v103, v222, v196
	v_fmac_f32_e32 v103, v223, v197
	v_fmac_f32_e32 v103, v224, v232
	v_fmac_f32_e32 v103, v225, v233
	v_fmac_f32_e32 v103, v226, v234
	v_fmac_f32_e32 v103, v227, v235
	v_fmac_f32_e32 v103, v228, v236
	v_fmac_f32_e32 v103, v229, v237
	v_fmac_f32_e32 v103, v230, v238
	v_fmac_f32_e32 v103, v231, v239
	ds_read_b128 v[190:193], v171 offset:11328
	ds_read_b128 v[194:197], v171 offset:11344
	ds_read_b128 v[232:235], v171 offset:11360
	ds_read_b128 v[236:239], v171 offset:11376
	s_waitcnt lgkmcnt(4)
	v_fmac_f32_e32 v108, v200, v174
	v_fmac_f32_e32 v108, v201, v175
	v_fmac_f32_e32 v108, v202, v176
	v_fmac_f32_e32 v108, v203, v177
	v_fmac_f32_e32 v108, v204, v178
	v_fmac_f32_e32 v108, v205, v179
	v_fmac_f32_e32 v108, v206, v180
	v_fmac_f32_e32 v108, v207, v181
	v_fmac_f32_e32 v108, v208, v182
	v_fmac_f32_e32 v108, v209, v183
	v_fmac_f32_e32 v108, v210, v184
	v_fmac_f32_e32 v108, v211, v185
	v_fmac_f32_e32 v108, v212, v186
	v_fmac_f32_e32 v108, v213, v187
	v_fmac_f32_e32 v108, v214, v188
	v_fmac_f32_e32 v108, v215, v189
	ds_read_b128 v[174:177], v171 offset:11776
	ds_read_b128 v[178:181], v171 offset:11792
	ds_read_b128 v[182:185], v171 offset:11808
	ds_read_b128 v[186:189], v171 offset:11824
	s_waitcnt lgkmcnt(4)
	v_fmac_f32_e32 v108, v216, v190
	v_fmac_f32_e32 v108, v217, v191
	v_fmac_f32_e32 v108, v218, v192
	v_fmac_f32_e32 v108, v219, v193
	v_fmac_f32_e32 v108, v220, v194
	v_fmac_f32_e32 v108, v221, v195
	v_fmac_f32_e32 v108, v222, v196
	v_fmac_f32_e32 v108, v223, v197
	v_fmac_f32_e32 v108, v224, v232
	v_fmac_f32_e32 v108, v225, v233
	v_fmac_f32_e32 v108, v226, v234
	v_fmac_f32_e32 v108, v227, v235
	v_fmac_f32_e32 v108, v228, v236
	v_fmac_f32_e32 v108, v229, v237
	v_fmac_f32_e32 v108, v230, v238
	v_fmac_f32_e32 v108, v231, v239
	ds_read_b128 v[190:193], v171 offset:11840
	ds_read_b128 v[194:197], v171 offset:11856
	ds_read_b128 v[232:235], v171 offset:11872
	ds_read_b128 v[236:239], v171 offset:11888
	s_waitcnt lgkmcnt(4)
	v_fmac_f32_e32 v109, v200, v174
	v_fmac_f32_e32 v109, v201, v175
	v_fmac_f32_e32 v109, v202, v176
	v_fmac_f32_e32 v109, v203, v177
	v_fmac_f32_e32 v109, v204, v178
	v_fmac_f32_e32 v109, v205, v179
	v_fmac_f32_e32 v109, v206, v180
	v_fmac_f32_e32 v109, v207, v181
	v_fmac_f32_e32 v109, v208, v182
	v_fmac_f32_e32 v109, v209, v183
	v_fmac_f32_e32 v109, v210, v184
	v_fmac_f32_e32 v109, v211, v185
	v_fmac_f32_e32 v109, v212, v186
	v_fmac_f32_e32 v109, v213, v187
	v_fmac_f32_e32 v109, v214, v188
	v_fmac_f32_e32 v109, v215, v189
	ds_read_b128 v[174:177], v171 offset:12288
	ds_read_b128 v[178:181], v171 offset:12304
	ds_read_b128 v[182:185], v171 offset:12320
	ds_read_b128 v[186:189], v171 offset:12336
	s_waitcnt lgkmcnt(4)
	v_fmac_f32_e32 v109, v216, v190
	v_fmac_f32_e32 v109, v217, v191
	v_fmac_f32_e32 v109, v218, v192
	v_fmac_f32_e32 v109, v219, v193
	v_fmac_f32_e32 v109, v220, v194
	v_fmac_f32_e32 v109, v221, v195
	v_fmac_f32_e32 v109, v222, v196
	v_fmac_f32_e32 v109, v223, v197
	v_fmac_f32_e32 v109, v224, v232
	v_fmac_f32_e32 v109, v225, v233
	v_fmac_f32_e32 v109, v226, v234
	v_fmac_f32_e32 v109, v227, v235
	v_fmac_f32_e32 v109, v228, v236
	v_fmac_f32_e32 v109, v229, v237
	v_fmac_f32_e32 v109, v230, v238
	v_fmac_f32_e32 v109, v231, v239
	ds_read_b128 v[190:193], v171 offset:12352
	ds_read_b128 v[194:197], v171 offset:12368
	ds_read_b128 v[232:235], v171 offset:12384
	ds_read_b128 v[236:239], v171 offset:12400
	s_waitcnt lgkmcnt(4)
	v_fmac_f32_e32 v106, v200, v174
	v_fmac_f32_e32 v106, v201, v175
	v_fmac_f32_e32 v106, v202, v176
	v_fmac_f32_e32 v106, v203, v177
	v_fmac_f32_e32 v106, v204, v178
	v_fmac_f32_e32 v106, v205, v179
	v_fmac_f32_e32 v106, v206, v180
	v_fmac_f32_e32 v106, v207, v181
	v_fmac_f32_e32 v106, v208, v182
	v_fmac_f32_e32 v106, v209, v183
	v_fmac_f32_e32 v106, v210, v184
	v_fmac_f32_e32 v106, v211, v185
	v_fmac_f32_e32 v106, v212, v186
	v_fmac_f32_e32 v106, v213, v187
	v_fmac_f32_e32 v106, v214, v188
	v_fmac_f32_e32 v106, v215, v189
	ds_read_b128 v[174:177], v171 offset:12800
	ds_read_b128 v[178:181], v171 offset:12816
	ds_read_b128 v[182:185], v171 offset:12832
	ds_read_b128 v[186:189], v171 offset:12848
	s_waitcnt lgkmcnt(4)
	v_fmac_f32_e32 v106, v216, v190
	v_fmac_f32_e32 v106, v217, v191
	v_fmac_f32_e32 v106, v218, v192
	v_fmac_f32_e32 v106, v219, v193
	v_fmac_f32_e32 v106, v220, v194
	v_fmac_f32_e32 v106, v221, v195
	v_fmac_f32_e32 v106, v222, v196
	v_fmac_f32_e32 v106, v223, v197
	v_fmac_f32_e32 v106, v224, v232
	v_fmac_f32_e32 v106, v225, v233
	v_fmac_f32_e32 v106, v226, v234
	v_fmac_f32_e32 v106, v227, v235
	v_fmac_f32_e32 v106, v228, v236
	v_fmac_f32_e32 v106, v229, v237
	v_fmac_f32_e32 v106, v230, v238
	v_fmac_f32_e32 v106, v231, v239
	ds_read_b128 v[190:193], v171 offset:12864
	ds_read_b128 v[194:197], v171 offset:12880
	ds_read_b128 v[232:235], v171 offset:12896
	ds_read_b128 v[236:239], v171 offset:12912
	s_waitcnt lgkmcnt(4)
	v_fmac_f32_e32 v107, v200, v174
	v_fmac_f32_e32 v107, v201, v175
	v_fmac_f32_e32 v107, v202, v176
	v_fmac_f32_e32 v107, v203, v177
	v_fmac_f32_e32 v107, v204, v178
	v_fmac_f32_e32 v107, v205, v179
	v_fmac_f32_e32 v107, v206, v180
	v_fmac_f32_e32 v107, v207, v181
	v_fmac_f32_e32 v107, v208, v182
	v_fmac_f32_e32 v107, v209, v183
	v_fmac_f32_e32 v107, v210, v184
	v_fmac_f32_e32 v107, v211, v185
	v_fmac_f32_e32 v107, v212, v186
	v_fmac_f32_e32 v107, v213, v187
	v_fmac_f32_e32 v107, v214, v188
	v_fmac_f32_e32 v107, v215, v189
	ds_read_b128 v[174:177], v171 offset:13312
	ds_read_b128 v[178:181], v171 offset:13328
	ds_read_b128 v[182:185], v171 offset:13344
	ds_read_b128 v[186:189], v171 offset:13360
	s_waitcnt lgkmcnt(4)
	v_fmac_f32_e32 v107, v216, v190
	v_fmac_f32_e32 v107, v217, v191
	v_fmac_f32_e32 v107, v218, v192
	v_fmac_f32_e32 v107, v219, v193
	v_fmac_f32_e32 v107, v220, v194
	v_fmac_f32_e32 v107, v221, v195
	v_fmac_f32_e32 v107, v222, v196
	v_fmac_f32_e32 v107, v223, v197
	v_fmac_f32_e32 v107, v224, v232
	v_fmac_f32_e32 v107, v225, v233
	v_fmac_f32_e32 v107, v226, v234
	v_fmac_f32_e32 v107, v227, v235
	v_fmac_f32_e32 v107, v228, v236
	v_fmac_f32_e32 v107, v229, v237
	v_fmac_f32_e32 v107, v230, v238
	v_fmac_f32_e32 v107, v231, v239
	ds_read_b128 v[190:193], v171 offset:13376
	ds_read_b128 v[194:197], v171 offset:13392
	ds_read_b128 v[232:235], v171 offset:13408
	ds_read_b128 v[236:239], v171 offset:13424
	s_waitcnt lgkmcnt(4)
	v_fmac_f32_e32 v112, v200, v174
	v_fmac_f32_e32 v112, v201, v175
	v_fmac_f32_e32 v112, v202, v176
	v_fmac_f32_e32 v112, v203, v177
	v_fmac_f32_e32 v112, v204, v178
	v_fmac_f32_e32 v112, v205, v179
	v_fmac_f32_e32 v112, v206, v180
	v_fmac_f32_e32 v112, v207, v181
	v_fmac_f32_e32 v112, v208, v182
	v_fmac_f32_e32 v112, v209, v183
	v_fmac_f32_e32 v112, v210, v184
	v_fmac_f32_e32 v112, v211, v185
	v_fmac_f32_e32 v112, v212, v186
	v_fmac_f32_e32 v112, v213, v187
	v_fmac_f32_e32 v112, v214, v188
	v_fmac_f32_e32 v112, v215, v189
	ds_read_b128 v[174:177], v171 offset:13824
	ds_read_b128 v[178:181], v171 offset:13840
	ds_read_b128 v[182:185], v171 offset:13856
	ds_read_b128 v[186:189], v171 offset:13872
	s_waitcnt lgkmcnt(4)
	v_fmac_f32_e32 v112, v216, v190
	v_fmac_f32_e32 v112, v217, v191
	v_fmac_f32_e32 v112, v218, v192
	v_fmac_f32_e32 v112, v219, v193
	v_fmac_f32_e32 v112, v220, v194
	v_fmac_f32_e32 v112, v221, v195
	v_fmac_f32_e32 v112, v222, v196
	v_fmac_f32_e32 v112, v223, v197
	v_fmac_f32_e32 v112, v224, v232
	v_fmac_f32_e32 v112, v225, v233
	v_fmac_f32_e32 v112, v226, v234
	v_fmac_f32_e32 v112, v227, v235
	v_fmac_f32_e32 v112, v228, v236
	v_fmac_f32_e32 v112, v229, v237
	v_fmac_f32_e32 v112, v230, v238
	v_fmac_f32_e32 v112, v231, v239
	ds_read_b128 v[190:193], v171 offset:13888
	ds_read_b128 v[194:197], v171 offset:13904
	ds_read_b128 v[232:235], v171 offset:13920
	ds_read_b128 v[236:239], v171 offset:13936
	s_waitcnt lgkmcnt(4)
	v_fmac_f32_e32 v113, v200, v174
	v_fmac_f32_e32 v113, v201, v175
	v_fmac_f32_e32 v113, v202, v176
	v_fmac_f32_e32 v113, v203, v177
	v_fmac_f32_e32 v113, v204, v178
	v_fmac_f32_e32 v113, v205, v179
	v_fmac_f32_e32 v113, v206, v180
	v_fmac_f32_e32 v113, v207, v181
	v_fmac_f32_e32 v113, v208, v182
	v_fmac_f32_e32 v113, v209, v183
	v_fmac_f32_e32 v113, v210, v184
	v_fmac_f32_e32 v113, v211, v185
	v_fmac_f32_e32 v113, v212, v186
	v_fmac_f32_e32 v113, v213, v187
	v_fmac_f32_e32 v113, v214, v188
	v_fmac_f32_e32 v113, v215, v189
	ds_read_b128 v[174:177], v171 offset:14336
	ds_read_b128 v[178:181], v171 offset:14352
	ds_read_b128 v[182:185], v171 offset:14368
	ds_read_b128 v[186:189], v171 offset:14384
	s_waitcnt lgkmcnt(4)
	v_fmac_f32_e32 v113, v216, v190
	v_fmac_f32_e32 v113, v217, v191
	v_fmac_f32_e32 v113, v218, v192
	v_fmac_f32_e32 v113, v219, v193
	v_fmac_f32_e32 v113, v220, v194
	v_fmac_f32_e32 v113, v221, v195
	v_fmac_f32_e32 v113, v222, v196
	v_fmac_f32_e32 v113, v223, v197
	v_fmac_f32_e32 v113, v224, v232
	v_fmac_f32_e32 v113, v225, v233
	v_fmac_f32_e32 v113, v226, v234
	v_fmac_f32_e32 v113, v227, v235
	v_fmac_f32_e32 v113, v228, v236
	v_fmac_f32_e32 v113, v229, v237
	v_fmac_f32_e32 v113, v230, v238
	v_fmac_f32_e32 v113, v231, v239
	ds_read_b128 v[190:193], v171 offset:14400
	ds_read_b128 v[194:197], v171 offset:14416
	ds_read_b128 v[232:235], v171 offset:14432
	ds_read_b128 v[236:239], v171 offset:14448
	s_waitcnt lgkmcnt(4)
	v_fmac_f32_e32 v110, v200, v174
	v_fmac_f32_e32 v110, v201, v175
	v_fmac_f32_e32 v110, v202, v176
	v_fmac_f32_e32 v110, v203, v177
	v_fmac_f32_e32 v110, v204, v178
	v_fmac_f32_e32 v110, v205, v179
	v_fmac_f32_e32 v110, v206, v180
	v_fmac_f32_e32 v110, v207, v181
	v_fmac_f32_e32 v110, v208, v182
	v_fmac_f32_e32 v110, v209, v183
	v_fmac_f32_e32 v110, v210, v184
	v_fmac_f32_e32 v110, v211, v185
	v_fmac_f32_e32 v110, v212, v186
	v_fmac_f32_e32 v110, v213, v187
	v_fmac_f32_e32 v110, v214, v188
	v_fmac_f32_e32 v110, v215, v189
	ds_read_b128 v[174:177], v171 offset:14848
	ds_read_b128 v[178:181], v171 offset:14864
	ds_read_b128 v[182:185], v171 offset:14880
	ds_read_b128 v[186:189], v171 offset:14896
	s_waitcnt lgkmcnt(4)
	v_fmac_f32_e32 v110, v216, v190
	v_fmac_f32_e32 v110, v217, v191
	v_fmac_f32_e32 v110, v218, v192
	v_fmac_f32_e32 v110, v219, v193
	v_fmac_f32_e32 v110, v220, v194
	v_fmac_f32_e32 v110, v221, v195
	v_fmac_f32_e32 v110, v222, v196
	v_fmac_f32_e32 v110, v223, v197
	v_fmac_f32_e32 v110, v224, v232
	v_fmac_f32_e32 v110, v225, v233
	v_fmac_f32_e32 v110, v226, v234
	v_fmac_f32_e32 v110, v227, v235
	v_fmac_f32_e32 v110, v228, v236
	v_fmac_f32_e32 v110, v229, v237
	v_fmac_f32_e32 v110, v230, v238
	v_fmac_f32_e32 v110, v231, v239
	ds_read_b128 v[190:193], v171 offset:14912
	ds_read_b128 v[194:197], v171 offset:14928
	ds_read_b128 v[232:235], v171 offset:14944
	ds_read_b128 v[236:239], v171 offset:14960
	s_waitcnt lgkmcnt(4)
	v_fmac_f32_e32 v111, v200, v174
	v_fmac_f32_e32 v111, v201, v175
	v_fmac_f32_e32 v111, v202, v176
	v_fmac_f32_e32 v111, v203, v177
	v_fmac_f32_e32 v111, v204, v178
	v_fmac_f32_e32 v111, v205, v179
	v_fmac_f32_e32 v111, v206, v180
	v_fmac_f32_e32 v111, v207, v181
	v_fmac_f32_e32 v111, v208, v182
	v_fmac_f32_e32 v111, v209, v183
	v_fmac_f32_e32 v111, v210, v184
	v_fmac_f32_e32 v111, v211, v185
	v_fmac_f32_e32 v111, v212, v186
	v_fmac_f32_e32 v111, v213, v187
	v_fmac_f32_e32 v111, v214, v188
	v_fmac_f32_e32 v111, v215, v189
	ds_read_b128 v[174:177], v171 offset:15360
	ds_read_b128 v[178:181], v171 offset:15376
	ds_read_b128 v[182:185], v171 offset:15392
	ds_read_b128 v[186:189], v171 offset:15408
	s_waitcnt lgkmcnt(4)
	v_fmac_f32_e32 v111, v216, v190
	v_fmac_f32_e32 v111, v217, v191
	v_fmac_f32_e32 v111, v218, v192
	v_fmac_f32_e32 v111, v219, v193
	v_fmac_f32_e32 v111, v220, v194
	v_fmac_f32_e32 v111, v221, v195
	v_fmac_f32_e32 v111, v222, v196
	v_fmac_f32_e32 v111, v223, v197
	v_fmac_f32_e32 v111, v224, v232
	v_fmac_f32_e32 v111, v225, v233
	v_fmac_f32_e32 v111, v226, v234
	v_fmac_f32_e32 v111, v227, v235
	v_fmac_f32_e32 v111, v228, v236
	v_fmac_f32_e32 v111, v229, v237
	v_fmac_f32_e32 v111, v230, v238
	v_fmac_f32_e32 v111, v231, v239
	ds_read_b128 v[190:193], v171 offset:15424
	ds_read_b128 v[194:197], v171 offset:15440
	ds_read_b128 v[232:235], v171 offset:15456
	ds_read_b128 v[236:239], v171 offset:15472
	s_waitcnt lgkmcnt(4)
	v_fmac_f32_e32 v40, v200, v174
	v_fmac_f32_e32 v40, v201, v175
	v_fmac_f32_e32 v40, v202, v176
	v_fmac_f32_e32 v40, v203, v177
	v_fmac_f32_e32 v40, v204, v178
	v_fmac_f32_e32 v40, v205, v179
	v_fmac_f32_e32 v40, v206, v180
	v_fmac_f32_e32 v40, v207, v181
	v_fmac_f32_e32 v40, v208, v182
	v_fmac_f32_e32 v40, v209, v183
	v_fmac_f32_e32 v40, v210, v184
	v_fmac_f32_e32 v40, v211, v185
	v_fmac_f32_e32 v40, v212, v186
	v_fmac_f32_e32 v40, v213, v187
	v_fmac_f32_e32 v40, v214, v188
	v_fmac_f32_e32 v40, v215, v189
	ds_read_b128 v[174:177], v171 offset:15872
	ds_read_b128 v[178:181], v171 offset:15888
	ds_read_b128 v[182:185], v171 offset:15904
	ds_read_b128 v[186:189], v171 offset:15920
	s_waitcnt lgkmcnt(4)
	v_fmac_f32_e32 v40, v216, v190
	v_fmac_f32_e32 v40, v217, v191
	v_fmac_f32_e32 v40, v218, v192
	v_fmac_f32_e32 v40, v219, v193
	v_fmac_f32_e32 v40, v220, v194
	v_fmac_f32_e32 v40, v221, v195
	v_fmac_f32_e32 v40, v222, v196
	v_fmac_f32_e32 v40, v223, v197
	v_fmac_f32_e32 v40, v224, v232
	v_fmac_f32_e32 v40, v225, v233
	v_fmac_f32_e32 v40, v226, v234
	v_fmac_f32_e32 v40, v227, v235
	v_fmac_f32_e32 v40, v228, v236
	v_fmac_f32_e32 v40, v229, v237
	v_fmac_f32_e32 v40, v230, v238
	v_fmac_f32_e32 v40, v231, v239
	ds_read_b128 v[190:193], v171 offset:15936
	ds_read_b128 v[194:197], v171 offset:15952
	ds_read_b128 v[232:235], v171 offset:15968
	ds_read_b128 v[236:239], v171 offset:15984
	s_waitcnt lgkmcnt(4)
	v_fmac_f32_e32 v41, v200, v174
	v_fmac_f32_e32 v41, v201, v175
	v_fmac_f32_e32 v41, v202, v176
	v_fmac_f32_e32 v41, v203, v177
	v_fmac_f32_e32 v41, v204, v178
	v_fmac_f32_e32 v41, v205, v179
	v_fmac_f32_e32 v41, v206, v180
	v_fmac_f32_e32 v41, v207, v181
	v_fmac_f32_e32 v41, v208, v182
	v_fmac_f32_e32 v41, v209, v183
	v_fmac_f32_e32 v41, v210, v184
	v_fmac_f32_e32 v41, v211, v185
	v_fmac_f32_e32 v41, v212, v186
	v_fmac_f32_e32 v41, v213, v187
	v_fmac_f32_e32 v41, v214, v188
	v_fmac_f32_e32 v41, v215, v189
	s_waitcnt lgkmcnt(0)
	v_fmac_f32_e32 v41, v216, v190
	v_fmac_f32_e32 v41, v217, v191
	v_fmac_f32_e32 v41, v218, v192
	v_fmac_f32_e32 v41, v219, v193
	v_fmac_f32_e32 v41, v220, v194
	v_fmac_f32_e32 v41, v221, v195
	v_fmac_f32_e32 v41, v222, v196
	v_fmac_f32_e32 v41, v223, v197
	v_fmac_f32_e32 v41, v224, v232
	v_fmac_f32_e32 v41, v225, v233
	v_fmac_f32_e32 v41, v226, v234
	v_fmac_f32_e32 v41, v227, v235
	v_fmac_f32_e32 v41, v228, v236
	v_fmac_f32_e32 v41, v229, v237
	v_fmac_f32_e32 v41, v230, v238
	v_fmac_f32_e32 v41, v231, v239
	global_load_dword v200, v[80:81], off
	v_lshl_add_u64 v[80:81], v[80:81], 0, s[20:21]
	global_load_dword v174, v97, s[14:15] offset:128
	global_load_dword v201, v[80:81], off
	v_lshl_add_u64 v[80:81], v[80:81], 0, s[20:21]
	global_load_dword v175, v97, s[14:15] offset:132
	global_load_dword v202, v[80:81], off
	v_lshl_add_u64 v[80:81], v[80:81], 0, s[20:21]
	global_load_dword v176, v97, s[14:15] offset:136
	global_load_dword v203, v[80:81], off
	v_lshl_add_u64 v[80:81], v[80:81], 0, s[20:21]
	global_load_dword v177, v97, s[14:15] offset:140
	global_load_dword v204, v[80:81], off
	v_lshl_add_u64 v[80:81], v[80:81], 0, s[20:21]
	global_load_dword v178, v97, s[14:15] offset:144
	global_load_dword v205, v[80:81], off
	v_lshl_add_u64 v[80:81], v[80:81], 0, s[20:21]
	global_load_dword v179, v97, s[14:15] offset:148
	global_load_dword v206, v[80:81], off
	v_lshl_add_u64 v[80:81], v[80:81], 0, s[20:21]
	global_load_dword v180, v97, s[14:15] offset:152
	global_load_dword v207, v[80:81], off
	v_lshl_add_u64 v[80:81], v[80:81], 0, s[20:21]
	global_load_dword v181, v97, s[14:15] offset:156
	global_load_dword v208, v[80:81], off
	v_lshl_add_u64 v[80:81], v[80:81], 0, s[20:21]
	global_load_dword v182, v97, s[14:15] offset:160
	global_load_dword v209, v[80:81], off
	v_lshl_add_u64 v[80:81], v[80:81], 0, s[20:21]
	global_load_dword v183, v97, s[14:15] offset:164
	global_load_dword v210, v[80:81], off
	v_lshl_add_u64 v[80:81], v[80:81], 0, s[20:21]
	global_load_dword v184, v97, s[14:15] offset:168
	global_load_dword v211, v[80:81], off
	v_lshl_add_u64 v[80:81], v[80:81], 0, s[20:21]
	global_load_dword v185, v97, s[14:15] offset:172
	global_load_dword v212, v[80:81], off
	v_lshl_add_u64 v[80:81], v[80:81], 0, s[20:21]
	global_load_dword v186, v97, s[14:15] offset:176
	global_load_dword v213, v[80:81], off
	v_lshl_add_u64 v[80:81], v[80:81], 0, s[20:21]
	global_load_dword v187, v97, s[14:15] offset:180
	global_load_dword v214, v[80:81], off
	v_lshl_add_u64 v[80:81], v[80:81], 0, s[20:21]
	global_load_dword v188, v97, s[14:15] offset:184
	global_load_dword v215, v[80:81], off
	v_lshl_add_u64 v[80:81], v[80:81], 0, s[20:21]
	global_load_dword v189, v97, s[14:15] offset:188
	s_waitcnt vmcnt(30)
	global_load_dword v216, v[80:81], off
	v_lshl_add_u64 v[80:81], v[80:81], 0, s[20:21]
	global_load_dword v190, v97, s[14:15] offset:192
	global_load_dword v217, v[80:81], off
	v_lshl_add_u64 v[80:81], v[80:81], 0, s[20:21]
	global_load_dword v191, v97, s[14:15] offset:196
	global_load_dword v218, v[80:81], off
	v_lshl_add_u64 v[80:81], v[80:81], 0, s[20:21]
	global_load_dword v192, v97, s[14:15] offset:200
	global_load_dword v219, v[80:81], off
	v_lshl_add_u64 v[80:81], v[80:81], 0, s[20:21]
	global_load_dword v193, v97, s[14:15] offset:204
	global_load_dword v220, v[80:81], off
	v_lshl_add_u64 v[80:81], v[80:81], 0, s[20:21]
	global_load_dword v194, v97, s[14:15] offset:208
	global_load_dword v221, v[80:81], off
	v_lshl_add_u64 v[80:81], v[80:81], 0, s[20:21]
	global_load_dword v195, v97, s[14:15] offset:212
	global_load_dword v222, v[80:81], off
	v_lshl_add_u64 v[80:81], v[80:81], 0, s[20:21]
	global_load_dword v196, v97, s[14:15] offset:216
	global_load_dword v223, v[80:81], off
	v_lshl_add_u64 v[80:81], v[80:81], 0, s[20:21]
	global_load_dword v197, v97, s[14:15] offset:220
	global_load_dword v224, v[80:81], off
	v_lshl_add_u64 v[80:81], v[80:81], 0, s[20:21]
	global_load_dword v232, v97, s[14:15] offset:224
	global_load_dword v225, v[80:81], off
	v_lshl_add_u64 v[80:81], v[80:81], 0, s[20:21]
	global_load_dword v233, v97, s[14:15] offset:228
	global_load_dword v226, v[80:81], off
	v_lshl_add_u64 v[80:81], v[80:81], 0, s[20:21]
	global_load_dword v234, v97, s[14:15] offset:232
	global_load_dword v227, v[80:81], off
	v_lshl_add_u64 v[80:81], v[80:81], 0, s[20:21]
	global_load_dword v235, v97, s[14:15] offset:236
	global_load_dword v228, v[80:81], off
	v_lshl_add_u64 v[80:81], v[80:81], 0, s[20:21]
	global_load_dword v236, v97, s[14:15] offset:240
	global_load_dword v229, v[80:81], off
	v_lshl_add_u64 v[80:81], v[80:81], 0, s[20:21]
	global_load_dword v237, v97, s[14:15] offset:244
	global_load_dword v230, v[80:81], off
	v_lshl_add_u64 v[80:81], v[80:81], 0, s[20:21]
	global_load_dword v238, v97, s[14:15] offset:248
	global_load_dword v231, v[80:81], off
	v_lshl_add_u64 v[80:81], v[80:81], 0, s[20:21]
	global_load_dword v239, v97, s[14:15] offset:252
	s_waitcnt vmcnt(0)
	v_mul_f32_e32 v200, v200, v174
	v_mul_f32_e32 v201, v201, v175
	v_mul_f32_e32 v202, v202, v176
	v_mul_f32_e32 v203, v203, v177
	v_mul_f32_e32 v204, v204, v178
	v_mul_f32_e32 v205, v205, v179
	v_mul_f32_e32 v206, v206, v180
	v_mul_f32_e32 v207, v207, v181
	v_mul_f32_e32 v208, v208, v182
	v_mul_f32_e32 v209, v209, v183
	v_mul_f32_e32 v210, v210, v184
	v_mul_f32_e32 v211, v211, v185
	v_mul_f32_e32 v212, v212, v186
	v_mul_f32_e32 v213, v213, v187
	v_mul_f32_e32 v214, v214, v188
	v_mul_f32_e32 v215, v215, v189
	v_mul_f32_e32 v216, v216, v190
	v_mul_f32_e32 v217, v217, v191
	v_mul_f32_e32 v218, v218, v192
	v_mul_f32_e32 v219, v219, v193
	v_mul_f32_e32 v220, v220, v194
	v_mul_f32_e32 v221, v221, v195
	v_mul_f32_e32 v222, v222, v196
	v_mul_f32_e32 v223, v223, v197
	v_mul_f32_e32 v224, v224, v232
	v_mul_f32_e32 v225, v225, v233
	v_mul_f32_e32 v226, v226, v234
	v_mul_f32_e32 v227, v227, v235
	v_mul_f32_e32 v228, v228, v236
	v_mul_f32_e32 v229, v229, v237
	v_mul_f32_e32 v230, v230, v238
	v_mul_f32_e32 v231, v231, v239
	ds_read_b128 v[174:177], v171 offset:128
	ds_read_b128 v[178:181], v171 offset:144
	ds_read_b128 v[182:185], v171 offset:160
	ds_read_b128 v[186:189], v171 offset:176
	ds_read_b128 v[190:193], v171 offset:192
	ds_read_b128 v[194:197], v171 offset:208
	ds_read_b128 v[232:235], v171 offset:224
	ds_read_b128 v[236:239], v171 offset:240
	s_waitcnt lgkmcnt(4)
	v_fmac_f32_e32 v82, v200, v174
	v_fmac_f32_e32 v82, v201, v175
	v_fmac_f32_e32 v82, v202, v176
	v_fmac_f32_e32 v82, v203, v177
	v_fmac_f32_e32 v82, v204, v178
	v_fmac_f32_e32 v82, v205, v179
	v_fmac_f32_e32 v82, v206, v180
	v_fmac_f32_e32 v82, v207, v181
	v_fmac_f32_e32 v82, v208, v182
	v_fmac_f32_e32 v82, v209, v183
	v_fmac_f32_e32 v82, v210, v184
	v_fmac_f32_e32 v82, v211, v185
	v_fmac_f32_e32 v82, v212, v186
	v_fmac_f32_e32 v82, v213, v187
	v_fmac_f32_e32 v82, v214, v188
	v_fmac_f32_e32 v82, v215, v189
	ds_read_b128 v[174:177], v171 offset:640
	ds_read_b128 v[178:181], v171 offset:656
	ds_read_b128 v[182:185], v171 offset:672
	ds_read_b128 v[186:189], v171 offset:688
	s_waitcnt lgkmcnt(4)
	v_fmac_f32_e32 v82, v216, v190
	v_fmac_f32_e32 v82, v217, v191
	v_fmac_f32_e32 v82, v218, v192
	v_fmac_f32_e32 v82, v219, v193
	v_fmac_f32_e32 v82, v220, v194
	v_fmac_f32_e32 v82, v221, v195
	v_fmac_f32_e32 v82, v222, v196
	v_fmac_f32_e32 v82, v223, v197
	v_fmac_f32_e32 v82, v224, v232
	v_fmac_f32_e32 v82, v225, v233
	v_fmac_f32_e32 v82, v226, v234
	v_fmac_f32_e32 v82, v227, v235
	v_fmac_f32_e32 v82, v228, v236
	v_fmac_f32_e32 v82, v229, v237
	v_fmac_f32_e32 v82, v230, v238
	v_fmac_f32_e32 v82, v231, v239
	ds_read_b128 v[190:193], v171 offset:704
	ds_read_b128 v[194:197], v171 offset:720
	ds_read_b128 v[232:235], v171 offset:736
	ds_read_b128 v[236:239], v171 offset:752
	s_waitcnt lgkmcnt(4)
	v_fmac_f32_e32 v83, v200, v174
	v_fmac_f32_e32 v83, v201, v175
	v_fmac_f32_e32 v83, v202, v176
	v_fmac_f32_e32 v83, v203, v177
	v_fmac_f32_e32 v83, v204, v178
	v_fmac_f32_e32 v83, v205, v179
	v_fmac_f32_e32 v83, v206, v180
	v_fmac_f32_e32 v83, v207, v181
	v_fmac_f32_e32 v83, v208, v182
	v_fmac_f32_e32 v83, v209, v183
	v_fmac_f32_e32 v83, v210, v184
	v_fmac_f32_e32 v83, v211, v185
	v_fmac_f32_e32 v83, v212, v186
	v_fmac_f32_e32 v83, v213, v187
	v_fmac_f32_e32 v83, v214, v188
	v_fmac_f32_e32 v83, v215, v189
	ds_read_b128 v[174:177], v171 offset:1152
	ds_read_b128 v[178:181], v171 offset:1168
	ds_read_b128 v[182:185], v171 offset:1184
	ds_read_b128 v[186:189], v171 offset:1200
	s_waitcnt lgkmcnt(4)
	v_fmac_f32_e32 v83, v216, v190
	v_fmac_f32_e32 v83, v217, v191
	v_fmac_f32_e32 v83, v218, v192
	v_fmac_f32_e32 v83, v219, v193
	v_fmac_f32_e32 v83, v220, v194
	v_fmac_f32_e32 v83, v221, v195
	v_fmac_f32_e32 v83, v222, v196
	v_fmac_f32_e32 v83, v223, v197
	v_fmac_f32_e32 v83, v224, v232
	v_fmac_f32_e32 v83, v225, v233
	v_fmac_f32_e32 v83, v226, v234
	v_fmac_f32_e32 v83, v227, v235
	v_fmac_f32_e32 v83, v228, v236
	v_fmac_f32_e32 v83, v229, v237
	v_fmac_f32_e32 v83, v230, v238
	v_fmac_f32_e32 v83, v231, v239
	ds_read_b128 v[190:193], v171 offset:1216
	ds_read_b128 v[194:197], v171 offset:1232
	ds_read_b128 v[232:235], v171 offset:1248
	ds_read_b128 v[236:239], v171 offset:1264
	s_waitcnt lgkmcnt(4)
	v_fmac_f32_e32 v86, v200, v174
	v_fmac_f32_e32 v86, v201, v175
	v_fmac_f32_e32 v86, v202, v176
	v_fmac_f32_e32 v86, v203, v177
	v_fmac_f32_e32 v86, v204, v178
	v_fmac_f32_e32 v86, v205, v179
	v_fmac_f32_e32 v86, v206, v180
	v_fmac_f32_e32 v86, v207, v181
	v_fmac_f32_e32 v86, v208, v182
	v_fmac_f32_e32 v86, v209, v183
	v_fmac_f32_e32 v86, v210, v184
	v_fmac_f32_e32 v86, v211, v185
	v_fmac_f32_e32 v86, v212, v186
	v_fmac_f32_e32 v86, v213, v187
	v_fmac_f32_e32 v86, v214, v188
	v_fmac_f32_e32 v86, v215, v189
	ds_read_b128 v[174:177], v171 offset:1664
	ds_read_b128 v[178:181], v171 offset:1680
	ds_read_b128 v[182:185], v171 offset:1696
	ds_read_b128 v[186:189], v171 offset:1712
	s_waitcnt lgkmcnt(4)
	v_fmac_f32_e32 v86, v216, v190
	v_fmac_f32_e32 v86, v217, v191
	v_fmac_f32_e32 v86, v218, v192
	v_fmac_f32_e32 v86, v219, v193
	v_fmac_f32_e32 v86, v220, v194
	v_fmac_f32_e32 v86, v221, v195
	v_fmac_f32_e32 v86, v222, v196
	v_fmac_f32_e32 v86, v223, v197
	v_fmac_f32_e32 v86, v224, v232
	v_fmac_f32_e32 v86, v225, v233
	v_fmac_f32_e32 v86, v226, v234
	v_fmac_f32_e32 v86, v227, v235
	v_fmac_f32_e32 v86, v228, v236
	v_fmac_f32_e32 v86, v229, v237
	v_fmac_f32_e32 v86, v230, v238
	v_fmac_f32_e32 v86, v231, v239
	ds_read_b128 v[190:193], v171 offset:1728
	ds_read_b128 v[194:197], v171 offset:1744
	ds_read_b128 v[232:235], v171 offset:1760
	ds_read_b128 v[236:239], v171 offset:1776
	s_waitcnt lgkmcnt(4)
	v_fmac_f32_e32 v87, v200, v174
	v_fmac_f32_e32 v87, v201, v175
	v_fmac_f32_e32 v87, v202, v176
	v_fmac_f32_e32 v87, v203, v177
	v_fmac_f32_e32 v87, v204, v178
	v_fmac_f32_e32 v87, v205, v179
	v_fmac_f32_e32 v87, v206, v180
	v_fmac_f32_e32 v87, v207, v181
	v_fmac_f32_e32 v87, v208, v182
	v_fmac_f32_e32 v87, v209, v183
	v_fmac_f32_e32 v87, v210, v184
	v_fmac_f32_e32 v87, v211, v185
	v_fmac_f32_e32 v87, v212, v186
	v_fmac_f32_e32 v87, v213, v187
	v_fmac_f32_e32 v87, v214, v188
	v_fmac_f32_e32 v87, v215, v189
	ds_read_b128 v[174:177], v171 offset:2176
	ds_read_b128 v[178:181], v171 offset:2192
	ds_read_b128 v[182:185], v171 offset:2208
	ds_read_b128 v[186:189], v171 offset:2224
	s_waitcnt lgkmcnt(4)
	v_fmac_f32_e32 v87, v216, v190
	v_fmac_f32_e32 v87, v217, v191
	v_fmac_f32_e32 v87, v218, v192
	v_fmac_f32_e32 v87, v219, v193
	v_fmac_f32_e32 v87, v220, v194
	v_fmac_f32_e32 v87, v221, v195
	v_fmac_f32_e32 v87, v222, v196
	v_fmac_f32_e32 v87, v223, v197
	v_fmac_f32_e32 v87, v224, v232
	v_fmac_f32_e32 v87, v225, v233
	v_fmac_f32_e32 v87, v226, v234
	v_fmac_f32_e32 v87, v227, v235
	v_fmac_f32_e32 v87, v228, v236
	v_fmac_f32_e32 v87, v229, v237
	v_fmac_f32_e32 v87, v230, v238
	v_fmac_f32_e32 v87, v231, v239
	ds_read_b128 v[190:193], v171 offset:2240
	ds_read_b128 v[194:197], v171 offset:2256
	ds_read_b128 v[232:235], v171 offset:2272
	ds_read_b128 v[236:239], v171 offset:2288
	s_waitcnt lgkmcnt(4)
	v_fmac_f32_e32 v84, v200, v174
	v_fmac_f32_e32 v84, v201, v175
	v_fmac_f32_e32 v84, v202, v176
	v_fmac_f32_e32 v84, v203, v177
	v_fmac_f32_e32 v84, v204, v178
	v_fmac_f32_e32 v84, v205, v179
	v_fmac_f32_e32 v84, v206, v180
	v_fmac_f32_e32 v84, v207, v181
	v_fmac_f32_e32 v84, v208, v182
	v_fmac_f32_e32 v84, v209, v183
	v_fmac_f32_e32 v84, v210, v184
	v_fmac_f32_e32 v84, v211, v185
	v_fmac_f32_e32 v84, v212, v186
	v_fmac_f32_e32 v84, v213, v187
	v_fmac_f32_e32 v84, v214, v188
	v_fmac_f32_e32 v84, v215, v189
	ds_read_b128 v[174:177], v171 offset:2688
	ds_read_b128 v[178:181], v171 offset:2704
	ds_read_b128 v[182:185], v171 offset:2720
	ds_read_b128 v[186:189], v171 offset:2736
	s_waitcnt lgkmcnt(4)
	v_fmac_f32_e32 v84, v216, v190
	v_fmac_f32_e32 v84, v217, v191
	v_fmac_f32_e32 v84, v218, v192
	v_fmac_f32_e32 v84, v219, v193
	v_fmac_f32_e32 v84, v220, v194
	v_fmac_f32_e32 v84, v221, v195
	v_fmac_f32_e32 v84, v222, v196
	v_fmac_f32_e32 v84, v223, v197
	v_fmac_f32_e32 v84, v224, v232
	v_fmac_f32_e32 v84, v225, v233
	v_fmac_f32_e32 v84, v226, v234
	v_fmac_f32_e32 v84, v227, v235
	v_fmac_f32_e32 v84, v228, v236
	v_fmac_f32_e32 v84, v229, v237
	v_fmac_f32_e32 v84, v230, v238
	v_fmac_f32_e32 v84, v231, v239
	ds_read_b128 v[190:193], v171 offset:2752
	ds_read_b128 v[194:197], v171 offset:2768
	ds_read_b128 v[232:235], v171 offset:2784
	ds_read_b128 v[236:239], v171 offset:2800
	s_waitcnt lgkmcnt(4)
	v_fmac_f32_e32 v85, v200, v174
	v_fmac_f32_e32 v85, v201, v175
	v_fmac_f32_e32 v85, v202, v176
	v_fmac_f32_e32 v85, v203, v177
	v_fmac_f32_e32 v85, v204, v178
	v_fmac_f32_e32 v85, v205, v179
	v_fmac_f32_e32 v85, v206, v180
	v_fmac_f32_e32 v85, v207, v181
	v_fmac_f32_e32 v85, v208, v182
	v_fmac_f32_e32 v85, v209, v183
	v_fmac_f32_e32 v85, v210, v184
	v_fmac_f32_e32 v85, v211, v185
	v_fmac_f32_e32 v85, v212, v186
	v_fmac_f32_e32 v85, v213, v187
	v_fmac_f32_e32 v85, v214, v188
	v_fmac_f32_e32 v85, v215, v189
	ds_read_b128 v[174:177], v171 offset:3200
	ds_read_b128 v[178:181], v171 offset:3216
	ds_read_b128 v[182:185], v171 offset:3232
	ds_read_b128 v[186:189], v171 offset:3248
	s_waitcnt lgkmcnt(4)
	v_fmac_f32_e32 v85, v216, v190
	v_fmac_f32_e32 v85, v217, v191
	v_fmac_f32_e32 v85, v218, v192
	v_fmac_f32_e32 v85, v219, v193
	v_fmac_f32_e32 v85, v220, v194
	v_fmac_f32_e32 v85, v221, v195
	v_fmac_f32_e32 v85, v222, v196
	v_fmac_f32_e32 v85, v223, v197
	v_fmac_f32_e32 v85, v224, v232
	v_fmac_f32_e32 v85, v225, v233
	v_fmac_f32_e32 v85, v226, v234
	v_fmac_f32_e32 v85, v227, v235
	v_fmac_f32_e32 v85, v228, v236
	v_fmac_f32_e32 v85, v229, v237
	v_fmac_f32_e32 v85, v230, v238
	v_fmac_f32_e32 v85, v231, v239
	ds_read_b128 v[190:193], v171 offset:3264
	ds_read_b128 v[194:197], v171 offset:3280
	ds_read_b128 v[232:235], v171 offset:3296
	ds_read_b128 v[236:239], v171 offset:3312
	s_waitcnt lgkmcnt(4)
	v_fmac_f32_e32 v90, v200, v174
	v_fmac_f32_e32 v90, v201, v175
	v_fmac_f32_e32 v90, v202, v176
	v_fmac_f32_e32 v90, v203, v177
	v_fmac_f32_e32 v90, v204, v178
	v_fmac_f32_e32 v90, v205, v179
	v_fmac_f32_e32 v90, v206, v180
	v_fmac_f32_e32 v90, v207, v181
	v_fmac_f32_e32 v90, v208, v182
	v_fmac_f32_e32 v90, v209, v183
	v_fmac_f32_e32 v90, v210, v184
	v_fmac_f32_e32 v90, v211, v185
	v_fmac_f32_e32 v90, v212, v186
	v_fmac_f32_e32 v90, v213, v187
	v_fmac_f32_e32 v90, v214, v188
	v_fmac_f32_e32 v90, v215, v189
	ds_read_b128 v[174:177], v171 offset:3712
	ds_read_b128 v[178:181], v171 offset:3728
	ds_read_b128 v[182:185], v171 offset:3744
	ds_read_b128 v[186:189], v171 offset:3760
	s_waitcnt lgkmcnt(4)
	v_fmac_f32_e32 v90, v216, v190
	v_fmac_f32_e32 v90, v217, v191
	v_fmac_f32_e32 v90, v218, v192
	v_fmac_f32_e32 v90, v219, v193
	v_fmac_f32_e32 v90, v220, v194
	v_fmac_f32_e32 v90, v221, v195
	v_fmac_f32_e32 v90, v222, v196
	v_fmac_f32_e32 v90, v223, v197
	v_fmac_f32_e32 v90, v224, v232
	v_fmac_f32_e32 v90, v225, v233
	v_fmac_f32_e32 v90, v226, v234
	v_fmac_f32_e32 v90, v227, v235
	v_fmac_f32_e32 v90, v228, v236
	v_fmac_f32_e32 v90, v229, v237
	v_fmac_f32_e32 v90, v230, v238
	v_fmac_f32_e32 v90, v231, v239
	ds_read_b128 v[190:193], v171 offset:3776
	ds_read_b128 v[194:197], v171 offset:3792
	ds_read_b128 v[232:235], v171 offset:3808
	ds_read_b128 v[236:239], v171 offset:3824
	s_waitcnt lgkmcnt(4)
	v_fmac_f32_e32 v91, v200, v174
	v_fmac_f32_e32 v91, v201, v175
	v_fmac_f32_e32 v91, v202, v176
	v_fmac_f32_e32 v91, v203, v177
	v_fmac_f32_e32 v91, v204, v178
	v_fmac_f32_e32 v91, v205, v179
	v_fmac_f32_e32 v91, v206, v180
	v_fmac_f32_e32 v91, v207, v181
	v_fmac_f32_e32 v91, v208, v182
	v_fmac_f32_e32 v91, v209, v183
	v_fmac_f32_e32 v91, v210, v184
	v_fmac_f32_e32 v91, v211, v185
	v_fmac_f32_e32 v91, v212, v186
	v_fmac_f32_e32 v91, v213, v187
	v_fmac_f32_e32 v91, v214, v188
	v_fmac_f32_e32 v91, v215, v189
	ds_read_b128 v[174:177], v171 offset:4224
	ds_read_b128 v[178:181], v171 offset:4240
	ds_read_b128 v[182:185], v171 offset:4256
	ds_read_b128 v[186:189], v171 offset:4272
	s_waitcnt lgkmcnt(4)
	v_fmac_f32_e32 v91, v216, v190
	v_fmac_f32_e32 v91, v217, v191
	v_fmac_f32_e32 v91, v218, v192
	v_fmac_f32_e32 v91, v219, v193
	v_fmac_f32_e32 v91, v220, v194
	v_fmac_f32_e32 v91, v221, v195
	v_fmac_f32_e32 v91, v222, v196
	v_fmac_f32_e32 v91, v223, v197
	v_fmac_f32_e32 v91, v224, v232
	v_fmac_f32_e32 v91, v225, v233
	v_fmac_f32_e32 v91, v226, v234
	v_fmac_f32_e32 v91, v227, v235
	v_fmac_f32_e32 v91, v228, v236
	v_fmac_f32_e32 v91, v229, v237
	v_fmac_f32_e32 v91, v230, v238
	v_fmac_f32_e32 v91, v231, v239
	ds_read_b128 v[190:193], v171 offset:4288
	ds_read_b128 v[194:197], v171 offset:4304
	ds_read_b128 v[232:235], v171 offset:4320
	ds_read_b128 v[236:239], v171 offset:4336
	s_waitcnt lgkmcnt(4)
	v_fmac_f32_e32 v88, v200, v174
	v_fmac_f32_e32 v88, v201, v175
	v_fmac_f32_e32 v88, v202, v176
	v_fmac_f32_e32 v88, v203, v177
	v_fmac_f32_e32 v88, v204, v178
	v_fmac_f32_e32 v88, v205, v179
	v_fmac_f32_e32 v88, v206, v180
	v_fmac_f32_e32 v88, v207, v181
	v_fmac_f32_e32 v88, v208, v182
	v_fmac_f32_e32 v88, v209, v183
	v_fmac_f32_e32 v88, v210, v184
	v_fmac_f32_e32 v88, v211, v185
	v_fmac_f32_e32 v88, v212, v186
	v_fmac_f32_e32 v88, v213, v187
	v_fmac_f32_e32 v88, v214, v188
	v_fmac_f32_e32 v88, v215, v189
	ds_read_b128 v[174:177], v171 offset:4736
	ds_read_b128 v[178:181], v171 offset:4752
	ds_read_b128 v[182:185], v171 offset:4768
	ds_read_b128 v[186:189], v171 offset:4784
	s_waitcnt lgkmcnt(4)
	v_fmac_f32_e32 v88, v216, v190
	v_fmac_f32_e32 v88, v217, v191
	v_fmac_f32_e32 v88, v218, v192
	v_fmac_f32_e32 v88, v219, v193
	v_fmac_f32_e32 v88, v220, v194
	v_fmac_f32_e32 v88, v221, v195
	v_fmac_f32_e32 v88, v222, v196
	v_fmac_f32_e32 v88, v223, v197
	v_fmac_f32_e32 v88, v224, v232
	v_fmac_f32_e32 v88, v225, v233
	v_fmac_f32_e32 v88, v226, v234
	v_fmac_f32_e32 v88, v227, v235
	v_fmac_f32_e32 v88, v228, v236
	v_fmac_f32_e32 v88, v229, v237
	v_fmac_f32_e32 v88, v230, v238
	v_fmac_f32_e32 v88, v231, v239
	ds_read_b128 v[190:193], v171 offset:4800
	ds_read_b128 v[194:197], v171 offset:4816
	ds_read_b128 v[232:235], v171 offset:4832
	ds_read_b128 v[236:239], v171 offset:4848
	s_waitcnt lgkmcnt(4)
	v_fmac_f32_e32 v89, v200, v174
	v_fmac_f32_e32 v89, v201, v175
	v_fmac_f32_e32 v89, v202, v176
	v_fmac_f32_e32 v89, v203, v177
	v_fmac_f32_e32 v89, v204, v178
	v_fmac_f32_e32 v89, v205, v179
	v_fmac_f32_e32 v89, v206, v180
	v_fmac_f32_e32 v89, v207, v181
	v_fmac_f32_e32 v89, v208, v182
	v_fmac_f32_e32 v89, v209, v183
	v_fmac_f32_e32 v89, v210, v184
	v_fmac_f32_e32 v89, v211, v185
	v_fmac_f32_e32 v89, v212, v186
	v_fmac_f32_e32 v89, v213, v187
	v_fmac_f32_e32 v89, v214, v188
	v_fmac_f32_e32 v89, v215, v189
	ds_read_b128 v[174:177], v171 offset:5248
	ds_read_b128 v[178:181], v171 offset:5264
	ds_read_b128 v[182:185], v171 offset:5280
	ds_read_b128 v[186:189], v171 offset:5296
	s_waitcnt lgkmcnt(4)
	v_fmac_f32_e32 v89, v216, v190
	v_fmac_f32_e32 v89, v217, v191
	v_fmac_f32_e32 v89, v218, v192
	v_fmac_f32_e32 v89, v219, v193
	v_fmac_f32_e32 v89, v220, v194
	v_fmac_f32_e32 v89, v221, v195
	v_fmac_f32_e32 v89, v222, v196
	v_fmac_f32_e32 v89, v223, v197
	v_fmac_f32_e32 v89, v224, v232
	v_fmac_f32_e32 v89, v225, v233
	v_fmac_f32_e32 v89, v226, v234
	v_fmac_f32_e32 v89, v227, v235
	v_fmac_f32_e32 v89, v228, v236
	v_fmac_f32_e32 v89, v229, v237
	v_fmac_f32_e32 v89, v230, v238
	v_fmac_f32_e32 v89, v231, v239
	ds_read_b128 v[190:193], v171 offset:5312
	ds_read_b128 v[194:197], v171 offset:5328
	ds_read_b128 v[232:235], v171 offset:5344
	ds_read_b128 v[236:239], v171 offset:5360
	s_waitcnt lgkmcnt(4)
	v_fmac_f32_e32 v94, v200, v174
	v_fmac_f32_e32 v94, v201, v175
	v_fmac_f32_e32 v94, v202, v176
	v_fmac_f32_e32 v94, v203, v177
	v_fmac_f32_e32 v94, v204, v178
	v_fmac_f32_e32 v94, v205, v179
	v_fmac_f32_e32 v94, v206, v180
	v_fmac_f32_e32 v94, v207, v181
	v_fmac_f32_e32 v94, v208, v182
	v_fmac_f32_e32 v94, v209, v183
	v_fmac_f32_e32 v94, v210, v184
	v_fmac_f32_e32 v94, v211, v185
	v_fmac_f32_e32 v94, v212, v186
	v_fmac_f32_e32 v94, v213, v187
	v_fmac_f32_e32 v94, v214, v188
	v_fmac_f32_e32 v94, v215, v189
	ds_read_b128 v[174:177], v171 offset:5760
	ds_read_b128 v[178:181], v171 offset:5776
	ds_read_b128 v[182:185], v171 offset:5792
	ds_read_b128 v[186:189], v171 offset:5808
	s_waitcnt lgkmcnt(4)
	v_fmac_f32_e32 v94, v216, v190
	v_fmac_f32_e32 v94, v217, v191
	v_fmac_f32_e32 v94, v218, v192
	v_fmac_f32_e32 v94, v219, v193
	v_fmac_f32_e32 v94, v220, v194
	v_fmac_f32_e32 v94, v221, v195
	v_fmac_f32_e32 v94, v222, v196
	v_fmac_f32_e32 v94, v223, v197
	v_fmac_f32_e32 v94, v224, v232
	v_fmac_f32_e32 v94, v225, v233
	v_fmac_f32_e32 v94, v226, v234
	v_fmac_f32_e32 v94, v227, v235
	v_fmac_f32_e32 v94, v228, v236
	v_fmac_f32_e32 v94, v229, v237
	v_fmac_f32_e32 v94, v230, v238
	v_fmac_f32_e32 v94, v231, v239
	ds_read_b128 v[190:193], v171 offset:5824
	ds_read_b128 v[194:197], v171 offset:5840
	ds_read_b128 v[232:235], v171 offset:5856
	ds_read_b128 v[236:239], v171 offset:5872
	s_waitcnt lgkmcnt(4)
	v_fmac_f32_e32 v95, v200, v174
	v_fmac_f32_e32 v95, v201, v175
	v_fmac_f32_e32 v95, v202, v176
	v_fmac_f32_e32 v95, v203, v177
	v_fmac_f32_e32 v95, v204, v178
	v_fmac_f32_e32 v95, v205, v179
	v_fmac_f32_e32 v95, v206, v180
	v_fmac_f32_e32 v95, v207, v181
	v_fmac_f32_e32 v95, v208, v182
	v_fmac_f32_e32 v95, v209, v183
	v_fmac_f32_e32 v95, v210, v184
	v_fmac_f32_e32 v95, v211, v185
	v_fmac_f32_e32 v95, v212, v186
	v_fmac_f32_e32 v95, v213, v187
	v_fmac_f32_e32 v95, v214, v188
	v_fmac_f32_e32 v95, v215, v189
	ds_read_b128 v[174:177], v171 offset:6272
	ds_read_b128 v[178:181], v171 offset:6288
	ds_read_b128 v[182:185], v171 offset:6304
	ds_read_b128 v[186:189], v171 offset:6320
	s_waitcnt lgkmcnt(4)
	v_fmac_f32_e32 v95, v216, v190
	v_fmac_f32_e32 v95, v217, v191
	v_fmac_f32_e32 v95, v218, v192
	v_fmac_f32_e32 v95, v219, v193
	v_fmac_f32_e32 v95, v220, v194
	v_fmac_f32_e32 v95, v221, v195
	v_fmac_f32_e32 v95, v222, v196
	v_fmac_f32_e32 v95, v223, v197
	v_fmac_f32_e32 v95, v224, v232
	v_fmac_f32_e32 v95, v225, v233
	v_fmac_f32_e32 v95, v226, v234
	v_fmac_f32_e32 v95, v227, v235
	v_fmac_f32_e32 v95, v228, v236
	v_fmac_f32_e32 v95, v229, v237
	v_fmac_f32_e32 v95, v230, v238
	v_fmac_f32_e32 v95, v231, v239
	ds_read_b128 v[190:193], v171 offset:6336
	ds_read_b128 v[194:197], v171 offset:6352
	ds_read_b128 v[232:235], v171 offset:6368
	ds_read_b128 v[236:239], v171 offset:6384
	s_waitcnt lgkmcnt(4)
	v_fmac_f32_e32 v92, v200, v174
	v_fmac_f32_e32 v92, v201, v175
	v_fmac_f32_e32 v92, v202, v176
	v_fmac_f32_e32 v92, v203, v177
	v_fmac_f32_e32 v92, v204, v178
	v_fmac_f32_e32 v92, v205, v179
	v_fmac_f32_e32 v92, v206, v180
	v_fmac_f32_e32 v92, v207, v181
	v_fmac_f32_e32 v92, v208, v182
	v_fmac_f32_e32 v92, v209, v183
	v_fmac_f32_e32 v92, v210, v184
	v_fmac_f32_e32 v92, v211, v185
	v_fmac_f32_e32 v92, v212, v186
	v_fmac_f32_e32 v92, v213, v187
	v_fmac_f32_e32 v92, v214, v188
	v_fmac_f32_e32 v92, v215, v189
	ds_read_b128 v[174:177], v171 offset:6784
	ds_read_b128 v[178:181], v171 offset:6800
	ds_read_b128 v[182:185], v171 offset:6816
	ds_read_b128 v[186:189], v171 offset:6832
	s_waitcnt lgkmcnt(4)
	v_fmac_f32_e32 v92, v216, v190
	v_fmac_f32_e32 v92, v217, v191
	v_fmac_f32_e32 v92, v218, v192
	v_fmac_f32_e32 v92, v219, v193
	v_fmac_f32_e32 v92, v220, v194
	v_fmac_f32_e32 v92, v221, v195
	v_fmac_f32_e32 v92, v222, v196
	v_fmac_f32_e32 v92, v223, v197
	v_fmac_f32_e32 v92, v224, v232
	v_fmac_f32_e32 v92, v225, v233
	v_fmac_f32_e32 v92, v226, v234
	v_fmac_f32_e32 v92, v227, v235
	v_fmac_f32_e32 v92, v228, v236
	v_fmac_f32_e32 v92, v229, v237
	v_fmac_f32_e32 v92, v230, v238
	v_fmac_f32_e32 v92, v231, v239
	ds_read_b128 v[190:193], v171 offset:6848
	ds_read_b128 v[194:197], v171 offset:6864
	ds_read_b128 v[232:235], v171 offset:6880
	ds_read_b128 v[236:239], v171 offset:6896
	s_waitcnt lgkmcnt(4)
	v_fmac_f32_e32 v93, v200, v174
	v_fmac_f32_e32 v93, v201, v175
	v_fmac_f32_e32 v93, v202, v176
	v_fmac_f32_e32 v93, v203, v177
	v_fmac_f32_e32 v93, v204, v178
	v_fmac_f32_e32 v93, v205, v179
	v_fmac_f32_e32 v93, v206, v180
	v_fmac_f32_e32 v93, v207, v181
	v_fmac_f32_e32 v93, v208, v182
	v_fmac_f32_e32 v93, v209, v183
	v_fmac_f32_e32 v93, v210, v184
	v_fmac_f32_e32 v93, v211, v185
	v_fmac_f32_e32 v93, v212, v186
	v_fmac_f32_e32 v93, v213, v187
	v_fmac_f32_e32 v93, v214, v188
	v_fmac_f32_e32 v93, v215, v189
	ds_read_b128 v[174:177], v171 offset:7296
	ds_read_b128 v[178:181], v171 offset:7312
	ds_read_b128 v[182:185], v171 offset:7328
	ds_read_b128 v[186:189], v171 offset:7344
	s_waitcnt lgkmcnt(4)
	v_fmac_f32_e32 v93, v216, v190
	v_fmac_f32_e32 v93, v217, v191
	v_fmac_f32_e32 v93, v218, v192
	v_fmac_f32_e32 v93, v219, v193
	v_fmac_f32_e32 v93, v220, v194
	v_fmac_f32_e32 v93, v221, v195
	v_fmac_f32_e32 v93, v222, v196
	v_fmac_f32_e32 v93, v223, v197
	v_fmac_f32_e32 v93, v224, v232
	v_fmac_f32_e32 v93, v225, v233
	v_fmac_f32_e32 v93, v226, v234
	v_fmac_f32_e32 v93, v227, v235
	v_fmac_f32_e32 v93, v228, v236
	v_fmac_f32_e32 v93, v229, v237
	v_fmac_f32_e32 v93, v230, v238
	v_fmac_f32_e32 v93, v231, v239
	ds_read_b128 v[190:193], v171 offset:7360
	ds_read_b128 v[194:197], v171 offset:7376
	ds_read_b128 v[232:235], v171 offset:7392
	ds_read_b128 v[236:239], v171 offset:7408
	s_waitcnt lgkmcnt(4)
	v_fmac_f32_e32 v100, v200, v174
	v_fmac_f32_e32 v100, v201, v175
	v_fmac_f32_e32 v100, v202, v176
	v_fmac_f32_e32 v100, v203, v177
	v_fmac_f32_e32 v100, v204, v178
	v_fmac_f32_e32 v100, v205, v179
	v_fmac_f32_e32 v100, v206, v180
	v_fmac_f32_e32 v100, v207, v181
	v_fmac_f32_e32 v100, v208, v182
	v_fmac_f32_e32 v100, v209, v183
	v_fmac_f32_e32 v100, v210, v184
	v_fmac_f32_e32 v100, v211, v185
	v_fmac_f32_e32 v100, v212, v186
	v_fmac_f32_e32 v100, v213, v187
	v_fmac_f32_e32 v100, v214, v188
	v_fmac_f32_e32 v100, v215, v189
	ds_read_b128 v[174:177], v171 offset:7808
	ds_read_b128 v[178:181], v171 offset:7824
	ds_read_b128 v[182:185], v171 offset:7840
	ds_read_b128 v[186:189], v171 offset:7856
	s_waitcnt lgkmcnt(4)
	v_fmac_f32_e32 v100, v216, v190
	v_fmac_f32_e32 v100, v217, v191
	v_fmac_f32_e32 v100, v218, v192
	v_fmac_f32_e32 v100, v219, v193
	v_fmac_f32_e32 v100, v220, v194
	v_fmac_f32_e32 v100, v221, v195
	v_fmac_f32_e32 v100, v222, v196
	v_fmac_f32_e32 v100, v223, v197
	v_fmac_f32_e32 v100, v224, v232
	v_fmac_f32_e32 v100, v225, v233
	v_fmac_f32_e32 v100, v226, v234
	v_fmac_f32_e32 v100, v227, v235
	v_fmac_f32_e32 v100, v228, v236
	v_fmac_f32_e32 v100, v229, v237
	v_fmac_f32_e32 v100, v230, v238
	v_fmac_f32_e32 v100, v231, v239
	ds_read_b128 v[190:193], v171 offset:7872
	ds_read_b128 v[194:197], v171 offset:7888
	ds_read_b128 v[232:235], v171 offset:7904
	ds_read_b128 v[236:239], v171 offset:7920
	s_waitcnt lgkmcnt(4)
	v_fmac_f32_e32 v101, v200, v174
	v_fmac_f32_e32 v101, v201, v175
	v_fmac_f32_e32 v101, v202, v176
	v_fmac_f32_e32 v101, v203, v177
	v_fmac_f32_e32 v101, v204, v178
	v_fmac_f32_e32 v101, v205, v179
	v_fmac_f32_e32 v101, v206, v180
	v_fmac_f32_e32 v101, v207, v181
	v_fmac_f32_e32 v101, v208, v182
	v_fmac_f32_e32 v101, v209, v183
	v_fmac_f32_e32 v101, v210, v184
	v_fmac_f32_e32 v101, v211, v185
	v_fmac_f32_e32 v101, v212, v186
	v_fmac_f32_e32 v101, v213, v187
	v_fmac_f32_e32 v101, v214, v188
	v_fmac_f32_e32 v101, v215, v189
	ds_read_b128 v[174:177], v171 offset:8320
	ds_read_b128 v[178:181], v171 offset:8336
	ds_read_b128 v[182:185], v171 offset:8352
	ds_read_b128 v[186:189], v171 offset:8368
	s_waitcnt lgkmcnt(4)
	v_fmac_f32_e32 v101, v216, v190
	v_fmac_f32_e32 v101, v217, v191
	v_fmac_f32_e32 v101, v218, v192
	v_fmac_f32_e32 v101, v219, v193
	v_fmac_f32_e32 v101, v220, v194
	v_fmac_f32_e32 v101, v221, v195
	v_fmac_f32_e32 v101, v222, v196
	v_fmac_f32_e32 v101, v223, v197
	v_fmac_f32_e32 v101, v224, v232
	v_fmac_f32_e32 v101, v225, v233
	v_fmac_f32_e32 v101, v226, v234
	v_fmac_f32_e32 v101, v227, v235
	v_fmac_f32_e32 v101, v228, v236
	v_fmac_f32_e32 v101, v229, v237
	v_fmac_f32_e32 v101, v230, v238
	v_fmac_f32_e32 v101, v231, v239
	ds_read_b128 v[190:193], v171 offset:8384
	ds_read_b128 v[194:197], v171 offset:8400
	ds_read_b128 v[232:235], v171 offset:8416
	ds_read_b128 v[236:239], v171 offset:8432
	s_waitcnt lgkmcnt(4)
	v_fmac_f32_e32 v98, v200, v174
	v_fmac_f32_e32 v98, v201, v175
	v_fmac_f32_e32 v98, v202, v176
	v_fmac_f32_e32 v98, v203, v177
	v_fmac_f32_e32 v98, v204, v178
	v_fmac_f32_e32 v98, v205, v179
	v_fmac_f32_e32 v98, v206, v180
	v_fmac_f32_e32 v98, v207, v181
	v_fmac_f32_e32 v98, v208, v182
	v_fmac_f32_e32 v98, v209, v183
	v_fmac_f32_e32 v98, v210, v184
	v_fmac_f32_e32 v98, v211, v185
	v_fmac_f32_e32 v98, v212, v186
	v_fmac_f32_e32 v98, v213, v187
	v_fmac_f32_e32 v98, v214, v188
	v_fmac_f32_e32 v98, v215, v189
	ds_read_b128 v[174:177], v171 offset:8832
	ds_read_b128 v[178:181], v171 offset:8848
	ds_read_b128 v[182:185], v171 offset:8864
	ds_read_b128 v[186:189], v171 offset:8880
	s_waitcnt lgkmcnt(4)
	v_fmac_f32_e32 v98, v216, v190
	v_fmac_f32_e32 v98, v217, v191
	v_fmac_f32_e32 v98, v218, v192
	v_fmac_f32_e32 v98, v219, v193
	v_fmac_f32_e32 v98, v220, v194
	v_fmac_f32_e32 v98, v221, v195
	v_fmac_f32_e32 v98, v222, v196
	v_fmac_f32_e32 v98, v223, v197
	v_fmac_f32_e32 v98, v224, v232
	v_fmac_f32_e32 v98, v225, v233
	v_fmac_f32_e32 v98, v226, v234
	v_fmac_f32_e32 v98, v227, v235
	v_fmac_f32_e32 v98, v228, v236
	v_fmac_f32_e32 v98, v229, v237
	v_fmac_f32_e32 v98, v230, v238
	v_fmac_f32_e32 v98, v231, v239
	ds_read_b128 v[190:193], v171 offset:8896
	ds_read_b128 v[194:197], v171 offset:8912
	ds_read_b128 v[232:235], v171 offset:8928
	ds_read_b128 v[236:239], v171 offset:8944
	s_waitcnt lgkmcnt(4)
	v_fmac_f32_e32 v99, v200, v174
	v_fmac_f32_e32 v99, v201, v175
	v_fmac_f32_e32 v99, v202, v176
	v_fmac_f32_e32 v99, v203, v177
	v_fmac_f32_e32 v99, v204, v178
	v_fmac_f32_e32 v99, v205, v179
	v_fmac_f32_e32 v99, v206, v180
	v_fmac_f32_e32 v99, v207, v181
	v_fmac_f32_e32 v99, v208, v182
	v_fmac_f32_e32 v99, v209, v183
	v_fmac_f32_e32 v99, v210, v184
	v_fmac_f32_e32 v99, v211, v185
	v_fmac_f32_e32 v99, v212, v186
	v_fmac_f32_e32 v99, v213, v187
	v_fmac_f32_e32 v99, v214, v188
	v_fmac_f32_e32 v99, v215, v189
	ds_read_b128 v[174:177], v171 offset:9344
	ds_read_b128 v[178:181], v171 offset:9360
	ds_read_b128 v[182:185], v171 offset:9376
	ds_read_b128 v[186:189], v171 offset:9392
	s_waitcnt lgkmcnt(4)
	v_fmac_f32_e32 v99, v216, v190
	v_fmac_f32_e32 v99, v217, v191
	v_fmac_f32_e32 v99, v218, v192
	v_fmac_f32_e32 v99, v219, v193
	v_fmac_f32_e32 v99, v220, v194
	v_fmac_f32_e32 v99, v221, v195
	v_fmac_f32_e32 v99, v222, v196
	v_fmac_f32_e32 v99, v223, v197
	v_fmac_f32_e32 v99, v224, v232
	v_fmac_f32_e32 v99, v225, v233
	v_fmac_f32_e32 v99, v226, v234
	v_fmac_f32_e32 v99, v227, v235
	v_fmac_f32_e32 v99, v228, v236
	v_fmac_f32_e32 v99, v229, v237
	v_fmac_f32_e32 v99, v230, v238
	v_fmac_f32_e32 v99, v231, v239
	ds_read_b128 v[190:193], v171 offset:9408
	ds_read_b128 v[194:197], v171 offset:9424
	ds_read_b128 v[232:235], v171 offset:9440
	ds_read_b128 v[236:239], v171 offset:9456
	s_waitcnt lgkmcnt(4)
	v_fmac_f32_e32 v104, v200, v174
	v_fmac_f32_e32 v104, v201, v175
	v_fmac_f32_e32 v104, v202, v176
	v_fmac_f32_e32 v104, v203, v177
	v_fmac_f32_e32 v104, v204, v178
	v_fmac_f32_e32 v104, v205, v179
	v_fmac_f32_e32 v104, v206, v180
	v_fmac_f32_e32 v104, v207, v181
	v_fmac_f32_e32 v104, v208, v182
	v_fmac_f32_e32 v104, v209, v183
	v_fmac_f32_e32 v104, v210, v184
	v_fmac_f32_e32 v104, v211, v185
	v_fmac_f32_e32 v104, v212, v186
	v_fmac_f32_e32 v104, v213, v187
	v_fmac_f32_e32 v104, v214, v188
	v_fmac_f32_e32 v104, v215, v189
	ds_read_b128 v[174:177], v171 offset:9856
	ds_read_b128 v[178:181], v171 offset:9872
	ds_read_b128 v[182:185], v171 offset:9888
	ds_read_b128 v[186:189], v171 offset:9904
	s_waitcnt lgkmcnt(4)
	v_fmac_f32_e32 v104, v216, v190
	v_fmac_f32_e32 v104, v217, v191
	v_fmac_f32_e32 v104, v218, v192
	v_fmac_f32_e32 v104, v219, v193
	v_fmac_f32_e32 v104, v220, v194
	v_fmac_f32_e32 v104, v221, v195
	v_fmac_f32_e32 v104, v222, v196
	v_fmac_f32_e32 v104, v223, v197
	v_fmac_f32_e32 v104, v224, v232
	v_fmac_f32_e32 v104, v225, v233
	v_fmac_f32_e32 v104, v226, v234
	v_fmac_f32_e32 v104, v227, v235
	v_fmac_f32_e32 v104, v228, v236
	v_fmac_f32_e32 v104, v229, v237
	v_fmac_f32_e32 v104, v230, v238
	v_fmac_f32_e32 v104, v231, v239
	ds_read_b128 v[190:193], v171 offset:9920
	ds_read_b128 v[194:197], v171 offset:9936
	ds_read_b128 v[232:235], v171 offset:9952
	ds_read_b128 v[236:239], v171 offset:9968
	s_waitcnt lgkmcnt(4)
	v_fmac_f32_e32 v105, v200, v174
	v_fmac_f32_e32 v105, v201, v175
	v_fmac_f32_e32 v105, v202, v176
	v_fmac_f32_e32 v105, v203, v177
	v_fmac_f32_e32 v105, v204, v178
	v_fmac_f32_e32 v105, v205, v179
	v_fmac_f32_e32 v105, v206, v180
	v_fmac_f32_e32 v105, v207, v181
	v_fmac_f32_e32 v105, v208, v182
	v_fmac_f32_e32 v105, v209, v183
	v_fmac_f32_e32 v105, v210, v184
	v_fmac_f32_e32 v105, v211, v185
	v_fmac_f32_e32 v105, v212, v186
	v_fmac_f32_e32 v105, v213, v187
	v_fmac_f32_e32 v105, v214, v188
	v_fmac_f32_e32 v105, v215, v189
	ds_read_b128 v[174:177], v171 offset:10368
	ds_read_b128 v[178:181], v171 offset:10384
	ds_read_b128 v[182:185], v171 offset:10400
	ds_read_b128 v[186:189], v171 offset:10416
	s_waitcnt lgkmcnt(4)
	v_fmac_f32_e32 v105, v216, v190
	v_fmac_f32_e32 v105, v217, v191
	v_fmac_f32_e32 v105, v218, v192
	v_fmac_f32_e32 v105, v219, v193
	v_fmac_f32_e32 v105, v220, v194
	v_fmac_f32_e32 v105, v221, v195
	v_fmac_f32_e32 v105, v222, v196
	v_fmac_f32_e32 v105, v223, v197
	v_fmac_f32_e32 v105, v224, v232
	v_fmac_f32_e32 v105, v225, v233
	v_fmac_f32_e32 v105, v226, v234
	v_fmac_f32_e32 v105, v227, v235
	v_fmac_f32_e32 v105, v228, v236
	v_fmac_f32_e32 v105, v229, v237
	v_fmac_f32_e32 v105, v230, v238
	v_fmac_f32_e32 v105, v231, v239
	ds_read_b128 v[190:193], v171 offset:10432
	ds_read_b128 v[194:197], v171 offset:10448
	ds_read_b128 v[232:235], v171 offset:10464
	ds_read_b128 v[236:239], v171 offset:10480
	s_waitcnt lgkmcnt(4)
	v_fmac_f32_e32 v102, v200, v174
	v_fmac_f32_e32 v102, v201, v175
	v_fmac_f32_e32 v102, v202, v176
	v_fmac_f32_e32 v102, v203, v177
	v_fmac_f32_e32 v102, v204, v178
	v_fmac_f32_e32 v102, v205, v179
	v_fmac_f32_e32 v102, v206, v180
	v_fmac_f32_e32 v102, v207, v181
	v_fmac_f32_e32 v102, v208, v182
	v_fmac_f32_e32 v102, v209, v183
	v_fmac_f32_e32 v102, v210, v184
	v_fmac_f32_e32 v102, v211, v185
	v_fmac_f32_e32 v102, v212, v186
	v_fmac_f32_e32 v102, v213, v187
	v_fmac_f32_e32 v102, v214, v188
	v_fmac_f32_e32 v102, v215, v189
	ds_read_b128 v[174:177], v171 offset:10880
	ds_read_b128 v[178:181], v171 offset:10896
	ds_read_b128 v[182:185], v171 offset:10912
	ds_read_b128 v[186:189], v171 offset:10928
	s_waitcnt lgkmcnt(4)
	v_fmac_f32_e32 v102, v216, v190
	v_fmac_f32_e32 v102, v217, v191
	v_fmac_f32_e32 v102, v218, v192
	v_fmac_f32_e32 v102, v219, v193
	v_fmac_f32_e32 v102, v220, v194
	v_fmac_f32_e32 v102, v221, v195
	v_fmac_f32_e32 v102, v222, v196
	v_fmac_f32_e32 v102, v223, v197
	v_fmac_f32_e32 v102, v224, v232
	v_fmac_f32_e32 v102, v225, v233
	v_fmac_f32_e32 v102, v226, v234
	v_fmac_f32_e32 v102, v227, v235
	v_fmac_f32_e32 v102, v228, v236
	v_fmac_f32_e32 v102, v229, v237
	v_fmac_f32_e32 v102, v230, v238
	v_fmac_f32_e32 v102, v231, v239
	ds_read_b128 v[190:193], v171 offset:10944
	ds_read_b128 v[194:197], v171 offset:10960
	ds_read_b128 v[232:235], v171 offset:10976
	ds_read_b128 v[236:239], v171 offset:10992
	s_waitcnt lgkmcnt(4)
	v_fmac_f32_e32 v103, v200, v174
	v_fmac_f32_e32 v103, v201, v175
	v_fmac_f32_e32 v103, v202, v176
	v_fmac_f32_e32 v103, v203, v177
	v_fmac_f32_e32 v103, v204, v178
	v_fmac_f32_e32 v103, v205, v179
	v_fmac_f32_e32 v103, v206, v180
	v_fmac_f32_e32 v103, v207, v181
	v_fmac_f32_e32 v103, v208, v182
	v_fmac_f32_e32 v103, v209, v183
	v_fmac_f32_e32 v103, v210, v184
	v_fmac_f32_e32 v103, v211, v185
	v_fmac_f32_e32 v103, v212, v186
	v_fmac_f32_e32 v103, v213, v187
	v_fmac_f32_e32 v103, v214, v188
	v_fmac_f32_e32 v103, v215, v189
	ds_read_b128 v[174:177], v171 offset:11392
	ds_read_b128 v[178:181], v171 offset:11408
	ds_read_b128 v[182:185], v171 offset:11424
	ds_read_b128 v[186:189], v171 offset:11440
	s_waitcnt lgkmcnt(4)
	v_fmac_f32_e32 v103, v216, v190
	v_fmac_f32_e32 v103, v217, v191
	v_fmac_f32_e32 v103, v218, v192
	v_fmac_f32_e32 v103, v219, v193
	v_fmac_f32_e32 v103, v220, v194
	v_fmac_f32_e32 v103, v221, v195
	v_fmac_f32_e32 v103, v222, v196
	v_fmac_f32_e32 v103, v223, v197
	v_fmac_f32_e32 v103, v224, v232
	v_fmac_f32_e32 v103, v225, v233
	v_fmac_f32_e32 v103, v226, v234
	v_fmac_f32_e32 v103, v227, v235
	v_fmac_f32_e32 v103, v228, v236
	v_fmac_f32_e32 v103, v229, v237
	v_fmac_f32_e32 v103, v230, v238
	v_fmac_f32_e32 v103, v231, v239
	ds_read_b128 v[190:193], v171 offset:11456
	ds_read_b128 v[194:197], v171 offset:11472
	ds_read_b128 v[232:235], v171 offset:11488
	ds_read_b128 v[236:239], v171 offset:11504
	s_waitcnt lgkmcnt(4)
	v_fmac_f32_e32 v108, v200, v174
	v_fmac_f32_e32 v108, v201, v175
	v_fmac_f32_e32 v108, v202, v176
	v_fmac_f32_e32 v108, v203, v177
	v_fmac_f32_e32 v108, v204, v178
	v_fmac_f32_e32 v108, v205, v179
	v_fmac_f32_e32 v108, v206, v180
	v_fmac_f32_e32 v108, v207, v181
	v_fmac_f32_e32 v108, v208, v182
	v_fmac_f32_e32 v108, v209, v183
	v_fmac_f32_e32 v108, v210, v184
	v_fmac_f32_e32 v108, v211, v185
	v_fmac_f32_e32 v108, v212, v186
	v_fmac_f32_e32 v108, v213, v187
	v_fmac_f32_e32 v108, v214, v188
	v_fmac_f32_e32 v108, v215, v189
	ds_read_b128 v[174:177], v171 offset:11904
	ds_read_b128 v[178:181], v171 offset:11920
	ds_read_b128 v[182:185], v171 offset:11936
	ds_read_b128 v[186:189], v171 offset:11952
	s_waitcnt lgkmcnt(4)
	v_fmac_f32_e32 v108, v216, v190
	v_fmac_f32_e32 v108, v217, v191
	v_fmac_f32_e32 v108, v218, v192
	v_fmac_f32_e32 v108, v219, v193
	v_fmac_f32_e32 v108, v220, v194
	v_fmac_f32_e32 v108, v221, v195
	v_fmac_f32_e32 v108, v222, v196
	v_fmac_f32_e32 v108, v223, v197
	v_fmac_f32_e32 v108, v224, v232
	v_fmac_f32_e32 v108, v225, v233
	v_fmac_f32_e32 v108, v226, v234
	v_fmac_f32_e32 v108, v227, v235
	v_fmac_f32_e32 v108, v228, v236
	v_fmac_f32_e32 v108, v229, v237
	v_fmac_f32_e32 v108, v230, v238
	v_fmac_f32_e32 v108, v231, v239
	ds_read_b128 v[190:193], v171 offset:11968
	ds_read_b128 v[194:197], v171 offset:11984
	ds_read_b128 v[232:235], v171 offset:12000
	ds_read_b128 v[236:239], v171 offset:12016
	s_waitcnt lgkmcnt(4)
	v_fmac_f32_e32 v109, v200, v174
	v_fmac_f32_e32 v109, v201, v175
	v_fmac_f32_e32 v109, v202, v176
	v_fmac_f32_e32 v109, v203, v177
	v_fmac_f32_e32 v109, v204, v178
	v_fmac_f32_e32 v109, v205, v179
	v_fmac_f32_e32 v109, v206, v180
	v_fmac_f32_e32 v109, v207, v181
	v_fmac_f32_e32 v109, v208, v182
	v_fmac_f32_e32 v109, v209, v183
	v_fmac_f32_e32 v109, v210, v184
	v_fmac_f32_e32 v109, v211, v185
	v_fmac_f32_e32 v109, v212, v186
	v_fmac_f32_e32 v109, v213, v187
	v_fmac_f32_e32 v109, v214, v188
	v_fmac_f32_e32 v109, v215, v189
	ds_read_b128 v[174:177], v171 offset:12416
	ds_read_b128 v[178:181], v171 offset:12432
	ds_read_b128 v[182:185], v171 offset:12448
	ds_read_b128 v[186:189], v171 offset:12464
	s_waitcnt lgkmcnt(4)
	v_fmac_f32_e32 v109, v216, v190
	v_fmac_f32_e32 v109, v217, v191
	v_fmac_f32_e32 v109, v218, v192
	v_fmac_f32_e32 v109, v219, v193
	v_fmac_f32_e32 v109, v220, v194
	v_fmac_f32_e32 v109, v221, v195
	v_fmac_f32_e32 v109, v222, v196
	v_fmac_f32_e32 v109, v223, v197
	v_fmac_f32_e32 v109, v224, v232
	v_fmac_f32_e32 v109, v225, v233
	v_fmac_f32_e32 v109, v226, v234
	v_fmac_f32_e32 v109, v227, v235
	v_fmac_f32_e32 v109, v228, v236
	v_fmac_f32_e32 v109, v229, v237
	v_fmac_f32_e32 v109, v230, v238
	v_fmac_f32_e32 v109, v231, v239
	ds_read_b128 v[190:193], v171 offset:12480
	ds_read_b128 v[194:197], v171 offset:12496
	ds_read_b128 v[232:235], v171 offset:12512
	ds_read_b128 v[236:239], v171 offset:12528
	s_waitcnt lgkmcnt(4)
	v_fmac_f32_e32 v106, v200, v174
	v_fmac_f32_e32 v106, v201, v175
	v_fmac_f32_e32 v106, v202, v176
	v_fmac_f32_e32 v106, v203, v177
	v_fmac_f32_e32 v106, v204, v178
	v_fmac_f32_e32 v106, v205, v179
	v_fmac_f32_e32 v106, v206, v180
	v_fmac_f32_e32 v106, v207, v181
	v_fmac_f32_e32 v106, v208, v182
	v_fmac_f32_e32 v106, v209, v183
	v_fmac_f32_e32 v106, v210, v184
	v_fmac_f32_e32 v106, v211, v185
	v_fmac_f32_e32 v106, v212, v186
	v_fmac_f32_e32 v106, v213, v187
	v_fmac_f32_e32 v106, v214, v188
	v_fmac_f32_e32 v106, v215, v189
	ds_read_b128 v[174:177], v171 offset:12928
	ds_read_b128 v[178:181], v171 offset:12944
	ds_read_b128 v[182:185], v171 offset:12960
	ds_read_b128 v[186:189], v171 offset:12976
	s_waitcnt lgkmcnt(4)
	v_fmac_f32_e32 v106, v216, v190
	v_fmac_f32_e32 v106, v217, v191
	v_fmac_f32_e32 v106, v218, v192
	v_fmac_f32_e32 v106, v219, v193
	v_fmac_f32_e32 v106, v220, v194
	v_fmac_f32_e32 v106, v221, v195
	v_fmac_f32_e32 v106, v222, v196
	v_fmac_f32_e32 v106, v223, v197
	v_fmac_f32_e32 v106, v224, v232
	v_fmac_f32_e32 v106, v225, v233
	v_fmac_f32_e32 v106, v226, v234
	v_fmac_f32_e32 v106, v227, v235
	v_fmac_f32_e32 v106, v228, v236
	v_fmac_f32_e32 v106, v229, v237
	v_fmac_f32_e32 v106, v230, v238
	v_fmac_f32_e32 v106, v231, v239
	ds_read_b128 v[190:193], v171 offset:12992
	ds_read_b128 v[194:197], v171 offset:13008
	ds_read_b128 v[232:235], v171 offset:13024
	ds_read_b128 v[236:239], v171 offset:13040
	s_waitcnt lgkmcnt(4)
	v_fmac_f32_e32 v107, v200, v174
	v_fmac_f32_e32 v107, v201, v175
	v_fmac_f32_e32 v107, v202, v176
	v_fmac_f32_e32 v107, v203, v177
	v_fmac_f32_e32 v107, v204, v178
	v_fmac_f32_e32 v107, v205, v179
	v_fmac_f32_e32 v107, v206, v180
	v_fmac_f32_e32 v107, v207, v181
	v_fmac_f32_e32 v107, v208, v182
	v_fmac_f32_e32 v107, v209, v183
	v_fmac_f32_e32 v107, v210, v184
	v_fmac_f32_e32 v107, v211, v185
	v_fmac_f32_e32 v107, v212, v186
	v_fmac_f32_e32 v107, v213, v187
	v_fmac_f32_e32 v107, v214, v188
	v_fmac_f32_e32 v107, v215, v189
	ds_read_b128 v[174:177], v171 offset:13440
	ds_read_b128 v[178:181], v171 offset:13456
	ds_read_b128 v[182:185], v171 offset:13472
	ds_read_b128 v[186:189], v171 offset:13488
	s_waitcnt lgkmcnt(4)
	v_fmac_f32_e32 v107, v216, v190
	v_fmac_f32_e32 v107, v217, v191
	v_fmac_f32_e32 v107, v218, v192
	v_fmac_f32_e32 v107, v219, v193
	v_fmac_f32_e32 v107, v220, v194
	v_fmac_f32_e32 v107, v221, v195
	v_fmac_f32_e32 v107, v222, v196
	v_fmac_f32_e32 v107, v223, v197
	v_fmac_f32_e32 v107, v224, v232
	v_fmac_f32_e32 v107, v225, v233
	v_fmac_f32_e32 v107, v226, v234
	v_fmac_f32_e32 v107, v227, v235
	v_fmac_f32_e32 v107, v228, v236
	v_fmac_f32_e32 v107, v229, v237
	v_fmac_f32_e32 v107, v230, v238
	v_fmac_f32_e32 v107, v231, v239
	ds_read_b128 v[190:193], v171 offset:13504
	ds_read_b128 v[194:197], v171 offset:13520
	ds_read_b128 v[232:235], v171 offset:13536
	ds_read_b128 v[236:239], v171 offset:13552
	s_waitcnt lgkmcnt(4)
	v_fmac_f32_e32 v112, v200, v174
	v_fmac_f32_e32 v112, v201, v175
	v_fmac_f32_e32 v112, v202, v176
	v_fmac_f32_e32 v112, v203, v177
	v_fmac_f32_e32 v112, v204, v178
	v_fmac_f32_e32 v112, v205, v179
	v_fmac_f32_e32 v112, v206, v180
	v_fmac_f32_e32 v112, v207, v181
	v_fmac_f32_e32 v112, v208, v182
	v_fmac_f32_e32 v112, v209, v183
	v_fmac_f32_e32 v112, v210, v184
	v_fmac_f32_e32 v112, v211, v185
	v_fmac_f32_e32 v112, v212, v186
	v_fmac_f32_e32 v112, v213, v187
	v_fmac_f32_e32 v112, v214, v188
	v_fmac_f32_e32 v112, v215, v189
	ds_read_b128 v[174:177], v171 offset:13952
	ds_read_b128 v[178:181], v171 offset:13968
	ds_read_b128 v[182:185], v171 offset:13984
	ds_read_b128 v[186:189], v171 offset:14000
	s_waitcnt lgkmcnt(4)
	v_fmac_f32_e32 v112, v216, v190
	v_fmac_f32_e32 v112, v217, v191
	v_fmac_f32_e32 v112, v218, v192
	v_fmac_f32_e32 v112, v219, v193
	v_fmac_f32_e32 v112, v220, v194
	v_fmac_f32_e32 v112, v221, v195
	v_fmac_f32_e32 v112, v222, v196
	v_fmac_f32_e32 v112, v223, v197
	v_fmac_f32_e32 v112, v224, v232
	v_fmac_f32_e32 v112, v225, v233
	v_fmac_f32_e32 v112, v226, v234
	v_fmac_f32_e32 v112, v227, v235
	v_fmac_f32_e32 v112, v228, v236
	v_fmac_f32_e32 v112, v229, v237
	v_fmac_f32_e32 v112, v230, v238
	v_fmac_f32_e32 v112, v231, v239
	ds_read_b128 v[190:193], v171 offset:14016
	ds_read_b128 v[194:197], v171 offset:14032
	ds_read_b128 v[232:235], v171 offset:14048
	ds_read_b128 v[236:239], v171 offset:14064
	s_waitcnt lgkmcnt(4)
	v_fmac_f32_e32 v113, v200, v174
	v_fmac_f32_e32 v113, v201, v175
	v_fmac_f32_e32 v113, v202, v176
	v_fmac_f32_e32 v113, v203, v177
	v_fmac_f32_e32 v113, v204, v178
	v_fmac_f32_e32 v113, v205, v179
	v_fmac_f32_e32 v113, v206, v180
	v_fmac_f32_e32 v113, v207, v181
	v_fmac_f32_e32 v113, v208, v182
	v_fmac_f32_e32 v113, v209, v183
	v_fmac_f32_e32 v113, v210, v184
	v_fmac_f32_e32 v113, v211, v185
	v_fmac_f32_e32 v113, v212, v186
	v_fmac_f32_e32 v113, v213, v187
	v_fmac_f32_e32 v113, v214, v188
	v_fmac_f32_e32 v113, v215, v189
	ds_read_b128 v[174:177], v171 offset:14464
	ds_read_b128 v[178:181], v171 offset:14480
	ds_read_b128 v[182:185], v171 offset:14496
	ds_read_b128 v[186:189], v171 offset:14512
	s_waitcnt lgkmcnt(4)
	v_fmac_f32_e32 v113, v216, v190
	v_fmac_f32_e32 v113, v217, v191
	v_fmac_f32_e32 v113, v218, v192
	v_fmac_f32_e32 v113, v219, v193
	v_fmac_f32_e32 v113, v220, v194
	v_fmac_f32_e32 v113, v221, v195
	v_fmac_f32_e32 v113, v222, v196
	v_fmac_f32_e32 v113, v223, v197
	v_fmac_f32_e32 v113, v224, v232
	v_fmac_f32_e32 v113, v225, v233
	v_fmac_f32_e32 v113, v226, v234
	v_fmac_f32_e32 v113, v227, v235
	v_fmac_f32_e32 v113, v228, v236
	v_fmac_f32_e32 v113, v229, v237
	v_fmac_f32_e32 v113, v230, v238
	v_fmac_f32_e32 v113, v231, v239
	ds_read_b128 v[190:193], v171 offset:14528
	ds_read_b128 v[194:197], v171 offset:14544
	ds_read_b128 v[232:235], v171 offset:14560
	ds_read_b128 v[236:239], v171 offset:14576
	s_waitcnt lgkmcnt(4)
	v_fmac_f32_e32 v110, v200, v174
	v_fmac_f32_e32 v110, v201, v175
	v_fmac_f32_e32 v110, v202, v176
	v_fmac_f32_e32 v110, v203, v177
	v_fmac_f32_e32 v110, v204, v178
	v_fmac_f32_e32 v110, v205, v179
	v_fmac_f32_e32 v110, v206, v180
	v_fmac_f32_e32 v110, v207, v181
	v_fmac_f32_e32 v110, v208, v182
	v_fmac_f32_e32 v110, v209, v183
	v_fmac_f32_e32 v110, v210, v184
	v_fmac_f32_e32 v110, v211, v185
	v_fmac_f32_e32 v110, v212, v186
	v_fmac_f32_e32 v110, v213, v187
	v_fmac_f32_e32 v110, v214, v188
	v_fmac_f32_e32 v110, v215, v189
	ds_read_b128 v[174:177], v171 offset:14976
	ds_read_b128 v[178:181], v171 offset:14992
	ds_read_b128 v[182:185], v171 offset:15008
	ds_read_b128 v[186:189], v171 offset:15024
	s_waitcnt lgkmcnt(4)
	v_fmac_f32_e32 v110, v216, v190
	v_fmac_f32_e32 v110, v217, v191
	v_fmac_f32_e32 v110, v218, v192
	v_fmac_f32_e32 v110, v219, v193
	v_fmac_f32_e32 v110, v220, v194
	v_fmac_f32_e32 v110, v221, v195
	v_fmac_f32_e32 v110, v222, v196
	v_fmac_f32_e32 v110, v223, v197
	v_fmac_f32_e32 v110, v224, v232
	v_fmac_f32_e32 v110, v225, v233
	v_fmac_f32_e32 v110, v226, v234
	v_fmac_f32_e32 v110, v227, v235
	v_fmac_f32_e32 v110, v228, v236
	v_fmac_f32_e32 v110, v229, v237
	v_fmac_f32_e32 v110, v230, v238
	v_fmac_f32_e32 v110, v231, v239
	ds_read_b128 v[190:193], v171 offset:15040
	ds_read_b128 v[194:197], v171 offset:15056
	ds_read_b128 v[232:235], v171 offset:15072
	ds_read_b128 v[236:239], v171 offset:15088
	s_waitcnt lgkmcnt(4)
	v_fmac_f32_e32 v111, v200, v174
	v_fmac_f32_e32 v111, v201, v175
	v_fmac_f32_e32 v111, v202, v176
	v_fmac_f32_e32 v111, v203, v177
	v_fmac_f32_e32 v111, v204, v178
	v_fmac_f32_e32 v111, v205, v179
	v_fmac_f32_e32 v111, v206, v180
	v_fmac_f32_e32 v111, v207, v181
	v_fmac_f32_e32 v111, v208, v182
	v_fmac_f32_e32 v111, v209, v183
	v_fmac_f32_e32 v111, v210, v184
	v_fmac_f32_e32 v111, v211, v185
	v_fmac_f32_e32 v111, v212, v186
	v_fmac_f32_e32 v111, v213, v187
	v_fmac_f32_e32 v111, v214, v188
	v_fmac_f32_e32 v111, v215, v189
	ds_read_b128 v[174:177], v171 offset:15488
	ds_read_b128 v[178:181], v171 offset:15504
	ds_read_b128 v[182:185], v171 offset:15520
	ds_read_b128 v[186:189], v171 offset:15536
	s_waitcnt lgkmcnt(4)
	v_fmac_f32_e32 v111, v216, v190
	v_fmac_f32_e32 v111, v217, v191
	v_fmac_f32_e32 v111, v218, v192
	v_fmac_f32_e32 v111, v219, v193
	v_fmac_f32_e32 v111, v220, v194
	v_fmac_f32_e32 v111, v221, v195
	v_fmac_f32_e32 v111, v222, v196
	v_fmac_f32_e32 v111, v223, v197
	v_fmac_f32_e32 v111, v224, v232
	v_fmac_f32_e32 v111, v225, v233
	v_fmac_f32_e32 v111, v226, v234
	v_fmac_f32_e32 v111, v227, v235
	v_fmac_f32_e32 v111, v228, v236
	v_fmac_f32_e32 v111, v229, v237
	v_fmac_f32_e32 v111, v230, v238
	v_fmac_f32_e32 v111, v231, v239
	ds_read_b128 v[190:193], v171 offset:15552
	ds_read_b128 v[194:197], v171 offset:15568
	ds_read_b128 v[232:235], v171 offset:15584
	ds_read_b128 v[236:239], v171 offset:15600
	s_waitcnt lgkmcnt(4)
	v_fmac_f32_e32 v40, v200, v174
	v_fmac_f32_e32 v40, v201, v175
	v_fmac_f32_e32 v40, v202, v176
	v_fmac_f32_e32 v40, v203, v177
	v_fmac_f32_e32 v40, v204, v178
	v_fmac_f32_e32 v40, v205, v179
	v_fmac_f32_e32 v40, v206, v180
	v_fmac_f32_e32 v40, v207, v181
	v_fmac_f32_e32 v40, v208, v182
	v_fmac_f32_e32 v40, v209, v183
	v_fmac_f32_e32 v40, v210, v184
	v_fmac_f32_e32 v40, v211, v185
	v_fmac_f32_e32 v40, v212, v186
	v_fmac_f32_e32 v40, v213, v187
	v_fmac_f32_e32 v40, v214, v188
	v_fmac_f32_e32 v40, v215, v189
	ds_read_b128 v[174:177], v171 offset:16000
	ds_read_b128 v[178:181], v171 offset:16016
	ds_read_b128 v[182:185], v171 offset:16032
	ds_read_b128 v[186:189], v171 offset:16048
	s_waitcnt lgkmcnt(4)
	v_fmac_f32_e32 v40, v216, v190
	v_fmac_f32_e32 v40, v217, v191
	v_fmac_f32_e32 v40, v218, v192
	v_fmac_f32_e32 v40, v219, v193
	v_fmac_f32_e32 v40, v220, v194
	v_fmac_f32_e32 v40, v221, v195
	v_fmac_f32_e32 v40, v222, v196
	v_fmac_f32_e32 v40, v223, v197
	v_fmac_f32_e32 v40, v224, v232
	v_fmac_f32_e32 v40, v225, v233
	v_fmac_f32_e32 v40, v226, v234
	v_fmac_f32_e32 v40, v227, v235
	v_fmac_f32_e32 v40, v228, v236
	v_fmac_f32_e32 v40, v229, v237
	v_fmac_f32_e32 v40, v230, v238
	v_fmac_f32_e32 v40, v231, v239
	ds_read_b128 v[190:193], v171 offset:16064
	ds_read_b128 v[194:197], v171 offset:16080
	ds_read_b128 v[232:235], v171 offset:16096
	ds_read_b128 v[236:239], v171 offset:16112
	s_waitcnt lgkmcnt(4)
	v_fmac_f32_e32 v41, v200, v174
	v_fmac_f32_e32 v41, v201, v175
	v_fmac_f32_e32 v41, v202, v176
	v_fmac_f32_e32 v41, v203, v177
	v_fmac_f32_e32 v41, v204, v178
	v_fmac_f32_e32 v41, v205, v179
	v_fmac_f32_e32 v41, v206, v180
	v_fmac_f32_e32 v41, v207, v181
	v_fmac_f32_e32 v41, v208, v182
	v_fmac_f32_e32 v41, v209, v183
	v_fmac_f32_e32 v41, v210, v184
	v_fmac_f32_e32 v41, v211, v185
	v_fmac_f32_e32 v41, v212, v186
	v_fmac_f32_e32 v41, v213, v187
	v_fmac_f32_e32 v41, v214, v188
	v_fmac_f32_e32 v41, v215, v189
	s_waitcnt lgkmcnt(0)
	v_fmac_f32_e32 v41, v216, v190
	v_fmac_f32_e32 v41, v217, v191
	v_fmac_f32_e32 v41, v218, v192
	v_fmac_f32_e32 v41, v219, v193
	v_fmac_f32_e32 v41, v220, v194
	v_fmac_f32_e32 v41, v221, v195
	v_fmac_f32_e32 v41, v222, v196
	v_fmac_f32_e32 v41, v223, v197
	v_fmac_f32_e32 v41, v224, v232
	v_fmac_f32_e32 v41, v225, v233
	v_fmac_f32_e32 v41, v226, v234
	v_fmac_f32_e32 v41, v227, v235
	v_fmac_f32_e32 v41, v228, v236
	v_fmac_f32_e32 v41, v229, v237
	v_fmac_f32_e32 v41, v230, v238
	v_fmac_f32_e32 v41, v231, v239
	s_movk_i32 s0, 0x100
	s_mov_b32 s1, 0
	s_waitcnt lgkmcnt(0)
	v_add_u32_e32 v27, 0x400, v114
	ds_write2_b32 v114, v82, v83 offset1:66
	ds_write2_b32 v114, v86, v87 offset0:132 offset1:198
	ds_write2_b32 v27, v84, v85 offset0:8 offset1:74
	ds_write2_b32 v27, v90, v91 offset0:140 offset1:206
	v_add_u32_e32 v27, 0x800, v114
	ds_write2_b32 v27, v88, v89 offset0:16 offset1:82
	ds_write2_b32 v27, v94, v95 offset0:148 offset1:214
	v_add_u32_e32 v27, 0xc00, v114
	ds_write2_b32 v27, v92, v93 offset0:24 offset1:90
	ds_write2_b32 v27, v100, v101 offset0:156 offset1:222
	v_add_u32_e32 v27, 0x1000, v114
	ds_write2_b32 v27, v98, v99 offset0:32 offset1:98
	ds_write2_b32 v27, v104, v105 offset0:164 offset1:230
	v_add_u32_e32 v27, 0x1400, v114
	ds_write2_b32 v27, v102, v103 offset0:40 offset1:106
	ds_write2_b32 v27, v108, v109 offset0:172 offset1:238
	v_add_u32_e32 v27, 0x1800, v114
	ds_write2_b32 v27, v106, v107 offset0:48 offset1:114
	ds_write2_b32 v27, v112, v113 offset0:180 offset1:246
	v_add_u32_e32 v27, 0x1c00, v114
	ds_write2_b32 v27, v110, v111 offset0:56 offset1:122
	ds_write2_b32 v27, v40, v41 offset0:188 offset1:254
	s_waitcnt lgkmcnt(0)
	s_add_i32 s0, s78, 0xffffd000
	ds_read2_b32 v[28:29], v116 offset1:33
	s_lshl_b32 s1, s0, 5
	s_waitcnt lgkmcnt(0)
	v_cvt_pk_bf16_f32 v28, v28, v29
	ds_read2_b32 v[30:31], v116 offset0:66 offset1:99
	s_and_b32 s1, s1, 0x3e0
	s_waitcnt lgkmcnt(0)
	v_cvt_pk_bf16_f32 v29, v30, v31
	ds_read2_b32 v[30:31], v116 offset0:132 offset1:165
	v_or_b32_e32 v27, s1, v115
	s_waitcnt lgkmcnt(0)
	v_cvt_pk_bf16_f32 v30, v30, v31
	ds_read2_b32 v[32:33], v116 offset0:198 offset1:231
	v_lshlrev_b32_e32 v96, 11, v27
	s_lshl_b32 s0, s0, 2
	s_waitcnt lgkmcnt(0)
	v_cvt_pk_bf16_f32 v31, v32, v33
	v_lshl_add_u64 v[32:33], s[6:7], 0, v[96:97]
	s_and_b32 s16, s0, 0x180
	v_lshl_add_u64 v[32:33], v[32:33], 0, s[16:17]
	v_mov_b32_e32 v27, v97
	v_lshl_add_u64 v[32:33], v[32:33], 0, v[26:27]
	ds_read2_b32 v[34:35], v116 offset0:8 offset1:41
	global_store_dwordx4 v[32:33], v[28:31], off offset:1024
	s_waitcnt lgkmcnt(0)
	s_nop 0
	v_cvt_pk_bf16_f32 v28, v34, v35
	ds_read2_b32 v[30:31], v116 offset0:74 offset1:107
	s_waitcnt lgkmcnt(0)
	v_cvt_pk_bf16_f32 v29, v30, v31
	ds_read2_b32 v[30:31], v116 offset0:140 offset1:173
	s_waitcnt lgkmcnt(0)
	v_cvt_pk_bf16_f32 v30, v30, v31
	ds_read2_b32 v[32:33], v116 offset0:206 offset1:239
	s_waitcnt lgkmcnt(0)
	v_cvt_pk_bf16_f32 v31, v32, v33
	v_or_b32_e32 v32, s1, v117
	v_lshlrev_b32_e32 v96, 11, v32
	v_lshl_add_u64 v[34:35], s[6:7], 0, v[96:97]
	v_lshl_add_u64 v[34:35], v[34:35], 0, s[16:17]
	v_lshl_add_u64 v[34:35], v[34:35], 0, v[26:27]
	ds_read2_b32 v[32:33], v116 offset0:16 offset1:49
	global_store_dwordx4 v[34:35], v[28:31], off offset:1024
	s_waitcnt lgkmcnt(0)
	s_nop 0
	v_cvt_pk_bf16_f32 v28, v32, v33
	ds_read2_b32 v[30:31], v116 offset0:82 offset1:115
	s_waitcnt lgkmcnt(0)
	v_cvt_pk_bf16_f32 v29, v30, v31
	ds_read2_b32 v[30:31], v116 offset0:148 offset1:181
	s_waitcnt lgkmcnt(0)
	v_cvt_pk_bf16_f32 v30, v30, v31
	ds_read2_b32 v[32:33], v116 offset0:214 offset1:247
	s_waitcnt lgkmcnt(0)
	v_cvt_pk_bf16_f32 v31, v32, v33
	v_or_b32_e32 v32, s1, v118
	v_lshlrev_b32_e32 v96, 11, v32
	v_lshl_add_u64 v[34:35], s[6:7], 0, v[96:97]
	v_lshl_add_u64 v[34:35], v[34:35], 0, s[16:17]
	v_lshl_add_u64 v[34:35], v[34:35], 0, v[26:27]
	ds_read2_b32 v[32:33], v116 offset0:24 offset1:57
	global_store_dwordx4 v[34:35], v[28:31], off offset:1024
	s_waitcnt lgkmcnt(0)
	s_nop 0
	v_cvt_pk_bf16_f32 v28, v32, v33
	ds_read2_b32 v[30:31], v116 offset0:90 offset1:123
	s_waitcnt lgkmcnt(0)
	v_cvt_pk_bf16_f32 v29, v30, v31
	ds_read2_b32 v[30:31], v116 offset0:156 offset1:189
	s_waitcnt lgkmcnt(0)
	v_cvt_pk_bf16_f32 v30, v30, v31
	v_or_b32_e32 v31, s1, v119
	v_lshlrev_b32_e32 v96, 11, v31
	v_lshl_add_u64 v[34:35], s[6:7], 0, v[96:97]
	ds_read2_b32 v[32:33], v116 offset0:222 offset1:255
	v_lshl_add_u64 v[34:35], v[34:35], 0, s[16:17]
	s_waitcnt lgkmcnt(0)
	v_cvt_pk_bf16_f32 v31, v32, v33
	v_lshl_add_u64 v[32:33], v[34:35], 0, v[26:27]
	global_store_dwordx4 v[32:33], v[28:31], off offset:1024
	s_waitcnt lgkmcnt(0)
	s_mov_b64 s[0:1], 0

.LBB0_1050:
	v_readlane_b32 s14, v255, 15
	v_lshlrev_b32_e32 v170, 4, v246
	v_lshrrev_b32_e32 v171, 5, v246
	v_lshlrev_b32_e32 v171, 8, v171
	s_mov_b32 m0, s14
	v_add_u32_e32 v171, s14, v171
	v_readfirstlane_b32 s14, v28
	v_readfirstlane_b32 s15, v29
	s_nop 4
	global_load_lds_dwordx4 v170, s[14:15]
	s_add_i32 m0, m0, 0x400
	v_add_u32_e32 v170, 0x400, v170
	global_load_lds_dwordx4 v170, s[14:15]
	s_add_i32 m0, m0, 0x400
	v_add_u32_e32 v170, 0x400, v170
	global_load_lds_dwordx4 v170, s[14:15]
	s_add_i32 m0, m0, 0x400
	v_add_u32_e32 v170, 0x400, v170
	global_load_lds_dwordx4 v170, s[14:15]
	s_add_i32 m0, m0, 0x400
	v_add_u32_e32 v170, 0x400, v170
	global_load_lds_dwordx4 v170, s[14:15]
	s_add_i32 m0, m0, 0x400
	v_add_u32_e32 v170, 0x400, v170
	global_load_lds_dwordx4 v170, s[14:15]
	s_add_i32 m0, m0, 0x400
	v_add_u32_e32 v170, 0x400, v170
	global_load_lds_dwordx4 v170, s[14:15]
	s_add_i32 m0, m0, 0x400
	v_add_u32_e32 v170, 0x400, v170
	global_load_lds_dwordx4 v170, s[14:15]
	s_add_i32 m0, m0, 0x400
	v_add_u32_e32 v170, 0x400, v170
	global_load_lds_dwordx4 v170, s[14:15]
	s_add_i32 m0, m0, 0x400
	v_add_u32_e32 v170, 0x400, v170
	global_load_lds_dwordx4 v170, s[14:15]
	s_add_i32 m0, m0, 0x400
	v_add_u32_e32 v170, 0x400, v170
	global_load_lds_dwordx4 v170, s[14:15]
	s_add_i32 m0, m0, 0x400
	v_add_u32_e32 v170, 0x400, v170
	global_load_lds_dwordx4 v170, s[14:15]
	s_add_i32 m0, m0, 0x400
	v_add_u32_e32 v170, 0x400, v170
	global_load_lds_dwordx4 v170, s[14:15]
	s_add_i32 m0, m0, 0x400
	v_add_u32_e32 v170, 0x400, v170
	global_load_lds_dwordx4 v170, s[14:15]
	s_add_i32 m0, m0, 0x400
	v_add_u32_e32 v170, 0x400, v170
	global_load_lds_dwordx4 v170, s[14:15]
	s_add_i32 m0, m0, 0x400
	v_add_u32_e32 v170, 0x400, v170
	global_load_lds_dwordx4 v170, s[14:15]
	s_mov_b32 s14, s6
	s_mov_b32 s15, s7
	global_load_dword v200, v[80:81], off
	v_lshl_add_u64 v[80:81], v[80:81], 0, s[58:59]
	global_load_dword v174, v97, s[14:15] offset:0
	global_load_dword v201, v[80:81], off
	v_lshl_add_u64 v[80:81], v[80:81], 0, s[58:59]
	global_load_dword v175, v97, s[14:15] offset:4
	global_load_dword v202, v[80:81], off
	v_lshl_add_u64 v[80:81], v[80:81], 0, s[58:59]
	global_load_dword v176, v97, s[14:15] offset:8
	global_load_dword v203, v[80:81], off
	v_lshl_add_u64 v[80:81], v[80:81], 0, s[58:59]
	global_load_dword v177, v97, s[14:15] offset:12
	global_load_dword v204, v[80:81], off
	v_lshl_add_u64 v[80:81], v[80:81], 0, s[58:59]
	global_load_dword v178, v97, s[14:15] offset:16
	global_load_dword v205, v[80:81], off
	v_lshl_add_u64 v[80:81], v[80:81], 0, s[58:59]
	global_load_dword v179, v97, s[14:15] offset:20
	global_load_dword v206, v[80:81], off
	v_lshl_add_u64 v[80:81], v[80:81], 0, s[58:59]
	global_load_dword v180, v97, s[14:15] offset:24
	global_load_dword v207, v[80:81], off
	v_lshl_add_u64 v[80:81], v[80:81], 0, s[58:59]
	global_load_dword v181, v97, s[14:15] offset:28
	global_load_dword v208, v[80:81], off
	v_lshl_add_u64 v[80:81], v[80:81], 0, s[58:59]
	global_load_dword v182, v97, s[14:15] offset:32
	global_load_dword v209, v[80:81], off
	v_lshl_add_u64 v[80:81], v[80:81], 0, s[58:59]
	global_load_dword v183, v97, s[14:15] offset:36
	global_load_dword v210, v[80:81], off
	v_lshl_add_u64 v[80:81], v[80:81], 0, s[58:59]
	global_load_dword v184, v97, s[14:15] offset:40
	global_load_dword v211, v[80:81], off
	v_lshl_add_u64 v[80:81], v[80:81], 0, s[58:59]
	global_load_dword v185, v97, s[14:15] offset:44
	global_load_dword v212, v[80:81], off
	v_lshl_add_u64 v[80:81], v[80:81], 0, s[58:59]
	global_load_dword v186, v97, s[14:15] offset:48
	global_load_dword v213, v[80:81], off
	v_lshl_add_u64 v[80:81], v[80:81], 0, s[58:59]
	global_load_dword v187, v97, s[14:15] offset:52
	global_load_dword v214, v[80:81], off
	v_lshl_add_u64 v[80:81], v[80:81], 0, s[58:59]
	global_load_dword v188, v97, s[14:15] offset:56
	global_load_dword v215, v[80:81], off
	v_lshl_add_u64 v[80:81], v[80:81], 0, s[58:59]
	global_load_dword v189, v97, s[14:15] offset:60
	s_waitcnt vmcnt(30)
	global_load_dword v216, v[80:81], off
	v_lshl_add_u64 v[80:81], v[80:81], 0, s[58:59]
	global_load_dword v190, v97, s[14:15] offset:64
	global_load_dword v217, v[80:81], off
	v_lshl_add_u64 v[80:81], v[80:81], 0, s[58:59]
	global_load_dword v191, v97, s[14:15] offset:68
	global_load_dword v218, v[80:81], off
	v_lshl_add_u64 v[80:81], v[80:81], 0, s[58:59]
	global_load_dword v192, v97, s[14:15] offset:72
	global_load_dword v219, v[80:81], off
	v_lshl_add_u64 v[80:81], v[80:81], 0, s[58:59]
	global_load_dword v193, v97, s[14:15] offset:76
	global_load_dword v220, v[80:81], off
	v_lshl_add_u64 v[80:81], v[80:81], 0, s[58:59]
	global_load_dword v194, v97, s[14:15] offset:80
	global_load_dword v221, v[80:81], off
	v_lshl_add_u64 v[80:81], v[80:81], 0, s[58:59]
	global_load_dword v195, v97, s[14:15] offset:84
	global_load_dword v222, v[80:81], off
	v_lshl_add_u64 v[80:81], v[80:81], 0, s[58:59]
	global_load_dword v196, v97, s[14:15] offset:88
	global_load_dword v223, v[80:81], off
	v_lshl_add_u64 v[80:81], v[80:81], 0, s[58:59]
	global_load_dword v197, v97, s[14:15] offset:92
	global_load_dword v224, v[80:81], off
	v_lshl_add_u64 v[80:81], v[80:81], 0, s[58:59]
	global_load_dword v232, v97, s[14:15] offset:96
	global_load_dword v225, v[80:81], off
	v_lshl_add_u64 v[80:81], v[80:81], 0, s[58:59]
	global_load_dword v233, v97, s[14:15] offset:100
	global_load_dword v226, v[80:81], off
	v_lshl_add_u64 v[80:81], v[80:81], 0, s[58:59]
	global_load_dword v234, v97, s[14:15] offset:104
	global_load_dword v227, v[80:81], off
	v_lshl_add_u64 v[80:81], v[80:81], 0, s[58:59]
	global_load_dword v235, v97, s[14:15] offset:108
	global_load_dword v228, v[80:81], off
	v_lshl_add_u64 v[80:81], v[80:81], 0, s[58:59]
	global_load_dword v236, v97, s[14:15] offset:112
	global_load_dword v229, v[80:81], off
	v_lshl_add_u64 v[80:81], v[80:81], 0, s[58:59]
	global_load_dword v237, v97, s[14:15] offset:116
	global_load_dword v230, v[80:81], off
	v_lshl_add_u64 v[80:81], v[80:81], 0, s[58:59]
	global_load_dword v238, v97, s[14:15] offset:120
	global_load_dword v231, v[80:81], off
	v_lshl_add_u64 v[80:81], v[80:81], 0, s[58:59]
	global_load_dword v239, v97, s[14:15] offset:124
	s_waitcnt vmcnt(0)
	v_mul_f32_e32 v200, v200, v174
	v_mul_f32_e32 v201, v201, v175
	v_mul_f32_e32 v202, v202, v176
	v_mul_f32_e32 v203, v203, v177
	v_mul_f32_e32 v204, v204, v178
	v_mul_f32_e32 v205, v205, v179
	v_mul_f32_e32 v206, v206, v180
	v_mul_f32_e32 v207, v207, v181
	v_mul_f32_e32 v208, v208, v182
	v_mul_f32_e32 v209, v209, v183
	v_mul_f32_e32 v210, v210, v184
	v_mul_f32_e32 v211, v211, v185
	v_mul_f32_e32 v212, v212, v186
	v_mul_f32_e32 v213, v213, v187
	v_mul_f32_e32 v214, v214, v188
	v_mul_f32_e32 v215, v215, v189
	v_mul_f32_e32 v216, v216, v190
	v_mul_f32_e32 v217, v217, v191
	v_mul_f32_e32 v218, v218, v192
	v_mul_f32_e32 v219, v219, v193
	v_mul_f32_e32 v220, v220, v194
	v_mul_f32_e32 v221, v221, v195
	v_mul_f32_e32 v222, v222, v196
	v_mul_f32_e32 v223, v223, v197
	v_mul_f32_e32 v224, v224, v232
	v_mul_f32_e32 v225, v225, v233
	v_mul_f32_e32 v226, v226, v234
	v_mul_f32_e32 v227, v227, v235
	v_mul_f32_e32 v228, v228, v236
	v_mul_f32_e32 v229, v229, v237
	v_mul_f32_e32 v230, v230, v238
	v_mul_f32_e32 v231, v231, v239
	ds_read_b128 v[174:177], v171 offset:0
	ds_read_b128 v[178:181], v171 offset:16
	ds_read_b128 v[182:185], v171 offset:32
	ds_read_b128 v[186:189], v171 offset:48
	ds_read_b128 v[190:193], v171 offset:64
	ds_read_b128 v[194:197], v171 offset:80
	ds_read_b128 v[232:235], v171 offset:96
	ds_read_b128 v[236:239], v171 offset:112
	s_waitcnt lgkmcnt(4)
	v_fmac_f32_e32 v82, v200, v174
	v_fmac_f32_e32 v82, v201, v175
	v_fmac_f32_e32 v82, v202, v176
	v_fmac_f32_e32 v82, v203, v177
	v_fmac_f32_e32 v82, v204, v178
	v_fmac_f32_e32 v82, v205, v179
	v_fmac_f32_e32 v82, v206, v180
	v_fmac_f32_e32 v82, v207, v181
	v_fmac_f32_e32 v82, v208, v182
	v_fmac_f32_e32 v82, v209, v183
	v_fmac_f32_e32 v82, v210, v184
	v_fmac_f32_e32 v82, v211, v185
	v_fmac_f32_e32 v82, v212, v186
	v_fmac_f32_e32 v82, v213, v187
	v_fmac_f32_e32 v82, v214, v188
	v_fmac_f32_e32 v82, v215, v189
	ds_read_b128 v[174:177], v171 offset:512
	ds_read_b128 v[178:181], v171 offset:528
	ds_read_b128 v[182:185], v171 offset:544
	ds_read_b128 v[186:189], v171 offset:560
	s_waitcnt lgkmcnt(4)
	v_fmac_f32_e32 v82, v216, v190
	v_fmac_f32_e32 v82, v217, v191
	v_fmac_f32_e32 v82, v218, v192
	v_fmac_f32_e32 v82, v219, v193
	v_fmac_f32_e32 v82, v220, v194
	v_fmac_f32_e32 v82, v221, v195
	v_fmac_f32_e32 v82, v222, v196
	v_fmac_f32_e32 v82, v223, v197
	v_fmac_f32_e32 v82, v224, v232
	v_fmac_f32_e32 v82, v225, v233
	v_fmac_f32_e32 v82, v226, v234
	v_fmac_f32_e32 v82, v227, v235
	v_fmac_f32_e32 v82, v228, v236
	v_fmac_f32_e32 v82, v229, v237
	v_fmac_f32_e32 v82, v230, v238
	v_fmac_f32_e32 v82, v231, v239
	ds_read_b128 v[190:193], v171 offset:576
	ds_read_b128 v[194:197], v171 offset:592
	ds_read_b128 v[232:235], v171 offset:608
	ds_read_b128 v[236:239], v171 offset:624
	s_waitcnt lgkmcnt(4)
	v_fmac_f32_e32 v83, v200, v174
	v_fmac_f32_e32 v83, v201, v175
	v_fmac_f32_e32 v83, v202, v176
	v_fmac_f32_e32 v83, v203, v177
	v_fmac_f32_e32 v83, v204, v178
	v_fmac_f32_e32 v83, v205, v179
	v_fmac_f32_e32 v83, v206, v180
	v_fmac_f32_e32 v83, v207, v181
	v_fmac_f32_e32 v83, v208, v182
	v_fmac_f32_e32 v83, v209, v183
	v_fmac_f32_e32 v83, v210, v184
	v_fmac_f32_e32 v83, v211, v185
	v_fmac_f32_e32 v83, v212, v186
	v_fmac_f32_e32 v83, v213, v187
	v_fmac_f32_e32 v83, v214, v188
	v_fmac_f32_e32 v83, v215, v189
	ds_read_b128 v[174:177], v171 offset:1024
	ds_read_b128 v[178:181], v171 offset:1040
	ds_read_b128 v[182:185], v171 offset:1056
	ds_read_b128 v[186:189], v171 offset:1072
	s_waitcnt lgkmcnt(4)
	v_fmac_f32_e32 v83, v216, v190
	v_fmac_f32_e32 v83, v217, v191
	v_fmac_f32_e32 v83, v218, v192
	v_fmac_f32_e32 v83, v219, v193
	v_fmac_f32_e32 v83, v220, v194
	v_fmac_f32_e32 v83, v221, v195
	v_fmac_f32_e32 v83, v222, v196
	v_fmac_f32_e32 v83, v223, v197
	v_fmac_f32_e32 v83, v224, v232
	v_fmac_f32_e32 v83, v225, v233
	v_fmac_f32_e32 v83, v226, v234
	v_fmac_f32_e32 v83, v227, v235
	v_fmac_f32_e32 v83, v228, v236
	v_fmac_f32_e32 v83, v229, v237
	v_fmac_f32_e32 v83, v230, v238
	v_fmac_f32_e32 v83, v231, v239
	ds_read_b128 v[190:193], v171 offset:1088
	ds_read_b128 v[194:197], v171 offset:1104
	ds_read_b128 v[232:235], v171 offset:1120
	ds_read_b128 v[236:239], v171 offset:1136
	s_waitcnt lgkmcnt(4)
	v_fmac_f32_e32 v86, v200, v174
	v_fmac_f32_e32 v86, v201, v175
	v_fmac_f32_e32 v86, v202, v176
	v_fmac_f32_e32 v86, v203, v177
	v_fmac_f32_e32 v86, v204, v178
	v_fmac_f32_e32 v86, v205, v179
	v_fmac_f32_e32 v86, v206, v180
	v_fmac_f32_e32 v86, v207, v181
	v_fmac_f32_e32 v86, v208, v182
	v_fmac_f32_e32 v86, v209, v183
	v_fmac_f32_e32 v86, v210, v184
	v_fmac_f32_e32 v86, v211, v185
	v_fmac_f32_e32 v86, v212, v186
	v_fmac_f32_e32 v86, v213, v187
	v_fmac_f32_e32 v86, v214, v188
	v_fmac_f32_e32 v86, v215, v189
	ds_read_b128 v[174:177], v171 offset:1536
	ds_read_b128 v[178:181], v171 offset:1552
	ds_read_b128 v[182:185], v171 offset:1568
	ds_read_b128 v[186:189], v171 offset:1584
	s_waitcnt lgkmcnt(4)
	v_fmac_f32_e32 v86, v216, v190
	v_fmac_f32_e32 v86, v217, v191
	v_fmac_f32_e32 v86, v218, v192
	v_fmac_f32_e32 v86, v219, v193
	v_fmac_f32_e32 v86, v220, v194
	v_fmac_f32_e32 v86, v221, v195
	v_fmac_f32_e32 v86, v222, v196
	v_fmac_f32_e32 v86, v223, v197
	v_fmac_f32_e32 v86, v224, v232
	v_fmac_f32_e32 v86, v225, v233
	v_fmac_f32_e32 v86, v226, v234
	v_fmac_f32_e32 v86, v227, v235
	v_fmac_f32_e32 v86, v228, v236
	v_fmac_f32_e32 v86, v229, v237
	v_fmac_f32_e32 v86, v230, v238
	v_fmac_f32_e32 v86, v231, v239
	ds_read_b128 v[190:193], v171 offset:1600
	ds_read_b128 v[194:197], v171 offset:1616
	ds_read_b128 v[232:235], v171 offset:1632
	ds_read_b128 v[236:239], v171 offset:1648
	s_waitcnt lgkmcnt(4)
	v_fmac_f32_e32 v87, v200, v174
	v_fmac_f32_e32 v87, v201, v175
	v_fmac_f32_e32 v87, v202, v176
	v_fmac_f32_e32 v87, v203, v177
	v_fmac_f32_e32 v87, v204, v178
	v_fmac_f32_e32 v87, v205, v179
	v_fmac_f32_e32 v87, v206, v180
	v_fmac_f32_e32 v87, v207, v181
	v_fmac_f32_e32 v87, v208, v182
	v_fmac_f32_e32 v87, v209, v183
	v_fmac_f32_e32 v87, v210, v184
	v_fmac_f32_e32 v87, v211, v185
	v_fmac_f32_e32 v87, v212, v186
	v_fmac_f32_e32 v87, v213, v187
	v_fmac_f32_e32 v87, v214, v188
	v_fmac_f32_e32 v87, v215, v189
	ds_read_b128 v[174:177], v171 offset:2048
	ds_read_b128 v[178:181], v171 offset:2064
	ds_read_b128 v[182:185], v171 offset:2080
	ds_read_b128 v[186:189], v171 offset:2096
	s_waitcnt lgkmcnt(4)
	v_fmac_f32_e32 v87, v216, v190
	v_fmac_f32_e32 v87, v217, v191
	v_fmac_f32_e32 v87, v218, v192
	v_fmac_f32_e32 v87, v219, v193
	v_fmac_f32_e32 v87, v220, v194
	v_fmac_f32_e32 v87, v221, v195
	v_fmac_f32_e32 v87, v222, v196
	v_fmac_f32_e32 v87, v223, v197
	v_fmac_f32_e32 v87, v224, v232
	v_fmac_f32_e32 v87, v225, v233
	v_fmac_f32_e32 v87, v226, v234
	v_fmac_f32_e32 v87, v227, v235
	v_fmac_f32_e32 v87, v228, v236
	v_fmac_f32_e32 v87, v229, v237
	v_fmac_f32_e32 v87, v230, v238
	v_fmac_f32_e32 v87, v231, v239
	ds_read_b128 v[190:193], v171 offset:2112
	ds_read_b128 v[194:197], v171 offset:2128
	ds_read_b128 v[232:235], v171 offset:2144
	ds_read_b128 v[236:239], v171 offset:2160
	s_waitcnt lgkmcnt(4)
	v_fmac_f32_e32 v84, v200, v174
	v_fmac_f32_e32 v84, v201, v175
	v_fmac_f32_e32 v84, v202, v176
	v_fmac_f32_e32 v84, v203, v177
	v_fmac_f32_e32 v84, v204, v178
	v_fmac_f32_e32 v84, v205, v179
	v_fmac_f32_e32 v84, v206, v180
	v_fmac_f32_e32 v84, v207, v181
	v_fmac_f32_e32 v84, v208, v182
	v_fmac_f32_e32 v84, v209, v183
	v_fmac_f32_e32 v84, v210, v184
	v_fmac_f32_e32 v84, v211, v185
	v_fmac_f32_e32 v84, v212, v186
	v_fmac_f32_e32 v84, v213, v187
	v_fmac_f32_e32 v84, v214, v188
	v_fmac_f32_e32 v84, v215, v189
	ds_read_b128 v[174:177], v171 offset:2560
	ds_read_b128 v[178:181], v171 offset:2576
	ds_read_b128 v[182:185], v171 offset:2592
	ds_read_b128 v[186:189], v171 offset:2608
	s_waitcnt lgkmcnt(4)
	v_fmac_f32_e32 v84, v216, v190
	v_fmac_f32_e32 v84, v217, v191
	v_fmac_f32_e32 v84, v218, v192
	v_fmac_f32_e32 v84, v219, v193
	v_fmac_f32_e32 v84, v220, v194
	v_fmac_f32_e32 v84, v221, v195
	v_fmac_f32_e32 v84, v222, v196
	v_fmac_f32_e32 v84, v223, v197
	v_fmac_f32_e32 v84, v224, v232
	v_fmac_f32_e32 v84, v225, v233
	v_fmac_f32_e32 v84, v226, v234
	v_fmac_f32_e32 v84, v227, v235
	v_fmac_f32_e32 v84, v228, v236
	v_fmac_f32_e32 v84, v229, v237
	v_fmac_f32_e32 v84, v230, v238
	v_fmac_f32_e32 v84, v231, v239
	ds_read_b128 v[190:193], v171 offset:2624
	ds_read_b128 v[194:197], v171 offset:2640
	ds_read_b128 v[232:235], v171 offset:2656
	ds_read_b128 v[236:239], v171 offset:2672
	s_waitcnt lgkmcnt(4)
	v_fmac_f32_e32 v85, v200, v174
	v_fmac_f32_e32 v85, v201, v175
	v_fmac_f32_e32 v85, v202, v176
	v_fmac_f32_e32 v85, v203, v177
	v_fmac_f32_e32 v85, v204, v178
	v_fmac_f32_e32 v85, v205, v179
	v_fmac_f32_e32 v85, v206, v180
	v_fmac_f32_e32 v85, v207, v181
	v_fmac_f32_e32 v85, v208, v182
	v_fmac_f32_e32 v85, v209, v183
	v_fmac_f32_e32 v85, v210, v184
	v_fmac_f32_e32 v85, v211, v185
	v_fmac_f32_e32 v85, v212, v186
	v_fmac_f32_e32 v85, v213, v187
	v_fmac_f32_e32 v85, v214, v188
	v_fmac_f32_e32 v85, v215, v189
	ds_read_b128 v[174:177], v171 offset:3072
	ds_read_b128 v[178:181], v171 offset:3088
	ds_read_b128 v[182:185], v171 offset:3104
	ds_read_b128 v[186:189], v171 offset:3120
	s_waitcnt lgkmcnt(4)
	v_fmac_f32_e32 v85, v216, v190
	v_fmac_f32_e32 v85, v217, v191
	v_fmac_f32_e32 v85, v218, v192
	v_fmac_f32_e32 v85, v219, v193
	v_fmac_f32_e32 v85, v220, v194
	v_fmac_f32_e32 v85, v221, v195
	v_fmac_f32_e32 v85, v222, v196
	v_fmac_f32_e32 v85, v223, v197
	v_fmac_f32_e32 v85, v224, v232
	v_fmac_f32_e32 v85, v225, v233
	v_fmac_f32_e32 v85, v226, v234
	v_fmac_f32_e32 v85, v227, v235
	v_fmac_f32_e32 v85, v228, v236
	v_fmac_f32_e32 v85, v229, v237
	v_fmac_f32_e32 v85, v230, v238
	v_fmac_f32_e32 v85, v231, v239
	ds_read_b128 v[190:193], v171 offset:3136
	ds_read_b128 v[194:197], v171 offset:3152
	ds_read_b128 v[232:235], v171 offset:3168
	ds_read_b128 v[236:239], v171 offset:3184
	s_waitcnt lgkmcnt(4)
	v_fmac_f32_e32 v90, v200, v174
	v_fmac_f32_e32 v90, v201, v175
	v_fmac_f32_e32 v90, v202, v176
	v_fmac_f32_e32 v90, v203, v177
	v_fmac_f32_e32 v90, v204, v178
	v_fmac_f32_e32 v90, v205, v179
	v_fmac_f32_e32 v90, v206, v180
	v_fmac_f32_e32 v90, v207, v181
	v_fmac_f32_e32 v90, v208, v182
	v_fmac_f32_e32 v90, v209, v183
	v_fmac_f32_e32 v90, v210, v184
	v_fmac_f32_e32 v90, v211, v185
	v_fmac_f32_e32 v90, v212, v186
	v_fmac_f32_e32 v90, v213, v187
	v_fmac_f32_e32 v90, v214, v188
	v_fmac_f32_e32 v90, v215, v189
	ds_read_b128 v[174:177], v171 offset:3584
	ds_read_b128 v[178:181], v171 offset:3600
	ds_read_b128 v[182:185], v171 offset:3616
	ds_read_b128 v[186:189], v171 offset:3632
	s_waitcnt lgkmcnt(4)
	v_fmac_f32_e32 v90, v216, v190
	v_fmac_f32_e32 v90, v217, v191
	v_fmac_f32_e32 v90, v218, v192
	v_fmac_f32_e32 v90, v219, v193
	v_fmac_f32_e32 v90, v220, v194
	v_fmac_f32_e32 v90, v221, v195
	v_fmac_f32_e32 v90, v222, v196
	v_fmac_f32_e32 v90, v223, v197
	v_fmac_f32_e32 v90, v224, v232
	v_fmac_f32_e32 v90, v225, v233
	v_fmac_f32_e32 v90, v226, v234
	v_fmac_f32_e32 v90, v227, v235
	v_fmac_f32_e32 v90, v228, v236
	v_fmac_f32_e32 v90, v229, v237
	v_fmac_f32_e32 v90, v230, v238
	v_fmac_f32_e32 v90, v231, v239
	ds_read_b128 v[190:193], v171 offset:3648
	ds_read_b128 v[194:197], v171 offset:3664
	ds_read_b128 v[232:235], v171 offset:3680
	ds_read_b128 v[236:239], v171 offset:3696
	s_waitcnt lgkmcnt(4)
	v_fmac_f32_e32 v91, v200, v174
	v_fmac_f32_e32 v91, v201, v175
	v_fmac_f32_e32 v91, v202, v176
	v_fmac_f32_e32 v91, v203, v177
	v_fmac_f32_e32 v91, v204, v178
	v_fmac_f32_e32 v91, v205, v179
	v_fmac_f32_e32 v91, v206, v180
	v_fmac_f32_e32 v91, v207, v181
	v_fmac_f32_e32 v91, v208, v182
	v_fmac_f32_e32 v91, v209, v183
	v_fmac_f32_e32 v91, v210, v184
	v_fmac_f32_e32 v91, v211, v185
	v_fmac_f32_e32 v91, v212, v186
	v_fmac_f32_e32 v91, v213, v187
	v_fmac_f32_e32 v91, v214, v188
	v_fmac_f32_e32 v91, v215, v189
	ds_read_b128 v[174:177], v171 offset:4096
	ds_read_b128 v[178:181], v171 offset:4112
	ds_read_b128 v[182:185], v171 offset:4128
	ds_read_b128 v[186:189], v171 offset:4144
	s_waitcnt lgkmcnt(4)
	v_fmac_f32_e32 v91, v216, v190
	v_fmac_f32_e32 v91, v217, v191
	v_fmac_f32_e32 v91, v218, v192
	v_fmac_f32_e32 v91, v219, v193
	v_fmac_f32_e32 v91, v220, v194
	v_fmac_f32_e32 v91, v221, v195
	v_fmac_f32_e32 v91, v222, v196
	v_fmac_f32_e32 v91, v223, v197
	v_fmac_f32_e32 v91, v224, v232
	v_fmac_f32_e32 v91, v225, v233
	v_fmac_f32_e32 v91, v226, v234
	v_fmac_f32_e32 v91, v227, v235
	v_fmac_f32_e32 v91, v228, v236
	v_fmac_f32_e32 v91, v229, v237
	v_fmac_f32_e32 v91, v230, v238
	v_fmac_f32_e32 v91, v231, v239
	ds_read_b128 v[190:193], v171 offset:4160
	ds_read_b128 v[194:197], v171 offset:4176
	ds_read_b128 v[232:235], v171 offset:4192
	ds_read_b128 v[236:239], v171 offset:4208
	s_waitcnt lgkmcnt(4)
	v_fmac_f32_e32 v88, v200, v174
	v_fmac_f32_e32 v88, v201, v175
	v_fmac_f32_e32 v88, v202, v176
	v_fmac_f32_e32 v88, v203, v177
	v_fmac_f32_e32 v88, v204, v178
	v_fmac_f32_e32 v88, v205, v179
	v_fmac_f32_e32 v88, v206, v180
	v_fmac_f32_e32 v88, v207, v181
	v_fmac_f32_e32 v88, v208, v182
	v_fmac_f32_e32 v88, v209, v183
	v_fmac_f32_e32 v88, v210, v184
	v_fmac_f32_e32 v88, v211, v185
	v_fmac_f32_e32 v88, v212, v186
	v_fmac_f32_e32 v88, v213, v187
	v_fmac_f32_e32 v88, v214, v188
	v_fmac_f32_e32 v88, v215, v189
	ds_read_b128 v[174:177], v171 offset:4608
	ds_read_b128 v[178:181], v171 offset:4624
	ds_read_b128 v[182:185], v171 offset:4640
	ds_read_b128 v[186:189], v171 offset:4656
	s_waitcnt lgkmcnt(4)
	v_fmac_f32_e32 v88, v216, v190
	v_fmac_f32_e32 v88, v217, v191
	v_fmac_f32_e32 v88, v218, v192
	v_fmac_f32_e32 v88, v219, v193
	v_fmac_f32_e32 v88, v220, v194
	v_fmac_f32_e32 v88, v221, v195
	v_fmac_f32_e32 v88, v222, v196
	v_fmac_f32_e32 v88, v223, v197
	v_fmac_f32_e32 v88, v224, v232
	v_fmac_f32_e32 v88, v225, v233
	v_fmac_f32_e32 v88, v226, v234
	v_fmac_f32_e32 v88, v227, v235
	v_fmac_f32_e32 v88, v228, v236
	v_fmac_f32_e32 v88, v229, v237
	v_fmac_f32_e32 v88, v230, v238
	v_fmac_f32_e32 v88, v231, v239
	ds_read_b128 v[190:193], v171 offset:4672
	ds_read_b128 v[194:197], v171 offset:4688
	ds_read_b128 v[232:235], v171 offset:4704
	ds_read_b128 v[236:239], v171 offset:4720
	s_waitcnt lgkmcnt(4)
	v_fmac_f32_e32 v89, v200, v174
	v_fmac_f32_e32 v89, v201, v175
	v_fmac_f32_e32 v89, v202, v176
	v_fmac_f32_e32 v89, v203, v177
	v_fmac_f32_e32 v89, v204, v178
	v_fmac_f32_e32 v89, v205, v179
	v_fmac_f32_e32 v89, v206, v180
	v_fmac_f32_e32 v89, v207, v181
	v_fmac_f32_e32 v89, v208, v182
	v_fmac_f32_e32 v89, v209, v183
	v_fmac_f32_e32 v89, v210, v184
	v_fmac_f32_e32 v89, v211, v185
	v_fmac_f32_e32 v89, v212, v186
	v_fmac_f32_e32 v89, v213, v187
	v_fmac_f32_e32 v89, v214, v188
	v_fmac_f32_e32 v89, v215, v189
	ds_read_b128 v[174:177], v171 offset:5120
	ds_read_b128 v[178:181], v171 offset:5136
	ds_read_b128 v[182:185], v171 offset:5152
	ds_read_b128 v[186:189], v171 offset:5168
	s_waitcnt lgkmcnt(4)
	v_fmac_f32_e32 v89, v216, v190
	v_fmac_f32_e32 v89, v217, v191
	v_fmac_f32_e32 v89, v218, v192
	v_fmac_f32_e32 v89, v219, v193
	v_fmac_f32_e32 v89, v220, v194
	v_fmac_f32_e32 v89, v221, v195
	v_fmac_f32_e32 v89, v222, v196
	v_fmac_f32_e32 v89, v223, v197
	v_fmac_f32_e32 v89, v224, v232
	v_fmac_f32_e32 v89, v225, v233
	v_fmac_f32_e32 v89, v226, v234
	v_fmac_f32_e32 v89, v227, v235
	v_fmac_f32_e32 v89, v228, v236
	v_fmac_f32_e32 v89, v229, v237
	v_fmac_f32_e32 v89, v230, v238
	v_fmac_f32_e32 v89, v231, v239
	ds_read_b128 v[190:193], v171 offset:5184
	ds_read_b128 v[194:197], v171 offset:5200
	ds_read_b128 v[232:235], v171 offset:5216
	ds_read_b128 v[236:239], v171 offset:5232
	s_waitcnt lgkmcnt(4)
	v_fmac_f32_e32 v94, v200, v174
	v_fmac_f32_e32 v94, v201, v175
	v_fmac_f32_e32 v94, v202, v176
	v_fmac_f32_e32 v94, v203, v177
	v_fmac_f32_e32 v94, v204, v178
	v_fmac_f32_e32 v94, v205, v179
	v_fmac_f32_e32 v94, v206, v180
	v_fmac_f32_e32 v94, v207, v181
	v_fmac_f32_e32 v94, v208, v182
	v_fmac_f32_e32 v94, v209, v183
	v_fmac_f32_e32 v94, v210, v184
	v_fmac_f32_e32 v94, v211, v185
	v_fmac_f32_e32 v94, v212, v186
	v_fmac_f32_e32 v94, v213, v187
	v_fmac_f32_e32 v94, v214, v188
	v_fmac_f32_e32 v94, v215, v189
	ds_read_b128 v[174:177], v171 offset:5632
	ds_read_b128 v[178:181], v171 offset:5648
	ds_read_b128 v[182:185], v171 offset:5664
	ds_read_b128 v[186:189], v171 offset:5680
	s_waitcnt lgkmcnt(4)
	v_fmac_f32_e32 v94, v216, v190
	v_fmac_f32_e32 v94, v217, v191
	v_fmac_f32_e32 v94, v218, v192
	v_fmac_f32_e32 v94, v219, v193
	v_fmac_f32_e32 v94, v220, v194
	v_fmac_f32_e32 v94, v221, v195
	v_fmac_f32_e32 v94, v222, v196
	v_fmac_f32_e32 v94, v223, v197
	v_fmac_f32_e32 v94, v224, v232
	v_fmac_f32_e32 v94, v225, v233
	v_fmac_f32_e32 v94, v226, v234
	v_fmac_f32_e32 v94, v227, v235
	v_fmac_f32_e32 v94, v228, v236
	v_fmac_f32_e32 v94, v229, v237
	v_fmac_f32_e32 v94, v230, v238
	v_fmac_f32_e32 v94, v231, v239
	ds_read_b128 v[190:193], v171 offset:5696
	ds_read_b128 v[194:197], v171 offset:5712
	ds_read_b128 v[232:235], v171 offset:5728
	ds_read_b128 v[236:239], v171 offset:5744
	s_waitcnt lgkmcnt(4)
	v_fmac_f32_e32 v95, v200, v174
	v_fmac_f32_e32 v95, v201, v175
	v_fmac_f32_e32 v95, v202, v176
	v_fmac_f32_e32 v95, v203, v177
	v_fmac_f32_e32 v95, v204, v178
	v_fmac_f32_e32 v95, v205, v179
	v_fmac_f32_e32 v95, v206, v180
	v_fmac_f32_e32 v95, v207, v181
	v_fmac_f32_e32 v95, v208, v182
	v_fmac_f32_e32 v95, v209, v183
	v_fmac_f32_e32 v95, v210, v184
	v_fmac_f32_e32 v95, v211, v185
	v_fmac_f32_e32 v95, v212, v186
	v_fmac_f32_e32 v95, v213, v187
	v_fmac_f32_e32 v95, v214, v188
	v_fmac_f32_e32 v95, v215, v189
	ds_read_b128 v[174:177], v171 offset:6144
	ds_read_b128 v[178:181], v171 offset:6160
	ds_read_b128 v[182:185], v171 offset:6176
	ds_read_b128 v[186:189], v171 offset:6192
	s_waitcnt lgkmcnt(4)
	v_fmac_f32_e32 v95, v216, v190
	v_fmac_f32_e32 v95, v217, v191
	v_fmac_f32_e32 v95, v218, v192
	v_fmac_f32_e32 v95, v219, v193
	v_fmac_f32_e32 v95, v220, v194
	v_fmac_f32_e32 v95, v221, v195
	v_fmac_f32_e32 v95, v222, v196
	v_fmac_f32_e32 v95, v223, v197
	v_fmac_f32_e32 v95, v224, v232
	v_fmac_f32_e32 v95, v225, v233
	v_fmac_f32_e32 v95, v226, v234
	v_fmac_f32_e32 v95, v227, v235
	v_fmac_f32_e32 v95, v228, v236
	v_fmac_f32_e32 v95, v229, v237
	v_fmac_f32_e32 v95, v230, v238
	v_fmac_f32_e32 v95, v231, v239
	ds_read_b128 v[190:193], v171 offset:6208
	ds_read_b128 v[194:197], v171 offset:6224
	ds_read_b128 v[232:235], v171 offset:6240
	ds_read_b128 v[236:239], v171 offset:6256
	s_waitcnt lgkmcnt(4)
	v_fmac_f32_e32 v92, v200, v174
	v_fmac_f32_e32 v92, v201, v175
	v_fmac_f32_e32 v92, v202, v176
	v_fmac_f32_e32 v92, v203, v177
	v_fmac_f32_e32 v92, v204, v178
	v_fmac_f32_e32 v92, v205, v179
	v_fmac_f32_e32 v92, v206, v180
	v_fmac_f32_e32 v92, v207, v181
	v_fmac_f32_e32 v92, v208, v182
	v_fmac_f32_e32 v92, v209, v183
	v_fmac_f32_e32 v92, v210, v184
	v_fmac_f32_e32 v92, v211, v185
	v_fmac_f32_e32 v92, v212, v186
	v_fmac_f32_e32 v92, v213, v187
	v_fmac_f32_e32 v92, v214, v188
	v_fmac_f32_e32 v92, v215, v189
	ds_read_b128 v[174:177], v171 offset:6656
	ds_read_b128 v[178:181], v171 offset:6672
	ds_read_b128 v[182:185], v171 offset:6688
	ds_read_b128 v[186:189], v171 offset:6704
	s_waitcnt lgkmcnt(4)
	v_fmac_f32_e32 v92, v216, v190
	v_fmac_f32_e32 v92, v217, v191
	v_fmac_f32_e32 v92, v218, v192
	v_fmac_f32_e32 v92, v219, v193
	v_fmac_f32_e32 v92, v220, v194
	v_fmac_f32_e32 v92, v221, v195
	v_fmac_f32_e32 v92, v222, v196
	v_fmac_f32_e32 v92, v223, v197
	v_fmac_f32_e32 v92, v224, v232
	v_fmac_f32_e32 v92, v225, v233
	v_fmac_f32_e32 v92, v226, v234
	v_fmac_f32_e32 v92, v227, v235
	v_fmac_f32_e32 v92, v228, v236
	v_fmac_f32_e32 v92, v229, v237
	v_fmac_f32_e32 v92, v230, v238
	v_fmac_f32_e32 v92, v231, v239
	ds_read_b128 v[190:193], v171 offset:6720
	ds_read_b128 v[194:197], v171 offset:6736
	ds_read_b128 v[232:235], v171 offset:6752
	ds_read_b128 v[236:239], v171 offset:6768
	s_waitcnt lgkmcnt(4)
	v_fmac_f32_e32 v93, v200, v174
	v_fmac_f32_e32 v93, v201, v175
	v_fmac_f32_e32 v93, v202, v176
	v_fmac_f32_e32 v93, v203, v177
	v_fmac_f32_e32 v93, v204, v178
	v_fmac_f32_e32 v93, v205, v179
	v_fmac_f32_e32 v93, v206, v180
	v_fmac_f32_e32 v93, v207, v181
	v_fmac_f32_e32 v93, v208, v182
	v_fmac_f32_e32 v93, v209, v183
	v_fmac_f32_e32 v93, v210, v184
	v_fmac_f32_e32 v93, v211, v185
	v_fmac_f32_e32 v93, v212, v186
	v_fmac_f32_e32 v93, v213, v187
	v_fmac_f32_e32 v93, v214, v188
	v_fmac_f32_e32 v93, v215, v189
	ds_read_b128 v[174:177], v171 offset:7168
	ds_read_b128 v[178:181], v171 offset:7184
	ds_read_b128 v[182:185], v171 offset:7200
	ds_read_b128 v[186:189], v171 offset:7216
	s_waitcnt lgkmcnt(4)
	v_fmac_f32_e32 v93, v216, v190
	v_fmac_f32_e32 v93, v217, v191
	v_fmac_f32_e32 v93, v218, v192
	v_fmac_f32_e32 v93, v219, v193
	v_fmac_f32_e32 v93, v220, v194
	v_fmac_f32_e32 v93, v221, v195
	v_fmac_f32_e32 v93, v222, v196
	v_fmac_f32_e32 v93, v223, v197
	v_fmac_f32_e32 v93, v224, v232
	v_fmac_f32_e32 v93, v225, v233
	v_fmac_f32_e32 v93, v226, v234
	v_fmac_f32_e32 v93, v227, v235
	v_fmac_f32_e32 v93, v228, v236
	v_fmac_f32_e32 v93, v229, v237
	v_fmac_f32_e32 v93, v230, v238
	v_fmac_f32_e32 v93, v231, v239
	ds_read_b128 v[190:193], v171 offset:7232
	ds_read_b128 v[194:197], v171 offset:7248
	ds_read_b128 v[232:235], v171 offset:7264
	ds_read_b128 v[236:239], v171 offset:7280
	s_waitcnt lgkmcnt(4)
	v_fmac_f32_e32 v100, v200, v174
	v_fmac_f32_e32 v100, v201, v175
	v_fmac_f32_e32 v100, v202, v176
	v_fmac_f32_e32 v100, v203, v177
	v_fmac_f32_e32 v100, v204, v178
	v_fmac_f32_e32 v100, v205, v179
	v_fmac_f32_e32 v100, v206, v180
	v_fmac_f32_e32 v100, v207, v181
	v_fmac_f32_e32 v100, v208, v182
	v_fmac_f32_e32 v100, v209, v183
	v_fmac_f32_e32 v100, v210, v184
	v_fmac_f32_e32 v100, v211, v185
	v_fmac_f32_e32 v100, v212, v186
	v_fmac_f32_e32 v100, v213, v187
	v_fmac_f32_e32 v100, v214, v188
	v_fmac_f32_e32 v100, v215, v189
	ds_read_b128 v[174:177], v171 offset:7680
	ds_read_b128 v[178:181], v171 offset:7696
	ds_read_b128 v[182:185], v171 offset:7712
	ds_read_b128 v[186:189], v171 offset:7728
	s_waitcnt lgkmcnt(4)
	v_fmac_f32_e32 v100, v216, v190
	v_fmac_f32_e32 v100, v217, v191
	v_fmac_f32_e32 v100, v218, v192
	v_fmac_f32_e32 v100, v219, v193
	v_fmac_f32_e32 v100, v220, v194
	v_fmac_f32_e32 v100, v221, v195
	v_fmac_f32_e32 v100, v222, v196
	v_fmac_f32_e32 v100, v223, v197
	v_fmac_f32_e32 v100, v224, v232
	v_fmac_f32_e32 v100, v225, v233
	v_fmac_f32_e32 v100, v226, v234
	v_fmac_f32_e32 v100, v227, v235
	v_fmac_f32_e32 v100, v228, v236
	v_fmac_f32_e32 v100, v229, v237
	v_fmac_f32_e32 v100, v230, v238
	v_fmac_f32_e32 v100, v231, v239
	ds_read_b128 v[190:193], v171 offset:7744
	ds_read_b128 v[194:197], v171 offset:7760
	ds_read_b128 v[232:235], v171 offset:7776
	ds_read_b128 v[236:239], v171 offset:7792
	s_waitcnt lgkmcnt(4)
	v_fmac_f32_e32 v101, v200, v174
	v_fmac_f32_e32 v101, v201, v175
	v_fmac_f32_e32 v101, v202, v176
	v_fmac_f32_e32 v101, v203, v177
	v_fmac_f32_e32 v101, v204, v178
	v_fmac_f32_e32 v101, v205, v179
	v_fmac_f32_e32 v101, v206, v180
	v_fmac_f32_e32 v101, v207, v181
	v_fmac_f32_e32 v101, v208, v182
	v_fmac_f32_e32 v101, v209, v183
	v_fmac_f32_e32 v101, v210, v184
	v_fmac_f32_e32 v101, v211, v185
	v_fmac_f32_e32 v101, v212, v186
	v_fmac_f32_e32 v101, v213, v187
	v_fmac_f32_e32 v101, v214, v188
	v_fmac_f32_e32 v101, v215, v189
	ds_read_b128 v[174:177], v171 offset:8192
	ds_read_b128 v[178:181], v171 offset:8208
	ds_read_b128 v[182:185], v171 offset:8224
	ds_read_b128 v[186:189], v171 offset:8240
	s_waitcnt lgkmcnt(4)
	v_fmac_f32_e32 v101, v216, v190
	v_fmac_f32_e32 v101, v217, v191
	v_fmac_f32_e32 v101, v218, v192
	v_fmac_f32_e32 v101, v219, v193
	v_fmac_f32_e32 v101, v220, v194
	v_fmac_f32_e32 v101, v221, v195
	v_fmac_f32_e32 v101, v222, v196
	v_fmac_f32_e32 v101, v223, v197
	v_fmac_f32_e32 v101, v224, v232
	v_fmac_f32_e32 v101, v225, v233
	v_fmac_f32_e32 v101, v226, v234
	v_fmac_f32_e32 v101, v227, v235
	v_fmac_f32_e32 v101, v228, v236
	v_fmac_f32_e32 v101, v229, v237
	v_fmac_f32_e32 v101, v230, v238
	v_fmac_f32_e32 v101, v231, v239
	ds_read_b128 v[190:193], v171 offset:8256
	ds_read_b128 v[194:197], v171 offset:8272
	ds_read_b128 v[232:235], v171 offset:8288
	ds_read_b128 v[236:239], v171 offset:8304
	s_waitcnt lgkmcnt(4)
	v_fmac_f32_e32 v98, v200, v174
	v_fmac_f32_e32 v98, v201, v175
	v_fmac_f32_e32 v98, v202, v176
	v_fmac_f32_e32 v98, v203, v177
	v_fmac_f32_e32 v98, v204, v178
	v_fmac_f32_e32 v98, v205, v179
	v_fmac_f32_e32 v98, v206, v180
	v_fmac_f32_e32 v98, v207, v181
	v_fmac_f32_e32 v98, v208, v182
	v_fmac_f32_e32 v98, v209, v183
	v_fmac_f32_e32 v98, v210, v184
	v_fmac_f32_e32 v98, v211, v185
	v_fmac_f32_e32 v98, v212, v186
	v_fmac_f32_e32 v98, v213, v187
	v_fmac_f32_e32 v98, v214, v188
	v_fmac_f32_e32 v98, v215, v189
	ds_read_b128 v[174:177], v171 offset:8704
	ds_read_b128 v[178:181], v171 offset:8720
	ds_read_b128 v[182:185], v171 offset:8736
	ds_read_b128 v[186:189], v171 offset:8752
	s_waitcnt lgkmcnt(4)
	v_fmac_f32_e32 v98, v216, v190
	v_fmac_f32_e32 v98, v217, v191
	v_fmac_f32_e32 v98, v218, v192
	v_fmac_f32_e32 v98, v219, v193
	v_fmac_f32_e32 v98, v220, v194
	v_fmac_f32_e32 v98, v221, v195
	v_fmac_f32_e32 v98, v222, v196
	v_fmac_f32_e32 v98, v223, v197
	v_fmac_f32_e32 v98, v224, v232
	v_fmac_f32_e32 v98, v225, v233
	v_fmac_f32_e32 v98, v226, v234
	v_fmac_f32_e32 v98, v227, v235
	v_fmac_f32_e32 v98, v228, v236
	v_fmac_f32_e32 v98, v229, v237
	v_fmac_f32_e32 v98, v230, v238
	v_fmac_f32_e32 v98, v231, v239
	ds_read_b128 v[190:193], v171 offset:8768
	ds_read_b128 v[194:197], v171 offset:8784
	ds_read_b128 v[232:235], v171 offset:8800
	ds_read_b128 v[236:239], v171 offset:8816
	s_waitcnt lgkmcnt(4)
	v_fmac_f32_e32 v99, v200, v174
	v_fmac_f32_e32 v99, v201, v175
	v_fmac_f32_e32 v99, v202, v176
	v_fmac_f32_e32 v99, v203, v177
	v_fmac_f32_e32 v99, v204, v178
	v_fmac_f32_e32 v99, v205, v179
	v_fmac_f32_e32 v99, v206, v180
	v_fmac_f32_e32 v99, v207, v181
	v_fmac_f32_e32 v99, v208, v182
	v_fmac_f32_e32 v99, v209, v183
	v_fmac_f32_e32 v99, v210, v184
	v_fmac_f32_e32 v99, v211, v185
	v_fmac_f32_e32 v99, v212, v186
	v_fmac_f32_e32 v99, v213, v187
	v_fmac_f32_e32 v99, v214, v188
	v_fmac_f32_e32 v99, v215, v189
	ds_read_b128 v[174:177], v171 offset:9216
	ds_read_b128 v[178:181], v171 offset:9232
	ds_read_b128 v[182:185], v171 offset:9248
	ds_read_b128 v[186:189], v171 offset:9264
	s_waitcnt lgkmcnt(4)
	v_fmac_f32_e32 v99, v216, v190
	v_fmac_f32_e32 v99, v217, v191
	v_fmac_f32_e32 v99, v218, v192
	v_fmac_f32_e32 v99, v219, v193
	v_fmac_f32_e32 v99, v220, v194
	v_fmac_f32_e32 v99, v221, v195
	v_fmac_f32_e32 v99, v222, v196
	v_fmac_f32_e32 v99, v223, v197
	v_fmac_f32_e32 v99, v224, v232
	v_fmac_f32_e32 v99, v225, v233
	v_fmac_f32_e32 v99, v226, v234
	v_fmac_f32_e32 v99, v227, v235
	v_fmac_f32_e32 v99, v228, v236
	v_fmac_f32_e32 v99, v229, v237
	v_fmac_f32_e32 v99, v230, v238
	v_fmac_f32_e32 v99, v231, v239
	ds_read_b128 v[190:193], v171 offset:9280
	ds_read_b128 v[194:197], v171 offset:9296
	ds_read_b128 v[232:235], v171 offset:9312
	ds_read_b128 v[236:239], v171 offset:9328
	s_waitcnt lgkmcnt(4)
	v_fmac_f32_e32 v104, v200, v174
	v_fmac_f32_e32 v104, v201, v175
	v_fmac_f32_e32 v104, v202, v176
	v_fmac_f32_e32 v104, v203, v177
	v_fmac_f32_e32 v104, v204, v178
	v_fmac_f32_e32 v104, v205, v179
	v_fmac_f32_e32 v104, v206, v180
	v_fmac_f32_e32 v104, v207, v181
	v_fmac_f32_e32 v104, v208, v182
	v_fmac_f32_e32 v104, v209, v183
	v_fmac_f32_e32 v104, v210, v184
	v_fmac_f32_e32 v104, v211, v185
	v_fmac_f32_e32 v104, v212, v186
	v_fmac_f32_e32 v104, v213, v187
	v_fmac_f32_e32 v104, v214, v188
	v_fmac_f32_e32 v104, v215, v189
	ds_read_b128 v[174:177], v171 offset:9728
	ds_read_b128 v[178:181], v171 offset:9744
	ds_read_b128 v[182:185], v171 offset:9760
	ds_read_b128 v[186:189], v171 offset:9776
	s_waitcnt lgkmcnt(4)
	v_fmac_f32_e32 v104, v216, v190
	v_fmac_f32_e32 v104, v217, v191
	v_fmac_f32_e32 v104, v218, v192
	v_fmac_f32_e32 v104, v219, v193
	v_fmac_f32_e32 v104, v220, v194
	v_fmac_f32_e32 v104, v221, v195
	v_fmac_f32_e32 v104, v222, v196
	v_fmac_f32_e32 v104, v223, v197
	v_fmac_f32_e32 v104, v224, v232
	v_fmac_f32_e32 v104, v225, v233
	v_fmac_f32_e32 v104, v226, v234
	v_fmac_f32_e32 v104, v227, v235
	v_fmac_f32_e32 v104, v228, v236
	v_fmac_f32_e32 v104, v229, v237
	v_fmac_f32_e32 v104, v230, v238
	v_fmac_f32_e32 v104, v231, v239
	ds_read_b128 v[190:193], v171 offset:9792
	ds_read_b128 v[194:197], v171 offset:9808
	ds_read_b128 v[232:235], v171 offset:9824
	ds_read_b128 v[236:239], v171 offset:9840
	s_waitcnt lgkmcnt(4)
	v_fmac_f32_e32 v105, v200, v174
	v_fmac_f32_e32 v105, v201, v175
	v_fmac_f32_e32 v105, v202, v176
	v_fmac_f32_e32 v105, v203, v177
	v_fmac_f32_e32 v105, v204, v178
	v_fmac_f32_e32 v105, v205, v179
	v_fmac_f32_e32 v105, v206, v180
	v_fmac_f32_e32 v105, v207, v181
	v_fmac_f32_e32 v105, v208, v182
	v_fmac_f32_e32 v105, v209, v183
	v_fmac_f32_e32 v105, v210, v184
	v_fmac_f32_e32 v105, v211, v185
	v_fmac_f32_e32 v105, v212, v186
	v_fmac_f32_e32 v105, v213, v187
	v_fmac_f32_e32 v105, v214, v188
	v_fmac_f32_e32 v105, v215, v189
	ds_read_b128 v[174:177], v171 offset:10240
	ds_read_b128 v[178:181], v171 offset:10256
	ds_read_b128 v[182:185], v171 offset:10272
	ds_read_b128 v[186:189], v171 offset:10288
	s_waitcnt lgkmcnt(4)
	v_fmac_f32_e32 v105, v216, v190
	v_fmac_f32_e32 v105, v217, v191
	v_fmac_f32_e32 v105, v218, v192
	v_fmac_f32_e32 v105, v219, v193
	v_fmac_f32_e32 v105, v220, v194
	v_fmac_f32_e32 v105, v221, v195
	v_fmac_f32_e32 v105, v222, v196
	v_fmac_f32_e32 v105, v223, v197
	v_fmac_f32_e32 v105, v224, v232
	v_fmac_f32_e32 v105, v225, v233
	v_fmac_f32_e32 v105, v226, v234
	v_fmac_f32_e32 v105, v227, v235
	v_fmac_f32_e32 v105, v228, v236
	v_fmac_f32_e32 v105, v229, v237
	v_fmac_f32_e32 v105, v230, v238
	v_fmac_f32_e32 v105, v231, v239
	ds_read_b128 v[190:193], v171 offset:10304
	ds_read_b128 v[194:197], v171 offset:10320
	ds_read_b128 v[232:235], v171 offset:10336
	ds_read_b128 v[236:239], v171 offset:10352
	s_waitcnt lgkmcnt(4)
	v_fmac_f32_e32 v102, v200, v174
	v_fmac_f32_e32 v102, v201, v175
	v_fmac_f32_e32 v102, v202, v176
	v_fmac_f32_e32 v102, v203, v177
	v_fmac_f32_e32 v102, v204, v178
	v_fmac_f32_e32 v102, v205, v179
	v_fmac_f32_e32 v102, v206, v180
	v_fmac_f32_e32 v102, v207, v181
	v_fmac_f32_e32 v102, v208, v182
	v_fmac_f32_e32 v102, v209, v183
	v_fmac_f32_e32 v102, v210, v184
	v_fmac_f32_e32 v102, v211, v185
	v_fmac_f32_e32 v102, v212, v186
	v_fmac_f32_e32 v102, v213, v187
	v_fmac_f32_e32 v102, v214, v188
	v_fmac_f32_e32 v102, v215, v189
	ds_read_b128 v[174:177], v171 offset:10752
	ds_read_b128 v[178:181], v171 offset:10768
	ds_read_b128 v[182:185], v171 offset:10784
	ds_read_b128 v[186:189], v171 offset:10800
	s_waitcnt lgkmcnt(4)
	v_fmac_f32_e32 v102, v216, v190
	v_fmac_f32_e32 v102, v217, v191
	v_fmac_f32_e32 v102, v218, v192
	v_fmac_f32_e32 v102, v219, v193
	v_fmac_f32_e32 v102, v220, v194
	v_fmac_f32_e32 v102, v221, v195
	v_fmac_f32_e32 v102, v222, v196
	v_fmac_f32_e32 v102, v223, v197
	v_fmac_f32_e32 v102, v224, v232
	v_fmac_f32_e32 v102, v225, v233
	v_fmac_f32_e32 v102, v226, v234
	v_fmac_f32_e32 v102, v227, v235
	v_fmac_f32_e32 v102, v228, v236
	v_fmac_f32_e32 v102, v229, v237
	v_fmac_f32_e32 v102, v230, v238
	v_fmac_f32_e32 v102, v231, v239
	ds_read_b128 v[190:193], v171 offset:10816
	ds_read_b128 v[194:197], v171 offset:10832
	ds_read_b128 v[232:235], v171 offset:10848
	ds_read_b128 v[236:239], v171 offset:10864
	s_waitcnt lgkmcnt(4)
	v_fmac_f32_e32 v103, v200, v174
	v_fmac_f32_e32 v103, v201, v175
	v_fmac_f32_e32 v103, v202, v176
	v_fmac_f32_e32 v103, v203, v177
	v_fmac_f32_e32 v103, v204, v178
	v_fmac_f32_e32 v103, v205, v179
	v_fmac_f32_e32 v103, v206, v180
	v_fmac_f32_e32 v103, v207, v181
	v_fmac_f32_e32 v103, v208, v182
	v_fmac_f32_e32 v103, v209, v183
	v_fmac_f32_e32 v103, v210, v184
	v_fmac_f32_e32 v103, v211, v185
	v_fmac_f32_e32 v103, v212, v186
	v_fmac_f32_e32 v103, v213, v187
	v_fmac_f32_e32 v103, v214, v188
	v_fmac_f32_e32 v103, v215, v189
	ds_read_b128 v[174:177], v171 offset:11264
	ds_read_b128 v[178:181], v171 offset:11280
	ds_read_b128 v[182:185], v171 offset:11296
	ds_read_b128 v[186:189], v171 offset:11312
	s_waitcnt lgkmcnt(4)
	v_fmac_f32_e32 v103, v216, v190
	v_fmac_f32_e32 v103, v217, v191
	v_fmac_f32_e32 v103, v218, v192
	v_fmac_f32_e32 v103, v219, v193
	v_fmac_f32_e32 v103, v220, v194
	v_fmac_f32_e32 v103, v221, v195
	v_fmac_f32_e32 v103, v222, v196
	v_fmac_f32_e32 v103, v223, v197
	v_fmac_f32_e32 v103, v224, v232
	v_fmac_f32_e32 v103, v225, v233
	v_fmac_f32_e32 v103, v226, v234
	v_fmac_f32_e32 v103, v227, v235
	v_fmac_f32_e32 v103, v228, v236
	v_fmac_f32_e32 v103, v229, v237
	v_fmac_f32_e32 v103, v230, v238
	v_fmac_f32_e32 v103, v231, v239
	ds_read_b128 v[190:193], v171 offset:11328
	ds_read_b128 v[194:197], v171 offset:11344
	ds_read_b128 v[232:235], v171 offset:11360
	ds_read_b128 v[236:239], v171 offset:11376
	s_waitcnt lgkmcnt(4)
	v_fmac_f32_e32 v108, v200, v174
	v_fmac_f32_e32 v108, v201, v175
	v_fmac_f32_e32 v108, v202, v176
	v_fmac_f32_e32 v108, v203, v177
	v_fmac_f32_e32 v108, v204, v178
	v_fmac_f32_e32 v108, v205, v179
	v_fmac_f32_e32 v108, v206, v180
	v_fmac_f32_e32 v108, v207, v181
	v_fmac_f32_e32 v108, v208, v182
	v_fmac_f32_e32 v108, v209, v183
	v_fmac_f32_e32 v108, v210, v184
	v_fmac_f32_e32 v108, v211, v185
	v_fmac_f32_e32 v108, v212, v186
	v_fmac_f32_e32 v108, v213, v187
	v_fmac_f32_e32 v108, v214, v188
	v_fmac_f32_e32 v108, v215, v189
	ds_read_b128 v[174:177], v171 offset:11776
	ds_read_b128 v[178:181], v171 offset:11792
	ds_read_b128 v[182:185], v171 offset:11808
	ds_read_b128 v[186:189], v171 offset:11824
	s_waitcnt lgkmcnt(4)
	v_fmac_f32_e32 v108, v216, v190
	v_fmac_f32_e32 v108, v217, v191
	v_fmac_f32_e32 v108, v218, v192
	v_fmac_f32_e32 v108, v219, v193
	v_fmac_f32_e32 v108, v220, v194
	v_fmac_f32_e32 v108, v221, v195
	v_fmac_f32_e32 v108, v222, v196
	v_fmac_f32_e32 v108, v223, v197
	v_fmac_f32_e32 v108, v224, v232
	v_fmac_f32_e32 v108, v225, v233
	v_fmac_f32_e32 v108, v226, v234
	v_fmac_f32_e32 v108, v227, v235
	v_fmac_f32_e32 v108, v228, v236
	v_fmac_f32_e32 v108, v229, v237
	v_fmac_f32_e32 v108, v230, v238
	v_fmac_f32_e32 v108, v231, v239
	ds_read_b128 v[190:193], v171 offset:11840
	ds_read_b128 v[194:197], v171 offset:11856
	ds_read_b128 v[232:235], v171 offset:11872
	ds_read_b128 v[236:239], v171 offset:11888
	s_waitcnt lgkmcnt(4)
	v_fmac_f32_e32 v109, v200, v174
	v_fmac_f32_e32 v109, v201, v175
	v_fmac_f32_e32 v109, v202, v176
	v_fmac_f32_e32 v109, v203, v177
	v_fmac_f32_e32 v109, v204, v178
	v_fmac_f32_e32 v109, v205, v179
	v_fmac_f32_e32 v109, v206, v180
	v_fmac_f32_e32 v109, v207, v181
	v_fmac_f32_e32 v109, v208, v182
	v_fmac_f32_e32 v109, v209, v183
	v_fmac_f32_e32 v109, v210, v184
	v_fmac_f32_e32 v109, v211, v185
	v_fmac_f32_e32 v109, v212, v186
	v_fmac_f32_e32 v109, v213, v187
	v_fmac_f32_e32 v109, v214, v188
	v_fmac_f32_e32 v109, v215, v189
	ds_read_b128 v[174:177], v171 offset:12288
	ds_read_b128 v[178:181], v171 offset:12304
	ds_read_b128 v[182:185], v171 offset:12320
	ds_read_b128 v[186:189], v171 offset:12336
	s_waitcnt lgkmcnt(4)
	v_fmac_f32_e32 v109, v216, v190
	v_fmac_f32_e32 v109, v217, v191
	v_fmac_f32_e32 v109, v218, v192
	v_fmac_f32_e32 v109, v219, v193
	v_fmac_f32_e32 v109, v220, v194
	v_fmac_f32_e32 v109, v221, v195
	v_fmac_f32_e32 v109, v222, v196
	v_fmac_f32_e32 v109, v223, v197
	v_fmac_f32_e32 v109, v224, v232
	v_fmac_f32_e32 v109, v225, v233
	v_fmac_f32_e32 v109, v226, v234
	v_fmac_f32_e32 v109, v227, v235
	v_fmac_f32_e32 v109, v228, v236
	v_fmac_f32_e32 v109, v229, v237
	v_fmac_f32_e32 v109, v230, v238
	v_fmac_f32_e32 v109, v231, v239
	ds_read_b128 v[190:193], v171 offset:12352
	ds_read_b128 v[194:197], v171 offset:12368
	ds_read_b128 v[232:235], v171 offset:12384
	ds_read_b128 v[236:239], v171 offset:12400
	s_waitcnt lgkmcnt(4)
	v_fmac_f32_e32 v106, v200, v174
	v_fmac_f32_e32 v106, v201, v175
	v_fmac_f32_e32 v106, v202, v176
	v_fmac_f32_e32 v106, v203, v177
	v_fmac_f32_e32 v106, v204, v178
	v_fmac_f32_e32 v106, v205, v179
	v_fmac_f32_e32 v106, v206, v180
	v_fmac_f32_e32 v106, v207, v181
	v_fmac_f32_e32 v106, v208, v182
	v_fmac_f32_e32 v106, v209, v183
	v_fmac_f32_e32 v106, v210, v184
	v_fmac_f32_e32 v106, v211, v185
	v_fmac_f32_e32 v106, v212, v186
	v_fmac_f32_e32 v106, v213, v187
	v_fmac_f32_e32 v106, v214, v188
	v_fmac_f32_e32 v106, v215, v189
	ds_read_b128 v[174:177], v171 offset:12800
	ds_read_b128 v[178:181], v171 offset:12816
	ds_read_b128 v[182:185], v171 offset:12832
	ds_read_b128 v[186:189], v171 offset:12848
	s_waitcnt lgkmcnt(4)
	v_fmac_f32_e32 v106, v216, v190
	v_fmac_f32_e32 v106, v217, v191
	v_fmac_f32_e32 v106, v218, v192
	v_fmac_f32_e32 v106, v219, v193
	v_fmac_f32_e32 v106, v220, v194
	v_fmac_f32_e32 v106, v221, v195
	v_fmac_f32_e32 v106, v222, v196
	v_fmac_f32_e32 v106, v223, v197
	v_fmac_f32_e32 v106, v224, v232
	v_fmac_f32_e32 v106, v225, v233
	v_fmac_f32_e32 v106, v226, v234
	v_fmac_f32_e32 v106, v227, v235
	v_fmac_f32_e32 v106, v228, v236
	v_fmac_f32_e32 v106, v229, v237
	v_fmac_f32_e32 v106, v230, v238
	v_fmac_f32_e32 v106, v231, v239
	ds_read_b128 v[190:193], v171 offset:12864
	ds_read_b128 v[194:197], v171 offset:12880
	ds_read_b128 v[232:235], v171 offset:12896
	ds_read_b128 v[236:239], v171 offset:12912
	s_waitcnt lgkmcnt(4)
	v_fmac_f32_e32 v107, v200, v174
	v_fmac_f32_e32 v107, v201, v175
	v_fmac_f32_e32 v107, v202, v176
	v_fmac_f32_e32 v107, v203, v177
	v_fmac_f32_e32 v107, v204, v178
	v_fmac_f32_e32 v107, v205, v179
	v_fmac_f32_e32 v107, v206, v180
	v_fmac_f32_e32 v107, v207, v181
	v_fmac_f32_e32 v107, v208, v182
	v_fmac_f32_e32 v107, v209, v183
	v_fmac_f32_e32 v107, v210, v184
	v_fmac_f32_e32 v107, v211, v185
	v_fmac_f32_e32 v107, v212, v186
	v_fmac_f32_e32 v107, v213, v187
	v_fmac_f32_e32 v107, v214, v188
	v_fmac_f32_e32 v107, v215, v189
	ds_read_b128 v[174:177], v171 offset:13312
	ds_read_b128 v[178:181], v171 offset:13328
	ds_read_b128 v[182:185], v171 offset:13344
	ds_read_b128 v[186:189], v171 offset:13360
	s_waitcnt lgkmcnt(4)
	v_fmac_f32_e32 v107, v216, v190
	v_fmac_f32_e32 v107, v217, v191
	v_fmac_f32_e32 v107, v218, v192
	v_fmac_f32_e32 v107, v219, v193
	v_fmac_f32_e32 v107, v220, v194
	v_fmac_f32_e32 v107, v221, v195
	v_fmac_f32_e32 v107, v222, v196
	v_fmac_f32_e32 v107, v223, v197
	v_fmac_f32_e32 v107, v224, v232
	v_fmac_f32_e32 v107, v225, v233
	v_fmac_f32_e32 v107, v226, v234
	v_fmac_f32_e32 v107, v227, v235
	v_fmac_f32_e32 v107, v228, v236
	v_fmac_f32_e32 v107, v229, v237
	v_fmac_f32_e32 v107, v230, v238
	v_fmac_f32_e32 v107, v231, v239
	ds_read_b128 v[190:193], v171 offset:13376
	ds_read_b128 v[194:197], v171 offset:13392
	ds_read_b128 v[232:235], v171 offset:13408
	ds_read_b128 v[236:239], v171 offset:13424
	s_waitcnt lgkmcnt(4)
	v_fmac_f32_e32 v112, v200, v174
	v_fmac_f32_e32 v112, v201, v175
	v_fmac_f32_e32 v112, v202, v176
	v_fmac_f32_e32 v112, v203, v177
	v_fmac_f32_e32 v112, v204, v178
	v_fmac_f32_e32 v112, v205, v179
	v_fmac_f32_e32 v112, v206, v180
	v_fmac_f32_e32 v112, v207, v181
	v_fmac_f32_e32 v112, v208, v182
	v_fmac_f32_e32 v112, v209, v183
	v_fmac_f32_e32 v112, v210, v184
	v_fmac_f32_e32 v112, v211, v185
	v_fmac_f32_e32 v112, v212, v186
	v_fmac_f32_e32 v112, v213, v187
	v_fmac_f32_e32 v112, v214, v188
	v_fmac_f32_e32 v112, v215, v189
	ds_read_b128 v[174:177], v171 offset:13824
	ds_read_b128 v[178:181], v171 offset:13840
	ds_read_b128 v[182:185], v171 offset:13856
	ds_read_b128 v[186:189], v171 offset:13872
	s_waitcnt lgkmcnt(4)
	v_fmac_f32_e32 v112, v216, v190
	v_fmac_f32_e32 v112, v217, v191
	v_fmac_f32_e32 v112, v218, v192
	v_fmac_f32_e32 v112, v219, v193
	v_fmac_f32_e32 v112, v220, v194
	v_fmac_f32_e32 v112, v221, v195
	v_fmac_f32_e32 v112, v222, v196
	v_fmac_f32_e32 v112, v223, v197
	v_fmac_f32_e32 v112, v224, v232
	v_fmac_f32_e32 v112, v225, v233
	v_fmac_f32_e32 v112, v226, v234
	v_fmac_f32_e32 v112, v227, v235
	v_fmac_f32_e32 v112, v228, v236
	v_fmac_f32_e32 v112, v229, v237
	v_fmac_f32_e32 v112, v230, v238
	v_fmac_f32_e32 v112, v231, v239
	ds_read_b128 v[190:193], v171 offset:13888
	ds_read_b128 v[194:197], v171 offset:13904
	ds_read_b128 v[232:235], v171 offset:13920
	ds_read_b128 v[236:239], v171 offset:13936
	s_waitcnt lgkmcnt(4)
	v_fmac_f32_e32 v113, v200, v174
	v_fmac_f32_e32 v113, v201, v175
	v_fmac_f32_e32 v113, v202, v176
	v_fmac_f32_e32 v113, v203, v177
	v_fmac_f32_e32 v113, v204, v178
	v_fmac_f32_e32 v113, v205, v179
	v_fmac_f32_e32 v113, v206, v180
	v_fmac_f32_e32 v113, v207, v181
	v_fmac_f32_e32 v113, v208, v182
	v_fmac_f32_e32 v113, v209, v183
	v_fmac_f32_e32 v113, v210, v184
	v_fmac_f32_e32 v113, v211, v185
	v_fmac_f32_e32 v113, v212, v186
	v_fmac_f32_e32 v113, v213, v187
	v_fmac_f32_e32 v113, v214, v188
	v_fmac_f32_e32 v113, v215, v189
	ds_read_b128 v[174:177], v171 offset:14336
	ds_read_b128 v[178:181], v171 offset:14352
	ds_read_b128 v[182:185], v171 offset:14368
	ds_read_b128 v[186:189], v171 offset:14384
	s_waitcnt lgkmcnt(4)
	v_fmac_f32_e32 v113, v216, v190
	v_fmac_f32_e32 v113, v217, v191
	v_fmac_f32_e32 v113, v218, v192
	v_fmac_f32_e32 v113, v219, v193
	v_fmac_f32_e32 v113, v220, v194
	v_fmac_f32_e32 v113, v221, v195
	v_fmac_f32_e32 v113, v222, v196
	v_fmac_f32_e32 v113, v223, v197
	v_fmac_f32_e32 v113, v224, v232
	v_fmac_f32_e32 v113, v225, v233
	v_fmac_f32_e32 v113, v226, v234
	v_fmac_f32_e32 v113, v227, v235
	v_fmac_f32_e32 v113, v228, v236
	v_fmac_f32_e32 v113, v229, v237
	v_fmac_f32_e32 v113, v230, v238
	v_fmac_f32_e32 v113, v231, v239
	ds_read_b128 v[190:193], v171 offset:14400
	ds_read_b128 v[194:197], v171 offset:14416
	ds_read_b128 v[232:235], v171 offset:14432
	ds_read_b128 v[236:239], v171 offset:14448
	s_waitcnt lgkmcnt(4)
	v_fmac_f32_e32 v110, v200, v174
	v_fmac_f32_e32 v110, v201, v175
	v_fmac_f32_e32 v110, v202, v176
	v_fmac_f32_e32 v110, v203, v177
	v_fmac_f32_e32 v110, v204, v178
	v_fmac_f32_e32 v110, v205, v179
	v_fmac_f32_e32 v110, v206, v180
	v_fmac_f32_e32 v110, v207, v181
	v_fmac_f32_e32 v110, v208, v182
	v_fmac_f32_e32 v110, v209, v183
	v_fmac_f32_e32 v110, v210, v184
	v_fmac_f32_e32 v110, v211, v185
	v_fmac_f32_e32 v110, v212, v186
	v_fmac_f32_e32 v110, v213, v187
	v_fmac_f32_e32 v110, v214, v188
	v_fmac_f32_e32 v110, v215, v189
	ds_read_b128 v[174:177], v171 offset:14848
	ds_read_b128 v[178:181], v171 offset:14864
	ds_read_b128 v[182:185], v171 offset:14880
	ds_read_b128 v[186:189], v171 offset:14896
	s_waitcnt lgkmcnt(4)
	v_fmac_f32_e32 v110, v216, v190
	v_fmac_f32_e32 v110, v217, v191
	v_fmac_f32_e32 v110, v218, v192
	v_fmac_f32_e32 v110, v219, v193
	v_fmac_f32_e32 v110, v220, v194
	v_fmac_f32_e32 v110, v221, v195
	v_fmac_f32_e32 v110, v222, v196
	v_fmac_f32_e32 v110, v223, v197
	v_fmac_f32_e32 v110, v224, v232
	v_fmac_f32_e32 v110, v225, v233
	v_fmac_f32_e32 v110, v226, v234
	v_fmac_f32_e32 v110, v227, v235
	v_fmac_f32_e32 v110, v228, v236
	v_fmac_f32_e32 v110, v229, v237
	v_fmac_f32_e32 v110, v230, v238
	v_fmac_f32_e32 v110, v231, v239
	ds_read_b128 v[190:193], v171 offset:14912
	ds_read_b128 v[194:197], v171 offset:14928
	ds_read_b128 v[232:235], v171 offset:14944
	ds_read_b128 v[236:239], v171 offset:14960
	s_waitcnt lgkmcnt(4)
	v_fmac_f32_e32 v111, v200, v174
	v_fmac_f32_e32 v111, v201, v175
	v_fmac_f32_e32 v111, v202, v176
	v_fmac_f32_e32 v111, v203, v177
	v_fmac_f32_e32 v111, v204, v178
	v_fmac_f32_e32 v111, v205, v179
	v_fmac_f32_e32 v111, v206, v180
	v_fmac_f32_e32 v111, v207, v181
	v_fmac_f32_e32 v111, v208, v182
	v_fmac_f32_e32 v111, v209, v183
	v_fmac_f32_e32 v111, v210, v184
	v_fmac_f32_e32 v111, v211, v185
	v_fmac_f32_e32 v111, v212, v186
	v_fmac_f32_e32 v111, v213, v187
	v_fmac_f32_e32 v111, v214, v188
	v_fmac_f32_e32 v111, v215, v189
	ds_read_b128 v[174:177], v171 offset:15360
	ds_read_b128 v[178:181], v171 offset:15376
	ds_read_b128 v[182:185], v171 offset:15392
	ds_read_b128 v[186:189], v171 offset:15408
	s_waitcnt lgkmcnt(4)
	v_fmac_f32_e32 v111, v216, v190
	v_fmac_f32_e32 v111, v217, v191
	v_fmac_f32_e32 v111, v218, v192
	v_fmac_f32_e32 v111, v219, v193
	v_fmac_f32_e32 v111, v220, v194
	v_fmac_f32_e32 v111, v221, v195
	v_fmac_f32_e32 v111, v222, v196
	v_fmac_f32_e32 v111, v223, v197
	v_fmac_f32_e32 v111, v224, v232
	v_fmac_f32_e32 v111, v225, v233
	v_fmac_f32_e32 v111, v226, v234
	v_fmac_f32_e32 v111, v227, v235
	v_fmac_f32_e32 v111, v228, v236
	v_fmac_f32_e32 v111, v229, v237
	v_fmac_f32_e32 v111, v230, v238
	v_fmac_f32_e32 v111, v231, v239
	ds_read_b128 v[190:193], v171 offset:15424
	ds_read_b128 v[194:197], v171 offset:15440
	ds_read_b128 v[232:235], v171 offset:15456
	ds_read_b128 v[236:239], v171 offset:15472
	s_waitcnt lgkmcnt(4)
	v_fmac_f32_e32 v34, v200, v174
	v_fmac_f32_e32 v34, v201, v175
	v_fmac_f32_e32 v34, v202, v176
	v_fmac_f32_e32 v34, v203, v177
	v_fmac_f32_e32 v34, v204, v178
	v_fmac_f32_e32 v34, v205, v179
	v_fmac_f32_e32 v34, v206, v180
	v_fmac_f32_e32 v34, v207, v181
	v_fmac_f32_e32 v34, v208, v182
	v_fmac_f32_e32 v34, v209, v183
	v_fmac_f32_e32 v34, v210, v184
	v_fmac_f32_e32 v34, v211, v185
	v_fmac_f32_e32 v34, v212, v186
	v_fmac_f32_e32 v34, v213, v187
	v_fmac_f32_e32 v34, v214, v188
	v_fmac_f32_e32 v34, v215, v189
	ds_read_b128 v[174:177], v171 offset:15872
	ds_read_b128 v[178:181], v171 offset:15888
	ds_read_b128 v[182:185], v171 offset:15904
	ds_read_b128 v[186:189], v171 offset:15920
	s_waitcnt lgkmcnt(4)
	v_fmac_f32_e32 v34, v216, v190
	v_fmac_f32_e32 v34, v217, v191
	v_fmac_f32_e32 v34, v218, v192
	v_fmac_f32_e32 v34, v219, v193
	v_fmac_f32_e32 v34, v220, v194
	v_fmac_f32_e32 v34, v221, v195
	v_fmac_f32_e32 v34, v222, v196
	v_fmac_f32_e32 v34, v223, v197
	v_fmac_f32_e32 v34, v224, v232
	v_fmac_f32_e32 v34, v225, v233
	v_fmac_f32_e32 v34, v226, v234
	v_fmac_f32_e32 v34, v227, v235
	v_fmac_f32_e32 v34, v228, v236
	v_fmac_f32_e32 v34, v229, v237
	v_fmac_f32_e32 v34, v230, v238
	v_fmac_f32_e32 v34, v231, v239
	ds_read_b128 v[190:193], v171 offset:15936
	ds_read_b128 v[194:197], v171 offset:15952
	ds_read_b128 v[232:235], v171 offset:15968
	ds_read_b128 v[236:239], v171 offset:15984
	s_waitcnt lgkmcnt(4)
	v_fmac_f32_e32 v35, v200, v174
	v_fmac_f32_e32 v35, v201, v175
	v_fmac_f32_e32 v35, v202, v176
	v_fmac_f32_e32 v35, v203, v177
	v_fmac_f32_e32 v35, v204, v178
	v_fmac_f32_e32 v35, v205, v179
	v_fmac_f32_e32 v35, v206, v180
	v_fmac_f32_e32 v35, v207, v181
	v_fmac_f32_e32 v35, v208, v182
	v_fmac_f32_e32 v35, v209, v183
	v_fmac_f32_e32 v35, v210, v184
	v_fmac_f32_e32 v35, v211, v185
	v_fmac_f32_e32 v35, v212, v186
	v_fmac_f32_e32 v35, v213, v187
	v_fmac_f32_e32 v35, v214, v188
	v_fmac_f32_e32 v35, v215, v189
	s_waitcnt lgkmcnt(0)
	v_fmac_f32_e32 v35, v216, v190
	v_fmac_f32_e32 v35, v217, v191
	v_fmac_f32_e32 v35, v218, v192
	v_fmac_f32_e32 v35, v219, v193
	v_fmac_f32_e32 v35, v220, v194
	v_fmac_f32_e32 v35, v221, v195
	v_fmac_f32_e32 v35, v222, v196
	v_fmac_f32_e32 v35, v223, v197
	v_fmac_f32_e32 v35, v224, v232
	v_fmac_f32_e32 v35, v225, v233
	v_fmac_f32_e32 v35, v226, v234
	v_fmac_f32_e32 v35, v227, v235
	v_fmac_f32_e32 v35, v228, v236
	v_fmac_f32_e32 v35, v229, v237
	v_fmac_f32_e32 v35, v230, v238
	v_fmac_f32_e32 v35, v231, v239
	global_load_dword v200, v[80:81], off
	v_lshl_add_u64 v[80:81], v[80:81], 0, s[58:59]
	global_load_dword v174, v97, s[14:15] offset:128
	global_load_dword v201, v[80:81], off
	v_lshl_add_u64 v[80:81], v[80:81], 0, s[58:59]
	global_load_dword v175, v97, s[14:15] offset:132
	global_load_dword v202, v[80:81], off
	v_lshl_add_u64 v[80:81], v[80:81], 0, s[58:59]
	global_load_dword v176, v97, s[14:15] offset:136
	global_load_dword v203, v[80:81], off
	v_lshl_add_u64 v[80:81], v[80:81], 0, s[58:59]
	global_load_dword v177, v97, s[14:15] offset:140
	global_load_dword v204, v[80:81], off
	v_lshl_add_u64 v[80:81], v[80:81], 0, s[58:59]
	global_load_dword v178, v97, s[14:15] offset:144
	global_load_dword v205, v[80:81], off
	v_lshl_add_u64 v[80:81], v[80:81], 0, s[58:59]
	global_load_dword v179, v97, s[14:15] offset:148
	global_load_dword v206, v[80:81], off
	v_lshl_add_u64 v[80:81], v[80:81], 0, s[58:59]
	global_load_dword v180, v97, s[14:15] offset:152
	global_load_dword v207, v[80:81], off
	v_lshl_add_u64 v[80:81], v[80:81], 0, s[58:59]
	global_load_dword v181, v97, s[14:15] offset:156
	global_load_dword v208, v[80:81], off
	v_lshl_add_u64 v[80:81], v[80:81], 0, s[58:59]
	global_load_dword v182, v97, s[14:15] offset:160
	global_load_dword v209, v[80:81], off
	v_lshl_add_u64 v[80:81], v[80:81], 0, s[58:59]
	global_load_dword v183, v97, s[14:15] offset:164
	global_load_dword v210, v[80:81], off
	v_lshl_add_u64 v[80:81], v[80:81], 0, s[58:59]
	global_load_dword v184, v97, s[14:15] offset:168
	global_load_dword v211, v[80:81], off
	v_lshl_add_u64 v[80:81], v[80:81], 0, s[58:59]
	global_load_dword v185, v97, s[14:15] offset:172
	global_load_dword v212, v[80:81], off
	v_lshl_add_u64 v[80:81], v[80:81], 0, s[58:59]
	global_load_dword v186, v97, s[14:15] offset:176
	global_load_dword v213, v[80:81], off
	v_lshl_add_u64 v[80:81], v[80:81], 0, s[58:59]
	global_load_dword v187, v97, s[14:15] offset:180
	global_load_dword v214, v[80:81], off
	v_lshl_add_u64 v[80:81], v[80:81], 0, s[58:59]
	global_load_dword v188, v97, s[14:15] offset:184
	global_load_dword v215, v[80:81], off
	v_lshl_add_u64 v[80:81], v[80:81], 0, s[58:59]
	global_load_dword v189, v97, s[14:15] offset:188
	s_waitcnt vmcnt(30)
	global_load_dword v216, v[80:81], off
	v_lshl_add_u64 v[80:81], v[80:81], 0, s[58:59]
	global_load_dword v190, v97, s[14:15] offset:192
	global_load_dword v217, v[80:81], off
	v_lshl_add_u64 v[80:81], v[80:81], 0, s[58:59]
	global_load_dword v191, v97, s[14:15] offset:196
	global_load_dword v218, v[80:81], off
	v_lshl_add_u64 v[80:81], v[80:81], 0, s[58:59]
	global_load_dword v192, v97, s[14:15] offset:200
	global_load_dword v219, v[80:81], off
	v_lshl_add_u64 v[80:81], v[80:81], 0, s[58:59]
	global_load_dword v193, v97, s[14:15] offset:204
	global_load_dword v220, v[80:81], off
	v_lshl_add_u64 v[80:81], v[80:81], 0, s[58:59]
	global_load_dword v194, v97, s[14:15] offset:208
	global_load_dword v221, v[80:81], off
	v_lshl_add_u64 v[80:81], v[80:81], 0, s[58:59]
	global_load_dword v195, v97, s[14:15] offset:212
	global_load_dword v222, v[80:81], off
	v_lshl_add_u64 v[80:81], v[80:81], 0, s[58:59]
	global_load_dword v196, v97, s[14:15] offset:216
	global_load_dword v223, v[80:81], off
	v_lshl_add_u64 v[80:81], v[80:81], 0, s[58:59]
	global_load_dword v197, v97, s[14:15] offset:220
	global_load_dword v224, v[80:81], off
	v_lshl_add_u64 v[80:81], v[80:81], 0, s[58:59]
	global_load_dword v232, v97, s[14:15] offset:224
	global_load_dword v225, v[80:81], off
	v_lshl_add_u64 v[80:81], v[80:81], 0, s[58:59]
	global_load_dword v233, v97, s[14:15] offset:228
	global_load_dword v226, v[80:81], off
	v_lshl_add_u64 v[80:81], v[80:81], 0, s[58:59]
	global_load_dword v234, v97, s[14:15] offset:232
	global_load_dword v227, v[80:81], off
	v_lshl_add_u64 v[80:81], v[80:81], 0, s[58:59]
	global_load_dword v235, v97, s[14:15] offset:236
	global_load_dword v228, v[80:81], off
	v_lshl_add_u64 v[80:81], v[80:81], 0, s[58:59]
	global_load_dword v236, v97, s[14:15] offset:240
	global_load_dword v229, v[80:81], off
	v_lshl_add_u64 v[80:81], v[80:81], 0, s[58:59]
	global_load_dword v237, v97, s[14:15] offset:244
	global_load_dword v230, v[80:81], off
	v_lshl_add_u64 v[80:81], v[80:81], 0, s[58:59]
	global_load_dword v238, v97, s[14:15] offset:248
	global_load_dword v231, v[80:81], off
	v_lshl_add_u64 v[80:81], v[80:81], 0, s[58:59]
	global_load_dword v239, v97, s[14:15] offset:252
	s_waitcnt vmcnt(0)
	v_mul_f32_e32 v200, v200, v174
	v_mul_f32_e32 v201, v201, v175
	v_mul_f32_e32 v202, v202, v176
	v_mul_f32_e32 v203, v203, v177
	v_mul_f32_e32 v204, v204, v178
	v_mul_f32_e32 v205, v205, v179
	v_mul_f32_e32 v206, v206, v180
	v_mul_f32_e32 v207, v207, v181
	v_mul_f32_e32 v208, v208, v182
	v_mul_f32_e32 v209, v209, v183
	v_mul_f32_e32 v210, v210, v184
	v_mul_f32_e32 v211, v211, v185
	v_mul_f32_e32 v212, v212, v186
	v_mul_f32_e32 v213, v213, v187
	v_mul_f32_e32 v214, v214, v188
	v_mul_f32_e32 v215, v215, v189
	v_mul_f32_e32 v216, v216, v190
	v_mul_f32_e32 v217, v217, v191
	v_mul_f32_e32 v218, v218, v192
	v_mul_f32_e32 v219, v219, v193
	v_mul_f32_e32 v220, v220, v194
	v_mul_f32_e32 v221, v221, v195
	v_mul_f32_e32 v222, v222, v196
	v_mul_f32_e32 v223, v223, v197
	v_mul_f32_e32 v224, v224, v232
	v_mul_f32_e32 v225, v225, v233
	v_mul_f32_e32 v226, v226, v234
	v_mul_f32_e32 v227, v227, v235
	v_mul_f32_e32 v228, v228, v236
	v_mul_f32_e32 v229, v229, v237
	v_mul_f32_e32 v230, v230, v238
	v_mul_f32_e32 v231, v231, v239
	ds_read_b128 v[174:177], v171 offset:128
	ds_read_b128 v[178:181], v171 offset:144
	ds_read_b128 v[182:185], v171 offset:160
	ds_read_b128 v[186:189], v171 offset:176
	ds_read_b128 v[190:193], v171 offset:192
	ds_read_b128 v[194:197], v171 offset:208
	ds_read_b128 v[232:235], v171 offset:224
	ds_read_b128 v[236:239], v171 offset:240
	s_waitcnt lgkmcnt(4)
	v_fmac_f32_e32 v82, v200, v174
	v_fmac_f32_e32 v82, v201, v175
	v_fmac_f32_e32 v82, v202, v176
	v_fmac_f32_e32 v82, v203, v177
	v_fmac_f32_e32 v82, v204, v178
	v_fmac_f32_e32 v82, v205, v179
	v_fmac_f32_e32 v82, v206, v180
	v_fmac_f32_e32 v82, v207, v181
	v_fmac_f32_e32 v82, v208, v182
	v_fmac_f32_e32 v82, v209, v183
	v_fmac_f32_e32 v82, v210, v184
	v_fmac_f32_e32 v82, v211, v185
	v_fmac_f32_e32 v82, v212, v186
	v_fmac_f32_e32 v82, v213, v187
	v_fmac_f32_e32 v82, v214, v188
	v_fmac_f32_e32 v82, v215, v189
	ds_read_b128 v[174:177], v171 offset:640
	ds_read_b128 v[178:181], v171 offset:656
	ds_read_b128 v[182:185], v171 offset:672
	ds_read_b128 v[186:189], v171 offset:688
	s_waitcnt lgkmcnt(4)
	v_fmac_f32_e32 v82, v216, v190
	v_fmac_f32_e32 v82, v217, v191
	v_fmac_f32_e32 v82, v218, v192
	v_fmac_f32_e32 v82, v219, v193
	v_fmac_f32_e32 v82, v220, v194
	v_fmac_f32_e32 v82, v221, v195
	v_fmac_f32_e32 v82, v222, v196
	v_fmac_f32_e32 v82, v223, v197
	v_fmac_f32_e32 v82, v224, v232
	v_fmac_f32_e32 v82, v225, v233
	v_fmac_f32_e32 v82, v226, v234
	v_fmac_f32_e32 v82, v227, v235
	v_fmac_f32_e32 v82, v228, v236
	v_fmac_f32_e32 v82, v229, v237
	v_fmac_f32_e32 v82, v230, v238
	v_fmac_f32_e32 v82, v231, v239
	ds_read_b128 v[190:193], v171 offset:704
	ds_read_b128 v[194:197], v171 offset:720
	ds_read_b128 v[232:235], v171 offset:736
	ds_read_b128 v[236:239], v171 offset:752
	s_waitcnt lgkmcnt(4)
	v_fmac_f32_e32 v83, v200, v174
	v_fmac_f32_e32 v83, v201, v175
	v_fmac_f32_e32 v83, v202, v176
	v_fmac_f32_e32 v83, v203, v177
	v_fmac_f32_e32 v83, v204, v178
	v_fmac_f32_e32 v83, v205, v179
	v_fmac_f32_e32 v83, v206, v180
	v_fmac_f32_e32 v83, v207, v181
	v_fmac_f32_e32 v83, v208, v182
	v_fmac_f32_e32 v83, v209, v183
	v_fmac_f32_e32 v83, v210, v184
	v_fmac_f32_e32 v83, v211, v185
	v_fmac_f32_e32 v83, v212, v186
	v_fmac_f32_e32 v83, v213, v187
	v_fmac_f32_e32 v83, v214, v188
	v_fmac_f32_e32 v83, v215, v189
	ds_read_b128 v[174:177], v171 offset:1152
	ds_read_b128 v[178:181], v171 offset:1168
	ds_read_b128 v[182:185], v171 offset:1184
	ds_read_b128 v[186:189], v171 offset:1200
	s_waitcnt lgkmcnt(4)
	v_fmac_f32_e32 v83, v216, v190
	v_fmac_f32_e32 v83, v217, v191
	v_fmac_f32_e32 v83, v218, v192
	v_fmac_f32_e32 v83, v219, v193
	v_fmac_f32_e32 v83, v220, v194
	v_fmac_f32_e32 v83, v221, v195
	v_fmac_f32_e32 v83, v222, v196
	v_fmac_f32_e32 v83, v223, v197
	v_fmac_f32_e32 v83, v224, v232
	v_fmac_f32_e32 v83, v225, v233
	v_fmac_f32_e32 v83, v226, v234
	v_fmac_f32_e32 v83, v227, v235
	v_fmac_f32_e32 v83, v228, v236
	v_fmac_f32_e32 v83, v229, v237
	v_fmac_f32_e32 v83, v230, v238
	v_fmac_f32_e32 v83, v231, v239
	ds_read_b128 v[190:193], v171 offset:1216
	ds_read_b128 v[194:197], v171 offset:1232
	ds_read_b128 v[232:235], v171 offset:1248
	ds_read_b128 v[236:239], v171 offset:1264
	s_waitcnt lgkmcnt(4)
	v_fmac_f32_e32 v86, v200, v174
	v_fmac_f32_e32 v86, v201, v175
	v_fmac_f32_e32 v86, v202, v176
	v_fmac_f32_e32 v86, v203, v177
	v_fmac_f32_e32 v86, v204, v178
	v_fmac_f32_e32 v86, v205, v179
	v_fmac_f32_e32 v86, v206, v180
	v_fmac_f32_e32 v86, v207, v181
	v_fmac_f32_e32 v86, v208, v182
	v_fmac_f32_e32 v86, v209, v183
	v_fmac_f32_e32 v86, v210, v184
	v_fmac_f32_e32 v86, v211, v185
	v_fmac_f32_e32 v86, v212, v186
	v_fmac_f32_e32 v86, v213, v187
	v_fmac_f32_e32 v86, v214, v188
	v_fmac_f32_e32 v86, v215, v189
	ds_read_b128 v[174:177], v171 offset:1664
	ds_read_b128 v[178:181], v171 offset:1680
	ds_read_b128 v[182:185], v171 offset:1696
	ds_read_b128 v[186:189], v171 offset:1712
	s_waitcnt lgkmcnt(4)
	v_fmac_f32_e32 v86, v216, v190
	v_fmac_f32_e32 v86, v217, v191
	v_fmac_f32_e32 v86, v218, v192
	v_fmac_f32_e32 v86, v219, v193
	v_fmac_f32_e32 v86, v220, v194
	v_fmac_f32_e32 v86, v221, v195
	v_fmac_f32_e32 v86, v222, v196
	v_fmac_f32_e32 v86, v223, v197
	v_fmac_f32_e32 v86, v224, v232
	v_fmac_f32_e32 v86, v225, v233
	v_fmac_f32_e32 v86, v226, v234
	v_fmac_f32_e32 v86, v227, v235
	v_fmac_f32_e32 v86, v228, v236
	v_fmac_f32_e32 v86, v229, v237
	v_fmac_f32_e32 v86, v230, v238
	v_fmac_f32_e32 v86, v231, v239
	ds_read_b128 v[190:193], v171 offset:1728
	ds_read_b128 v[194:197], v171 offset:1744
	ds_read_b128 v[232:235], v171 offset:1760
	ds_read_b128 v[236:239], v171 offset:1776
	s_waitcnt lgkmcnt(4)
	v_fmac_f32_e32 v87, v200, v174
	v_fmac_f32_e32 v87, v201, v175
	v_fmac_f32_e32 v87, v202, v176
	v_fmac_f32_e32 v87, v203, v177
	v_fmac_f32_e32 v87, v204, v178
	v_fmac_f32_e32 v87, v205, v179
	v_fmac_f32_e32 v87, v206, v180
	v_fmac_f32_e32 v87, v207, v181
	v_fmac_f32_e32 v87, v208, v182
	v_fmac_f32_e32 v87, v209, v183
	v_fmac_f32_e32 v87, v210, v184
	v_fmac_f32_e32 v87, v211, v185
	v_fmac_f32_e32 v87, v212, v186
	v_fmac_f32_e32 v87, v213, v187
	v_fmac_f32_e32 v87, v214, v188
	v_fmac_f32_e32 v87, v215, v189
	ds_read_b128 v[174:177], v171 offset:2176
	ds_read_b128 v[178:181], v171 offset:2192
	ds_read_b128 v[182:185], v171 offset:2208
	ds_read_b128 v[186:189], v171 offset:2224
	s_waitcnt lgkmcnt(4)
	v_fmac_f32_e32 v87, v216, v190
	v_fmac_f32_e32 v87, v217, v191
	v_fmac_f32_e32 v87, v218, v192
	v_fmac_f32_e32 v87, v219, v193
	v_fmac_f32_e32 v87, v220, v194
	v_fmac_f32_e32 v87, v221, v195
	v_fmac_f32_e32 v87, v222, v196
	v_fmac_f32_e32 v87, v223, v197
	v_fmac_f32_e32 v87, v224, v232
	v_fmac_f32_e32 v87, v225, v233
	v_fmac_f32_e32 v87, v226, v234
	v_fmac_f32_e32 v87, v227, v235
	v_fmac_f32_e32 v87, v228, v236
	v_fmac_f32_e32 v87, v229, v237
	v_fmac_f32_e32 v87, v230, v238
	v_fmac_f32_e32 v87, v231, v239
	ds_read_b128 v[190:193], v171 offset:2240
	ds_read_b128 v[194:197], v171 offset:2256
	ds_read_b128 v[232:235], v171 offset:2272
	ds_read_b128 v[236:239], v171 offset:2288
	s_waitcnt lgkmcnt(4)
	v_fmac_f32_e32 v84, v200, v174
	v_fmac_f32_e32 v84, v201, v175
	v_fmac_f32_e32 v84, v202, v176
	v_fmac_f32_e32 v84, v203, v177
	v_fmac_f32_e32 v84, v204, v178
	v_fmac_f32_e32 v84, v205, v179
	v_fmac_f32_e32 v84, v206, v180
	v_fmac_f32_e32 v84, v207, v181
	v_fmac_f32_e32 v84, v208, v182
	v_fmac_f32_e32 v84, v209, v183
	v_fmac_f32_e32 v84, v210, v184
	v_fmac_f32_e32 v84, v211, v185
	v_fmac_f32_e32 v84, v212, v186
	v_fmac_f32_e32 v84, v213, v187
	v_fmac_f32_e32 v84, v214, v188
	v_fmac_f32_e32 v84, v215, v189
	ds_read_b128 v[174:177], v171 offset:2688
	ds_read_b128 v[178:181], v171 offset:2704
	ds_read_b128 v[182:185], v171 offset:2720
	ds_read_b128 v[186:189], v171 offset:2736
	s_waitcnt lgkmcnt(4)
	v_fmac_f32_e32 v84, v216, v190
	v_fmac_f32_e32 v84, v217, v191
	v_fmac_f32_e32 v84, v218, v192
	v_fmac_f32_e32 v84, v219, v193
	v_fmac_f32_e32 v84, v220, v194
	v_fmac_f32_e32 v84, v221, v195
	v_fmac_f32_e32 v84, v222, v196
	v_fmac_f32_e32 v84, v223, v197
	v_fmac_f32_e32 v84, v224, v232
	v_fmac_f32_e32 v84, v225, v233
	v_fmac_f32_e32 v84, v226, v234
	v_fmac_f32_e32 v84, v227, v235
	v_fmac_f32_e32 v84, v228, v236
	v_fmac_f32_e32 v84, v229, v237
	v_fmac_f32_e32 v84, v230, v238
	v_fmac_f32_e32 v84, v231, v239
	ds_read_b128 v[190:193], v171 offset:2752
	ds_read_b128 v[194:197], v171 offset:2768
	ds_read_b128 v[232:235], v171 offset:2784
	ds_read_b128 v[236:239], v171 offset:2800
	s_waitcnt lgkmcnt(4)
	v_fmac_f32_e32 v85, v200, v174
	v_fmac_f32_e32 v85, v201, v175
	v_fmac_f32_e32 v85, v202, v176
	v_fmac_f32_e32 v85, v203, v177
	v_fmac_f32_e32 v85, v204, v178
	v_fmac_f32_e32 v85, v205, v179
	v_fmac_f32_e32 v85, v206, v180
	v_fmac_f32_e32 v85, v207, v181
	v_fmac_f32_e32 v85, v208, v182
	v_fmac_f32_e32 v85, v209, v183
	v_fmac_f32_e32 v85, v210, v184
	v_fmac_f32_e32 v85, v211, v185
	v_fmac_f32_e32 v85, v212, v186
	v_fmac_f32_e32 v85, v213, v187
	v_fmac_f32_e32 v85, v214, v188
	v_fmac_f32_e32 v85, v215, v189
	ds_read_b128 v[174:177], v171 offset:3200
	ds_read_b128 v[178:181], v171 offset:3216
	ds_read_b128 v[182:185], v171 offset:3232
	ds_read_b128 v[186:189], v171 offset:3248
	s_waitcnt lgkmcnt(4)
	v_fmac_f32_e32 v85, v216, v190
	v_fmac_f32_e32 v85, v217, v191
	v_fmac_f32_e32 v85, v218, v192
	v_fmac_f32_e32 v85, v219, v193
	v_fmac_f32_e32 v85, v220, v194
	v_fmac_f32_e32 v85, v221, v195
	v_fmac_f32_e32 v85, v222, v196
	v_fmac_f32_e32 v85, v223, v197
	v_fmac_f32_e32 v85, v224, v232
	v_fmac_f32_e32 v85, v225, v233
	v_fmac_f32_e32 v85, v226, v234
	v_fmac_f32_e32 v85, v227, v235
	v_fmac_f32_e32 v85, v228, v236
	v_fmac_f32_e32 v85, v229, v237
	v_fmac_f32_e32 v85, v230, v238
	v_fmac_f32_e32 v85, v231, v239
	ds_read_b128 v[190:193], v171 offset:3264
	ds_read_b128 v[194:197], v171 offset:3280
	ds_read_b128 v[232:235], v171 offset:3296
	ds_read_b128 v[236:239], v171 offset:3312
	s_waitcnt lgkmcnt(4)
	v_fmac_f32_e32 v90, v200, v174
	v_fmac_f32_e32 v90, v201, v175
	v_fmac_f32_e32 v90, v202, v176
	v_fmac_f32_e32 v90, v203, v177
	v_fmac_f32_e32 v90, v204, v178
	v_fmac_f32_e32 v90, v205, v179
	v_fmac_f32_e32 v90, v206, v180
	v_fmac_f32_e32 v90, v207, v181
	v_fmac_f32_e32 v90, v208, v182
	v_fmac_f32_e32 v90, v209, v183
	v_fmac_f32_e32 v90, v210, v184
	v_fmac_f32_e32 v90, v211, v185
	v_fmac_f32_e32 v90, v212, v186
	v_fmac_f32_e32 v90, v213, v187
	v_fmac_f32_e32 v90, v214, v188
	v_fmac_f32_e32 v90, v215, v189
	ds_read_b128 v[174:177], v171 offset:3712
	ds_read_b128 v[178:181], v171 offset:3728
	ds_read_b128 v[182:185], v171 offset:3744
	ds_read_b128 v[186:189], v171 offset:3760
	s_waitcnt lgkmcnt(4)
	v_fmac_f32_e32 v90, v216, v190
	v_fmac_f32_e32 v90, v217, v191
	v_fmac_f32_e32 v90, v218, v192
	v_fmac_f32_e32 v90, v219, v193
	v_fmac_f32_e32 v90, v220, v194
	v_fmac_f32_e32 v90, v221, v195
	v_fmac_f32_e32 v90, v222, v196
	v_fmac_f32_e32 v90, v223, v197
	v_fmac_f32_e32 v90, v224, v232
	v_fmac_f32_e32 v90, v225, v233
	v_fmac_f32_e32 v90, v226, v234
	v_fmac_f32_e32 v90, v227, v235
	v_fmac_f32_e32 v90, v228, v236
	v_fmac_f32_e32 v90, v229, v237
	v_fmac_f32_e32 v90, v230, v238
	v_fmac_f32_e32 v90, v231, v239
	ds_read_b128 v[190:193], v171 offset:3776
	ds_read_b128 v[194:197], v171 offset:3792
	ds_read_b128 v[232:235], v171 offset:3808
	ds_read_b128 v[236:239], v171 offset:3824
	s_waitcnt lgkmcnt(4)
	v_fmac_f32_e32 v91, v200, v174
	v_fmac_f32_e32 v91, v201, v175
	v_fmac_f32_e32 v91, v202, v176
	v_fmac_f32_e32 v91, v203, v177
	v_fmac_f32_e32 v91, v204, v178
	v_fmac_f32_e32 v91, v205, v179
	v_fmac_f32_e32 v91, v206, v180
	v_fmac_f32_e32 v91, v207, v181
	v_fmac_f32_e32 v91, v208, v182
	v_fmac_f32_e32 v91, v209, v183
	v_fmac_f32_e32 v91, v210, v184
	v_fmac_f32_e32 v91, v211, v185
	v_fmac_f32_e32 v91, v212, v186
	v_fmac_f32_e32 v91, v213, v187
	v_fmac_f32_e32 v91, v214, v188
	v_fmac_f32_e32 v91, v215, v189
	ds_read_b128 v[174:177], v171 offset:4224
	ds_read_b128 v[178:181], v171 offset:4240
	ds_read_b128 v[182:185], v171 offset:4256
	ds_read_b128 v[186:189], v171 offset:4272
	s_waitcnt lgkmcnt(4)
	v_fmac_f32_e32 v91, v216, v190
	v_fmac_f32_e32 v91, v217, v191
	v_fmac_f32_e32 v91, v218, v192
	v_fmac_f32_e32 v91, v219, v193
	v_fmac_f32_e32 v91, v220, v194
	v_fmac_f32_e32 v91, v221, v195
	v_fmac_f32_e32 v91, v222, v196
	v_fmac_f32_e32 v91, v223, v197
	v_fmac_f32_e32 v91, v224, v232
	v_fmac_f32_e32 v91, v225, v233
	v_fmac_f32_e32 v91, v226, v234
	v_fmac_f32_e32 v91, v227, v235
	v_fmac_f32_e32 v91, v228, v236
	v_fmac_f32_e32 v91, v229, v237
	v_fmac_f32_e32 v91, v230, v238
	v_fmac_f32_e32 v91, v231, v239
	ds_read_b128 v[190:193], v171 offset:4288
	ds_read_b128 v[194:197], v171 offset:4304
	ds_read_b128 v[232:235], v171 offset:4320
	ds_read_b128 v[236:239], v171 offset:4336
	s_waitcnt lgkmcnt(4)
	v_fmac_f32_e32 v88, v200, v174
	v_fmac_f32_e32 v88, v201, v175
	v_fmac_f32_e32 v88, v202, v176
	v_fmac_f32_e32 v88, v203, v177
	v_fmac_f32_e32 v88, v204, v178
	v_fmac_f32_e32 v88, v205, v179
	v_fmac_f32_e32 v88, v206, v180
	v_fmac_f32_e32 v88, v207, v181
	v_fmac_f32_e32 v88, v208, v182
	v_fmac_f32_e32 v88, v209, v183
	v_fmac_f32_e32 v88, v210, v184
	v_fmac_f32_e32 v88, v211, v185
	v_fmac_f32_e32 v88, v212, v186
	v_fmac_f32_e32 v88, v213, v187
	v_fmac_f32_e32 v88, v214, v188
	v_fmac_f32_e32 v88, v215, v189
	ds_read_b128 v[174:177], v171 offset:4736
	ds_read_b128 v[178:181], v171 offset:4752
	ds_read_b128 v[182:185], v171 offset:4768
	ds_read_b128 v[186:189], v171 offset:4784
	s_waitcnt lgkmcnt(4)
	v_fmac_f32_e32 v88, v216, v190
	v_fmac_f32_e32 v88, v217, v191
	v_fmac_f32_e32 v88, v218, v192
	v_fmac_f32_e32 v88, v219, v193
	v_fmac_f32_e32 v88, v220, v194
	v_fmac_f32_e32 v88, v221, v195
	v_fmac_f32_e32 v88, v222, v196
	v_fmac_f32_e32 v88, v223, v197
	v_fmac_f32_e32 v88, v224, v232
	v_fmac_f32_e32 v88, v225, v233
	v_fmac_f32_e32 v88, v226, v234
	v_fmac_f32_e32 v88, v227, v235
	v_fmac_f32_e32 v88, v228, v236
	v_fmac_f32_e32 v88, v229, v237
	v_fmac_f32_e32 v88, v230, v238
	v_fmac_f32_e32 v88, v231, v239
	ds_read_b128 v[190:193], v171 offset:4800
	ds_read_b128 v[194:197], v171 offset:4816
	ds_read_b128 v[232:235], v171 offset:4832
	ds_read_b128 v[236:239], v171 offset:4848
	s_waitcnt lgkmcnt(4)
	v_fmac_f32_e32 v89, v200, v174
	v_fmac_f32_e32 v89, v201, v175
	v_fmac_f32_e32 v89, v202, v176
	v_fmac_f32_e32 v89, v203, v177
	v_fmac_f32_e32 v89, v204, v178
	v_fmac_f32_e32 v89, v205, v179
	v_fmac_f32_e32 v89, v206, v180
	v_fmac_f32_e32 v89, v207, v181
	v_fmac_f32_e32 v89, v208, v182
	v_fmac_f32_e32 v89, v209, v183
	v_fmac_f32_e32 v89, v210, v184
	v_fmac_f32_e32 v89, v211, v185
	v_fmac_f32_e32 v89, v212, v186
	v_fmac_f32_e32 v89, v213, v187
	v_fmac_f32_e32 v89, v214, v188
	v_fmac_f32_e32 v89, v215, v189
	ds_read_b128 v[174:177], v171 offset:5248
	ds_read_b128 v[178:181], v171 offset:5264
	ds_read_b128 v[182:185], v171 offset:5280
	ds_read_b128 v[186:189], v171 offset:5296
	s_waitcnt lgkmcnt(4)
	v_fmac_f32_e32 v89, v216, v190
	v_fmac_f32_e32 v89, v217, v191
	v_fmac_f32_e32 v89, v218, v192
	v_fmac_f32_e32 v89, v219, v193
	v_fmac_f32_e32 v89, v220, v194
	v_fmac_f32_e32 v89, v221, v195
	v_fmac_f32_e32 v89, v222, v196
	v_fmac_f32_e32 v89, v223, v197
	v_fmac_f32_e32 v89, v224, v232
	v_fmac_f32_e32 v89, v225, v233
	v_fmac_f32_e32 v89, v226, v234
	v_fmac_f32_e32 v89, v227, v235
	v_fmac_f32_e32 v89, v228, v236
	v_fmac_f32_e32 v89, v229, v237
	v_fmac_f32_e32 v89, v230, v238
	v_fmac_f32_e32 v89, v231, v239
	ds_read_b128 v[190:193], v171 offset:5312
	ds_read_b128 v[194:197], v171 offset:5328
	ds_read_b128 v[232:235], v171 offset:5344
	ds_read_b128 v[236:239], v171 offset:5360
	s_waitcnt lgkmcnt(4)
	v_fmac_f32_e32 v94, v200, v174
	v_fmac_f32_e32 v94, v201, v175
	v_fmac_f32_e32 v94, v202, v176
	v_fmac_f32_e32 v94, v203, v177
	v_fmac_f32_e32 v94, v204, v178
	v_fmac_f32_e32 v94, v205, v179
	v_fmac_f32_e32 v94, v206, v180
	v_fmac_f32_e32 v94, v207, v181
	v_fmac_f32_e32 v94, v208, v182
	v_fmac_f32_e32 v94, v209, v183
	v_fmac_f32_e32 v94, v210, v184
	v_fmac_f32_e32 v94, v211, v185
	v_fmac_f32_e32 v94, v212, v186
	v_fmac_f32_e32 v94, v213, v187
	v_fmac_f32_e32 v94, v214, v188
	v_fmac_f32_e32 v94, v215, v189
	ds_read_b128 v[174:177], v171 offset:5760
	ds_read_b128 v[178:181], v171 offset:5776
	ds_read_b128 v[182:185], v171 offset:5792
	ds_read_b128 v[186:189], v171 offset:5808
	s_waitcnt lgkmcnt(4)
	v_fmac_f32_e32 v94, v216, v190
	v_fmac_f32_e32 v94, v217, v191
	v_fmac_f32_e32 v94, v218, v192
	v_fmac_f32_e32 v94, v219, v193
	v_fmac_f32_e32 v94, v220, v194
	v_fmac_f32_e32 v94, v221, v195
	v_fmac_f32_e32 v94, v222, v196
	v_fmac_f32_e32 v94, v223, v197
	v_fmac_f32_e32 v94, v224, v232
	v_fmac_f32_e32 v94, v225, v233
	v_fmac_f32_e32 v94, v226, v234
	v_fmac_f32_e32 v94, v227, v235
	v_fmac_f32_e32 v94, v228, v236
	v_fmac_f32_e32 v94, v229, v237
	v_fmac_f32_e32 v94, v230, v238
	v_fmac_f32_e32 v94, v231, v239
	ds_read_b128 v[190:193], v171 offset:5824
	ds_read_b128 v[194:197], v171 offset:5840
	ds_read_b128 v[232:235], v171 offset:5856
	ds_read_b128 v[236:239], v171 offset:5872
	s_waitcnt lgkmcnt(4)
	v_fmac_f32_e32 v95, v200, v174
	v_fmac_f32_e32 v95, v201, v175
	v_fmac_f32_e32 v95, v202, v176
	v_fmac_f32_e32 v95, v203, v177
	v_fmac_f32_e32 v95, v204, v178
	v_fmac_f32_e32 v95, v205, v179
	v_fmac_f32_e32 v95, v206, v180
	v_fmac_f32_e32 v95, v207, v181
	v_fmac_f32_e32 v95, v208, v182
	v_fmac_f32_e32 v95, v209, v183
	v_fmac_f32_e32 v95, v210, v184
	v_fmac_f32_e32 v95, v211, v185
	v_fmac_f32_e32 v95, v212, v186
	v_fmac_f32_e32 v95, v213, v187
	v_fmac_f32_e32 v95, v214, v188
	v_fmac_f32_e32 v95, v215, v189
	ds_read_b128 v[174:177], v171 offset:6272
	ds_read_b128 v[178:181], v171 offset:6288
	ds_read_b128 v[182:185], v171 offset:6304
	ds_read_b128 v[186:189], v171 offset:6320
	s_waitcnt lgkmcnt(4)
	v_fmac_f32_e32 v95, v216, v190
	v_fmac_f32_e32 v95, v217, v191
	v_fmac_f32_e32 v95, v218, v192
	v_fmac_f32_e32 v95, v219, v193
	v_fmac_f32_e32 v95, v220, v194
	v_fmac_f32_e32 v95, v221, v195
	v_fmac_f32_e32 v95, v222, v196
	v_fmac_f32_e32 v95, v223, v197
	v_fmac_f32_e32 v95, v224, v232
	v_fmac_f32_e32 v95, v225, v233
	v_fmac_f32_e32 v95, v226, v234
	v_fmac_f32_e32 v95, v227, v235
	v_fmac_f32_e32 v95, v228, v236
	v_fmac_f32_e32 v95, v229, v237
	v_fmac_f32_e32 v95, v230, v238
	v_fmac_f32_e32 v95, v231, v239
	ds_read_b128 v[190:193], v171 offset:6336
	ds_read_b128 v[194:197], v171 offset:6352
	ds_read_b128 v[232:235], v171 offset:6368
	ds_read_b128 v[236:239], v171 offset:6384
	s_waitcnt lgkmcnt(4)
	v_fmac_f32_e32 v92, v200, v174
	v_fmac_f32_e32 v92, v201, v175
	v_fmac_f32_e32 v92, v202, v176
	v_fmac_f32_e32 v92, v203, v177
	v_fmac_f32_e32 v92, v204, v178
	v_fmac_f32_e32 v92, v205, v179
	v_fmac_f32_e32 v92, v206, v180
	v_fmac_f32_e32 v92, v207, v181
	v_fmac_f32_e32 v92, v208, v182
	v_fmac_f32_e32 v92, v209, v183
	v_fmac_f32_e32 v92, v210, v184
	v_fmac_f32_e32 v92, v211, v185
	v_fmac_f32_e32 v92, v212, v186
	v_fmac_f32_e32 v92, v213, v187
	v_fmac_f32_e32 v92, v214, v188
	v_fmac_f32_e32 v92, v215, v189
	ds_read_b128 v[174:177], v171 offset:6784
	ds_read_b128 v[178:181], v171 offset:6800
	ds_read_b128 v[182:185], v171 offset:6816
	ds_read_b128 v[186:189], v171 offset:6832
	s_waitcnt lgkmcnt(4)
	v_fmac_f32_e32 v92, v216, v190
	v_fmac_f32_e32 v92, v217, v191
	v_fmac_f32_e32 v92, v218, v192
	v_fmac_f32_e32 v92, v219, v193
	v_fmac_f32_e32 v92, v220, v194
	v_fmac_f32_e32 v92, v221, v195
	v_fmac_f32_e32 v92, v222, v196
	v_fmac_f32_e32 v92, v223, v197
	v_fmac_f32_e32 v92, v224, v232
	v_fmac_f32_e32 v92, v225, v233
	v_fmac_f32_e32 v92, v226, v234
	v_fmac_f32_e32 v92, v227, v235
	v_fmac_f32_e32 v92, v228, v236
	v_fmac_f32_e32 v92, v229, v237
	v_fmac_f32_e32 v92, v230, v238
	v_fmac_f32_e32 v92, v231, v239
	ds_read_b128 v[190:193], v171 offset:6848
	ds_read_b128 v[194:197], v171 offset:6864
	ds_read_b128 v[232:235], v171 offset:6880
	ds_read_b128 v[236:239], v171 offset:6896
	s_waitcnt lgkmcnt(4)
	v_fmac_f32_e32 v93, v200, v174
	v_fmac_f32_e32 v93, v201, v175
	v_fmac_f32_e32 v93, v202, v176
	v_fmac_f32_e32 v93, v203, v177
	v_fmac_f32_e32 v93, v204, v178
	v_fmac_f32_e32 v93, v205, v179
	v_fmac_f32_e32 v93, v206, v180
	v_fmac_f32_e32 v93, v207, v181
	v_fmac_f32_e32 v93, v208, v182
	v_fmac_f32_e32 v93, v209, v183
	v_fmac_f32_e32 v93, v210, v184
	v_fmac_f32_e32 v93, v211, v185
	v_fmac_f32_e32 v93, v212, v186
	v_fmac_f32_e32 v93, v213, v187
	v_fmac_f32_e32 v93, v214, v188
	v_fmac_f32_e32 v93, v215, v189
	ds_read_b128 v[174:177], v171 offset:7296
	ds_read_b128 v[178:181], v171 offset:7312
	ds_read_b128 v[182:185], v171 offset:7328
	ds_read_b128 v[186:189], v171 offset:7344
	s_waitcnt lgkmcnt(4)
	v_fmac_f32_e32 v93, v216, v190
	v_fmac_f32_e32 v93, v217, v191
	v_fmac_f32_e32 v93, v218, v192
	v_fmac_f32_e32 v93, v219, v193
	v_fmac_f32_e32 v93, v220, v194
	v_fmac_f32_e32 v93, v221, v195
	v_fmac_f32_e32 v93, v222, v196
	v_fmac_f32_e32 v93, v223, v197
	v_fmac_f32_e32 v93, v224, v232
	v_fmac_f32_e32 v93, v225, v233
	v_fmac_f32_e32 v93, v226, v234
	v_fmac_f32_e32 v93, v227, v235
	v_fmac_f32_e32 v93, v228, v236
	v_fmac_f32_e32 v93, v229, v237
	v_fmac_f32_e32 v93, v230, v238
	v_fmac_f32_e32 v93, v231, v239
	ds_read_b128 v[190:193], v171 offset:7360
	ds_read_b128 v[194:197], v171 offset:7376
	ds_read_b128 v[232:235], v171 offset:7392
	ds_read_b128 v[236:239], v171 offset:7408
	s_waitcnt lgkmcnt(4)
	v_fmac_f32_e32 v100, v200, v174
	v_fmac_f32_e32 v100, v201, v175
	v_fmac_f32_e32 v100, v202, v176
	v_fmac_f32_e32 v100, v203, v177
	v_fmac_f32_e32 v100, v204, v178
	v_fmac_f32_e32 v100, v205, v179
	v_fmac_f32_e32 v100, v206, v180
	v_fmac_f32_e32 v100, v207, v181
	v_fmac_f32_e32 v100, v208, v182
	v_fmac_f32_e32 v100, v209, v183
	v_fmac_f32_e32 v100, v210, v184
	v_fmac_f32_e32 v100, v211, v185
	v_fmac_f32_e32 v100, v212, v186
	v_fmac_f32_e32 v100, v213, v187
	v_fmac_f32_e32 v100, v214, v188
	v_fmac_f32_e32 v100, v215, v189
	ds_read_b128 v[174:177], v171 offset:7808
	ds_read_b128 v[178:181], v171 offset:7824
	ds_read_b128 v[182:185], v171 offset:7840
	ds_read_b128 v[186:189], v171 offset:7856
	s_waitcnt lgkmcnt(4)
	v_fmac_f32_e32 v100, v216, v190
	v_fmac_f32_e32 v100, v217, v191
	v_fmac_f32_e32 v100, v218, v192
	v_fmac_f32_e32 v100, v219, v193
	v_fmac_f32_e32 v100, v220, v194
	v_fmac_f32_e32 v100, v221, v195
	v_fmac_f32_e32 v100, v222, v196
	v_fmac_f32_e32 v100, v223, v197
	v_fmac_f32_e32 v100, v224, v232
	v_fmac_f32_e32 v100, v225, v233
	v_fmac_f32_e32 v100, v226, v234
	v_fmac_f32_e32 v100, v227, v235
	v_fmac_f32_e32 v100, v228, v236
	v_fmac_f32_e32 v100, v229, v237
	v_fmac_f32_e32 v100, v230, v238
	v_fmac_f32_e32 v100, v231, v239
	ds_read_b128 v[190:193], v171 offset:7872
	ds_read_b128 v[194:197], v171 offset:7888
	ds_read_b128 v[232:235], v171 offset:7904
	ds_read_b128 v[236:239], v171 offset:7920
	s_waitcnt lgkmcnt(4)
	v_fmac_f32_e32 v101, v200, v174
	v_fmac_f32_e32 v101, v201, v175
	v_fmac_f32_e32 v101, v202, v176
	v_fmac_f32_e32 v101, v203, v177
	v_fmac_f32_e32 v101, v204, v178
	v_fmac_f32_e32 v101, v205, v179
	v_fmac_f32_e32 v101, v206, v180
	v_fmac_f32_e32 v101, v207, v181
	v_fmac_f32_e32 v101, v208, v182
	v_fmac_f32_e32 v101, v209, v183
	v_fmac_f32_e32 v101, v210, v184
	v_fmac_f32_e32 v101, v211, v185
	v_fmac_f32_e32 v101, v212, v186
	v_fmac_f32_e32 v101, v213, v187
	v_fmac_f32_e32 v101, v214, v188
	v_fmac_f32_e32 v101, v215, v189
	ds_read_b128 v[174:177], v171 offset:8320
	ds_read_b128 v[178:181], v171 offset:8336
	ds_read_b128 v[182:185], v171 offset:8352
	ds_read_b128 v[186:189], v171 offset:8368
	s_waitcnt lgkmcnt(4)
	v_fmac_f32_e32 v101, v216, v190
	v_fmac_f32_e32 v101, v217, v191
	v_fmac_f32_e32 v101, v218, v192
	v_fmac_f32_e32 v101, v219, v193
	v_fmac_f32_e32 v101, v220, v194
	v_fmac_f32_e32 v101, v221, v195
	v_fmac_f32_e32 v101, v222, v196
	v_fmac_f32_e32 v101, v223, v197
	v_fmac_f32_e32 v101, v224, v232
	v_fmac_f32_e32 v101, v225, v233
	v_fmac_f32_e32 v101, v226, v234
	v_fmac_f32_e32 v101, v227, v235
	v_fmac_f32_e32 v101, v228, v236
	v_fmac_f32_e32 v101, v229, v237
	v_fmac_f32_e32 v101, v230, v238
	v_fmac_f32_e32 v101, v231, v239
	ds_read_b128 v[190:193], v171 offset:8384
	ds_read_b128 v[194:197], v171 offset:8400
	ds_read_b128 v[232:235], v171 offset:8416
	ds_read_b128 v[236:239], v171 offset:8432
	s_waitcnt lgkmcnt(4)
	v_fmac_f32_e32 v98, v200, v174
	v_fmac_f32_e32 v98, v201, v175
	v_fmac_f32_e32 v98, v202, v176
	v_fmac_f32_e32 v98, v203, v177
	v_fmac_f32_e32 v98, v204, v178
	v_fmac_f32_e32 v98, v205, v179
	v_fmac_f32_e32 v98, v206, v180
	v_fmac_f32_e32 v98, v207, v181
	v_fmac_f32_e32 v98, v208, v182
	v_fmac_f32_e32 v98, v209, v183
	v_fmac_f32_e32 v98, v210, v184
	v_fmac_f32_e32 v98, v211, v185
	v_fmac_f32_e32 v98, v212, v186
	v_fmac_f32_e32 v98, v213, v187
	v_fmac_f32_e32 v98, v214, v188
	v_fmac_f32_e32 v98, v215, v189
	ds_read_b128 v[174:177], v171 offset:8832
	ds_read_b128 v[178:181], v171 offset:8848
	ds_read_b128 v[182:185], v171 offset:8864
	ds_read_b128 v[186:189], v171 offset:8880
	s_waitcnt lgkmcnt(4)
	v_fmac_f32_e32 v98, v216, v190
	v_fmac_f32_e32 v98, v217, v191
	v_fmac_f32_e32 v98, v218, v192
	v_fmac_f32_e32 v98, v219, v193
	v_fmac_f32_e32 v98, v220, v194
	v_fmac_f32_e32 v98, v221, v195
	v_fmac_f32_e32 v98, v222, v196
	v_fmac_f32_e32 v98, v223, v197
	v_fmac_f32_e32 v98, v224, v232
	v_fmac_f32_e32 v98, v225, v233
	v_fmac_f32_e32 v98, v226, v234
	v_fmac_f32_e32 v98, v227, v235
	v_fmac_f32_e32 v98, v228, v236
	v_fmac_f32_e32 v98, v229, v237
	v_fmac_f32_e32 v98, v230, v238
	v_fmac_f32_e32 v98, v231, v239
	ds_read_b128 v[190:193], v171 offset:8896
	ds_read_b128 v[194:197], v171 offset:8912
	ds_read_b128 v[232:235], v171 offset:8928
	ds_read_b128 v[236:239], v171 offset:8944
	s_waitcnt lgkmcnt(4)
	v_fmac_f32_e32 v99, v200, v174
	v_fmac_f32_e32 v99, v201, v175
	v_fmac_f32_e32 v99, v202, v176
	v_fmac_f32_e32 v99, v203, v177
	v_fmac_f32_e32 v99, v204, v178
	v_fmac_f32_e32 v99, v205, v179
	v_fmac_f32_e32 v99, v206, v180
	v_fmac_f32_e32 v99, v207, v181
	v_fmac_f32_e32 v99, v208, v182
	v_fmac_f32_e32 v99, v209, v183
	v_fmac_f32_e32 v99, v210, v184
	v_fmac_f32_e32 v99, v211, v185
	v_fmac_f32_e32 v99, v212, v186
	v_fmac_f32_e32 v99, v213, v187
	v_fmac_f32_e32 v99, v214, v188
	v_fmac_f32_e32 v99, v215, v189
	ds_read_b128 v[174:177], v171 offset:9344
	ds_read_b128 v[178:181], v171 offset:9360
	ds_read_b128 v[182:185], v171 offset:9376
	ds_read_b128 v[186:189], v171 offset:9392
	s_waitcnt lgkmcnt(4)
	v_fmac_f32_e32 v99, v216, v190
	v_fmac_f32_e32 v99, v217, v191
	v_fmac_f32_e32 v99, v218, v192
	v_fmac_f32_e32 v99, v219, v193
	v_fmac_f32_e32 v99, v220, v194
	v_fmac_f32_e32 v99, v221, v195
	v_fmac_f32_e32 v99, v222, v196
	v_fmac_f32_e32 v99, v223, v197
	v_fmac_f32_e32 v99, v224, v232
	v_fmac_f32_e32 v99, v225, v233
	v_fmac_f32_e32 v99, v226, v234
	v_fmac_f32_e32 v99, v227, v235
	v_fmac_f32_e32 v99, v228, v236
	v_fmac_f32_e32 v99, v229, v237
	v_fmac_f32_e32 v99, v230, v238
	v_fmac_f32_e32 v99, v231, v239
	ds_read_b128 v[190:193], v171 offset:9408
	ds_read_b128 v[194:197], v171 offset:9424
	ds_read_b128 v[232:235], v171 offset:9440
	ds_read_b128 v[236:239], v171 offset:9456
	s_waitcnt lgkmcnt(4)
	v_fmac_f32_e32 v104, v200, v174
	v_fmac_f32_e32 v104, v201, v175
	v_fmac_f32_e32 v104, v202, v176
	v_fmac_f32_e32 v104, v203, v177
	v_fmac_f32_e32 v104, v204, v178
	v_fmac_f32_e32 v104, v205, v179
	v_fmac_f32_e32 v104, v206, v180
	v_fmac_f32_e32 v104, v207, v181
	v_fmac_f32_e32 v104, v208, v182
	v_fmac_f32_e32 v104, v209, v183
	v_fmac_f32_e32 v104, v210, v184
	v_fmac_f32_e32 v104, v211, v185
	v_fmac_f32_e32 v104, v212, v186
	v_fmac_f32_e32 v104, v213, v187
	v_fmac_f32_e32 v104, v214, v188
	v_fmac_f32_e32 v104, v215, v189
	ds_read_b128 v[174:177], v171 offset:9856
	ds_read_b128 v[178:181], v171 offset:9872
	ds_read_b128 v[182:185], v171 offset:9888
	ds_read_b128 v[186:189], v171 offset:9904
	s_waitcnt lgkmcnt(4)
	v_fmac_f32_e32 v104, v216, v190
	v_fmac_f32_e32 v104, v217, v191
	v_fmac_f32_e32 v104, v218, v192
	v_fmac_f32_e32 v104, v219, v193
	v_fmac_f32_e32 v104, v220, v194
	v_fmac_f32_e32 v104, v221, v195
	v_fmac_f32_e32 v104, v222, v196
	v_fmac_f32_e32 v104, v223, v197
	v_fmac_f32_e32 v104, v224, v232
	v_fmac_f32_e32 v104, v225, v233
	v_fmac_f32_e32 v104, v226, v234
	v_fmac_f32_e32 v104, v227, v235
	v_fmac_f32_e32 v104, v228, v236
	v_fmac_f32_e32 v104, v229, v237
	v_fmac_f32_e32 v104, v230, v238
	v_fmac_f32_e32 v104, v231, v239
	ds_read_b128 v[190:193], v171 offset:9920
	ds_read_b128 v[194:197], v171 offset:9936
	ds_read_b128 v[232:235], v171 offset:9952
	ds_read_b128 v[236:239], v171 offset:9968
	s_waitcnt lgkmcnt(4)
	v_fmac_f32_e32 v105, v200, v174
	v_fmac_f32_e32 v105, v201, v175
	v_fmac_f32_e32 v105, v202, v176
	v_fmac_f32_e32 v105, v203, v177
	v_fmac_f32_e32 v105, v204, v178
	v_fmac_f32_e32 v105, v205, v179
	v_fmac_f32_e32 v105, v206, v180
	v_fmac_f32_e32 v105, v207, v181
	v_fmac_f32_e32 v105, v208, v182
	v_fmac_f32_e32 v105, v209, v183
	v_fmac_f32_e32 v105, v210, v184
	v_fmac_f32_e32 v105, v211, v185
	v_fmac_f32_e32 v105, v212, v186
	v_fmac_f32_e32 v105, v213, v187
	v_fmac_f32_e32 v105, v214, v188
	v_fmac_f32_e32 v105, v215, v189
	ds_read_b128 v[174:177], v171 offset:10368
	ds_read_b128 v[178:181], v171 offset:10384
	ds_read_b128 v[182:185], v171 offset:10400
	ds_read_b128 v[186:189], v171 offset:10416
	s_waitcnt lgkmcnt(4)
	v_fmac_f32_e32 v105, v216, v190
	v_fmac_f32_e32 v105, v217, v191
	v_fmac_f32_e32 v105, v218, v192
	v_fmac_f32_e32 v105, v219, v193
	v_fmac_f32_e32 v105, v220, v194
	v_fmac_f32_e32 v105, v221, v195
	v_fmac_f32_e32 v105, v222, v196
	v_fmac_f32_e32 v105, v223, v197
	v_fmac_f32_e32 v105, v224, v232
	v_fmac_f32_e32 v105, v225, v233
	v_fmac_f32_e32 v105, v226, v234
	v_fmac_f32_e32 v105, v227, v235
	v_fmac_f32_e32 v105, v228, v236
	v_fmac_f32_e32 v105, v229, v237
	v_fmac_f32_e32 v105, v230, v238
	v_fmac_f32_e32 v105, v231, v239
	ds_read_b128 v[190:193], v171 offset:10432
	ds_read_b128 v[194:197], v171 offset:10448
	ds_read_b128 v[232:235], v171 offset:10464
	ds_read_b128 v[236:239], v171 offset:10480
	s_waitcnt lgkmcnt(4)
	v_fmac_f32_e32 v102, v200, v174
	v_fmac_f32_e32 v102, v201, v175
	v_fmac_f32_e32 v102, v202, v176
	v_fmac_f32_e32 v102, v203, v177
	v_fmac_f32_e32 v102, v204, v178
	v_fmac_f32_e32 v102, v205, v179
	v_fmac_f32_e32 v102, v206, v180
	v_fmac_f32_e32 v102, v207, v181
	v_fmac_f32_e32 v102, v208, v182
	v_fmac_f32_e32 v102, v209, v183
	v_fmac_f32_e32 v102, v210, v184
	v_fmac_f32_e32 v102, v211, v185
	v_fmac_f32_e32 v102, v212, v186
	v_fmac_f32_e32 v102, v213, v187
	v_fmac_f32_e32 v102, v214, v188
	v_fmac_f32_e32 v102, v215, v189
	ds_read_b128 v[174:177], v171 offset:10880
	ds_read_b128 v[178:181], v171 offset:10896
	ds_read_b128 v[182:185], v171 offset:10912
	ds_read_b128 v[186:189], v171 offset:10928
	s_waitcnt lgkmcnt(4)
	v_fmac_f32_e32 v102, v216, v190
	v_fmac_f32_e32 v102, v217, v191
	v_fmac_f32_e32 v102, v218, v192
	v_fmac_f32_e32 v102, v219, v193
	v_fmac_f32_e32 v102, v220, v194
	v_fmac_f32_e32 v102, v221, v195
	v_fmac_f32_e32 v102, v222, v196
	v_fmac_f32_e32 v102, v223, v197
	v_fmac_f32_e32 v102, v224, v232
	v_fmac_f32_e32 v102, v225, v233
	v_fmac_f32_e32 v102, v226, v234
	v_fmac_f32_e32 v102, v227, v235
	v_fmac_f32_e32 v102, v228, v236
	v_fmac_f32_e32 v102, v229, v237
	v_fmac_f32_e32 v102, v230, v238
	v_fmac_f32_e32 v102, v231, v239
	ds_read_b128 v[190:193], v171 offset:10944
	ds_read_b128 v[194:197], v171 offset:10960
	ds_read_b128 v[232:235], v171 offset:10976
	ds_read_b128 v[236:239], v171 offset:10992
	s_waitcnt lgkmcnt(4)
	v_fmac_f32_e32 v103, v200, v174
	v_fmac_f32_e32 v103, v201, v175
	v_fmac_f32_e32 v103, v202, v176
	v_fmac_f32_e32 v103, v203, v177
	v_fmac_f32_e32 v103, v204, v178
	v_fmac_f32_e32 v103, v205, v179
	v_fmac_f32_e32 v103, v206, v180
	v_fmac_f32_e32 v103, v207, v181
	v_fmac_f32_e32 v103, v208, v182
	v_fmac_f32_e32 v103, v209, v183
	v_fmac_f32_e32 v103, v210, v184
	v_fmac_f32_e32 v103, v211, v185
	v_fmac_f32_e32 v103, v212, v186
	v_fmac_f32_e32 v103, v213, v187
	v_fmac_f32_e32 v103, v214, v188
	v_fmac_f32_e32 v103, v215, v189
	ds_read_b128 v[174:177], v171 offset:11392
	ds_read_b128 v[178:181], v171 offset:11408
	ds_read_b128 v[182:185], v171 offset:11424
	ds_read_b128 v[186:189], v171 offset:11440
	s_waitcnt lgkmcnt(4)
	v_fmac_f32_e32 v103, v216, v190
	v_fmac_f32_e32 v103, v217, v191
	v_fmac_f32_e32 v103, v218, v192
	v_fmac_f32_e32 v103, v219, v193
	v_fmac_f32_e32 v103, v220, v194
	v_fmac_f32_e32 v103, v221, v195
	v_fmac_f32_e32 v103, v222, v196
	v_fmac_f32_e32 v103, v223, v197
	v_fmac_f32_e32 v103, v224, v232
	v_fmac_f32_e32 v103, v225, v233
	v_fmac_f32_e32 v103, v226, v234
	v_fmac_f32_e32 v103, v227, v235
	v_fmac_f32_e32 v103, v228, v236
	v_fmac_f32_e32 v103, v229, v237
	v_fmac_f32_e32 v103, v230, v238
	v_fmac_f32_e32 v103, v231, v239
	ds_read_b128 v[190:193], v171 offset:11456
	ds_read_b128 v[194:197], v171 offset:11472
	ds_read_b128 v[232:235], v171 offset:11488
	ds_read_b128 v[236:239], v171 offset:11504
	s_waitcnt lgkmcnt(4)
	v_fmac_f32_e32 v108, v200, v174
	v_fmac_f32_e32 v108, v201, v175
	v_fmac_f32_e32 v108, v202, v176
	v_fmac_f32_e32 v108, v203, v177
	v_fmac_f32_e32 v108, v204, v178
	v_fmac_f32_e32 v108, v205, v179
	v_fmac_f32_e32 v108, v206, v180
	v_fmac_f32_e32 v108, v207, v181
	v_fmac_f32_e32 v108, v208, v182
	v_fmac_f32_e32 v108, v209, v183
	v_fmac_f32_e32 v108, v210, v184
	v_fmac_f32_e32 v108, v211, v185
	v_fmac_f32_e32 v108, v212, v186
	v_fmac_f32_e32 v108, v213, v187
	v_fmac_f32_e32 v108, v214, v188
	v_fmac_f32_e32 v108, v215, v189
	ds_read_b128 v[174:177], v171 offset:11904
	ds_read_b128 v[178:181], v171 offset:11920
	ds_read_b128 v[182:185], v171 offset:11936
	ds_read_b128 v[186:189], v171 offset:11952
	s_waitcnt lgkmcnt(4)
	v_fmac_f32_e32 v108, v216, v190
	v_fmac_f32_e32 v108, v217, v191
	v_fmac_f32_e32 v108, v218, v192
	v_fmac_f32_e32 v108, v219, v193
	v_fmac_f32_e32 v108, v220, v194
	v_fmac_f32_e32 v108, v221, v195
	v_fmac_f32_e32 v108, v222, v196
	v_fmac_f32_e32 v108, v223, v197
	v_fmac_f32_e32 v108, v224, v232
	v_fmac_f32_e32 v108, v225, v233
	v_fmac_f32_e32 v108, v226, v234
	v_fmac_f32_e32 v108, v227, v235
	v_fmac_f32_e32 v108, v228, v236
	v_fmac_f32_e32 v108, v229, v237
	v_fmac_f32_e32 v108, v230, v238
	v_fmac_f32_e32 v108, v231, v239
	ds_read_b128 v[190:193], v171 offset:11968
	ds_read_b128 v[194:197], v171 offset:11984
	ds_read_b128 v[232:235], v171 offset:12000
	ds_read_b128 v[236:239], v171 offset:12016
	s_waitcnt lgkmcnt(4)
	v_fmac_f32_e32 v109, v200, v174
	v_fmac_f32_e32 v109, v201, v175
	v_fmac_f32_e32 v109, v202, v176
	v_fmac_f32_e32 v109, v203, v177
	v_fmac_f32_e32 v109, v204, v178
	v_fmac_f32_e32 v109, v205, v179
	v_fmac_f32_e32 v109, v206, v180
	v_fmac_f32_e32 v109, v207, v181
	v_fmac_f32_e32 v109, v208, v182
	v_fmac_f32_e32 v109, v209, v183
	v_fmac_f32_e32 v109, v210, v184
	v_fmac_f32_e32 v109, v211, v185
	v_fmac_f32_e32 v109, v212, v186
	v_fmac_f32_e32 v109, v213, v187
	v_fmac_f32_e32 v109, v214, v188
	v_fmac_f32_e32 v109, v215, v189
	ds_read_b128 v[174:177], v171 offset:12416
	ds_read_b128 v[178:181], v171 offset:12432
	ds_read_b128 v[182:185], v171 offset:12448
	ds_read_b128 v[186:189], v171 offset:12464
	s_waitcnt lgkmcnt(4)
	v_fmac_f32_e32 v109, v216, v190
	v_fmac_f32_e32 v109, v217, v191
	v_fmac_f32_e32 v109, v218, v192
	v_fmac_f32_e32 v109, v219, v193
	v_fmac_f32_e32 v109, v220, v194
	v_fmac_f32_e32 v109, v221, v195
	v_fmac_f32_e32 v109, v222, v196
	v_fmac_f32_e32 v109, v223, v197
	v_fmac_f32_e32 v109, v224, v232
	v_fmac_f32_e32 v109, v225, v233
	v_fmac_f32_e32 v109, v226, v234
	v_fmac_f32_e32 v109, v227, v235
	v_fmac_f32_e32 v109, v228, v236
	v_fmac_f32_e32 v109, v229, v237
	v_fmac_f32_e32 v109, v230, v238
	v_fmac_f32_e32 v109, v231, v239
	ds_read_b128 v[190:193], v171 offset:12480
	ds_read_b128 v[194:197], v171 offset:12496
	ds_read_b128 v[232:235], v171 offset:12512
	ds_read_b128 v[236:239], v171 offset:12528
	s_waitcnt lgkmcnt(4)
	v_fmac_f32_e32 v106, v200, v174
	v_fmac_f32_e32 v106, v201, v175
	v_fmac_f32_e32 v106, v202, v176
	v_fmac_f32_e32 v106, v203, v177
	v_fmac_f32_e32 v106, v204, v178
	v_fmac_f32_e32 v106, v205, v179
	v_fmac_f32_e32 v106, v206, v180
	v_fmac_f32_e32 v106, v207, v181
	v_fmac_f32_e32 v106, v208, v182
	v_fmac_f32_e32 v106, v209, v183
	v_fmac_f32_e32 v106, v210, v184
	v_fmac_f32_e32 v106, v211, v185
	v_fmac_f32_e32 v106, v212, v186
	v_fmac_f32_e32 v106, v213, v187
	v_fmac_f32_e32 v106, v214, v188
	v_fmac_f32_e32 v106, v215, v189
	ds_read_b128 v[174:177], v171 offset:12928
	ds_read_b128 v[178:181], v171 offset:12944
	ds_read_b128 v[182:185], v171 offset:12960
	ds_read_b128 v[186:189], v171 offset:12976
	s_waitcnt lgkmcnt(4)
	v_fmac_f32_e32 v106, v216, v190
	v_fmac_f32_e32 v106, v217, v191
	v_fmac_f32_e32 v106, v218, v192
	v_fmac_f32_e32 v106, v219, v193
	v_fmac_f32_e32 v106, v220, v194
	v_fmac_f32_e32 v106, v221, v195
	v_fmac_f32_e32 v106, v222, v196
	v_fmac_f32_e32 v106, v223, v197
	v_fmac_f32_e32 v106, v224, v232
	v_fmac_f32_e32 v106, v225, v233
	v_fmac_f32_e32 v106, v226, v234
	v_fmac_f32_e32 v106, v227, v235
	v_fmac_f32_e32 v106, v228, v236
	v_fmac_f32_e32 v106, v229, v237
	v_fmac_f32_e32 v106, v230, v238
	v_fmac_f32_e32 v106, v231, v239
	ds_read_b128 v[190:193], v171 offset:12992
	ds_read_b128 v[194:197], v171 offset:13008
	ds_read_b128 v[232:235], v171 offset:13024
	ds_read_b128 v[236:239], v171 offset:13040
	s_waitcnt lgkmcnt(4)
	v_fmac_f32_e32 v107, v200, v174
	v_fmac_f32_e32 v107, v201, v175
	v_fmac_f32_e32 v107, v202, v176
	v_fmac_f32_e32 v107, v203, v177
	v_fmac_f32_e32 v107, v204, v178
	v_fmac_f32_e32 v107, v205, v179
	v_fmac_f32_e32 v107, v206, v180
	v_fmac_f32_e32 v107, v207, v181
	v_fmac_f32_e32 v107, v208, v182
	v_fmac_f32_e32 v107, v209, v183
	v_fmac_f32_e32 v107, v210, v184
	v_fmac_f32_e32 v107, v211, v185
	v_fmac_f32_e32 v107, v212, v186
	v_fmac_f32_e32 v107, v213, v187
	v_fmac_f32_e32 v107, v214, v188
	v_fmac_f32_e32 v107, v215, v189
	ds_read_b128 v[174:177], v171 offset:13440
	ds_read_b128 v[178:181], v171 offset:13456
	ds_read_b128 v[182:185], v171 offset:13472
	ds_read_b128 v[186:189], v171 offset:13488
	s_waitcnt lgkmcnt(4)
	v_fmac_f32_e32 v107, v216, v190
	v_fmac_f32_e32 v107, v217, v191
	v_fmac_f32_e32 v107, v218, v192
	v_fmac_f32_e32 v107, v219, v193
	v_fmac_f32_e32 v107, v220, v194
	v_fmac_f32_e32 v107, v221, v195
	v_fmac_f32_e32 v107, v222, v196
	v_fmac_f32_e32 v107, v223, v197
	v_fmac_f32_e32 v107, v224, v232
	v_fmac_f32_e32 v107, v225, v233
	v_fmac_f32_e32 v107, v226, v234
	v_fmac_f32_e32 v107, v227, v235
	v_fmac_f32_e32 v107, v228, v236
	v_fmac_f32_e32 v107, v229, v237
	v_fmac_f32_e32 v107, v230, v238
	v_fmac_f32_e32 v107, v231, v239
	ds_read_b128 v[190:193], v171 offset:13504
	ds_read_b128 v[194:197], v171 offset:13520
	ds_read_b128 v[232:235], v171 offset:13536
	ds_read_b128 v[236:239], v171 offset:13552
	s_waitcnt lgkmcnt(4)
	v_fmac_f32_e32 v112, v200, v174
	v_fmac_f32_e32 v112, v201, v175
	v_fmac_f32_e32 v112, v202, v176
	v_fmac_f32_e32 v112, v203, v177
	v_fmac_f32_e32 v112, v204, v178
	v_fmac_f32_e32 v112, v205, v179
	v_fmac_f32_e32 v112, v206, v180
	v_fmac_f32_e32 v112, v207, v181
	v_fmac_f32_e32 v112, v208, v182
	v_fmac_f32_e32 v112, v209, v183
	v_fmac_f32_e32 v112, v210, v184
	v_fmac_f32_e32 v112, v211, v185
	v_fmac_f32_e32 v112, v212, v186
	v_fmac_f32_e32 v112, v213, v187
	v_fmac_f32_e32 v112, v214, v188
	v_fmac_f32_e32 v112, v215, v189
	ds_read_b128 v[174:177], v171 offset:13952
	ds_read_b128 v[178:181], v171 offset:13968
	ds_read_b128 v[182:185], v171 offset:13984
	ds_read_b128 v[186:189], v171 offset:14000
	s_waitcnt lgkmcnt(4)
	v_fmac_f32_e32 v112, v216, v190
	v_fmac_f32_e32 v112, v217, v191
	v_fmac_f32_e32 v112, v218, v192
	v_fmac_f32_e32 v112, v219, v193
	v_fmac_f32_e32 v112, v220, v194
	v_fmac_f32_e32 v112, v221, v195
	v_fmac_f32_e32 v112, v222, v196
	v_fmac_f32_e32 v112, v223, v197
	v_fmac_f32_e32 v112, v224, v232
	v_fmac_f32_e32 v112, v225, v233
	v_fmac_f32_e32 v112, v226, v234
	v_fmac_f32_e32 v112, v227, v235
	v_fmac_f32_e32 v112, v228, v236
	v_fmac_f32_e32 v112, v229, v237
	v_fmac_f32_e32 v112, v230, v238
	v_fmac_f32_e32 v112, v231, v239
	ds_read_b128 v[190:193], v171 offset:14016
	ds_read_b128 v[194:197], v171 offset:14032
	ds_read_b128 v[232:235], v171 offset:14048
	ds_read_b128 v[236:239], v171 offset:14064
	s_waitcnt lgkmcnt(4)
	v_fmac_f32_e32 v113, v200, v174
	v_fmac_f32_e32 v113, v201, v175
	v_fmac_f32_e32 v113, v202, v176
	v_fmac_f32_e32 v113, v203, v177
	v_fmac_f32_e32 v113, v204, v178
	v_fmac_f32_e32 v113, v205, v179
	v_fmac_f32_e32 v113, v206, v180
	v_fmac_f32_e32 v113, v207, v181
	v_fmac_f32_e32 v113, v208, v182
	v_fmac_f32_e32 v113, v209, v183
	v_fmac_f32_e32 v113, v210, v184
	v_fmac_f32_e32 v113, v211, v185
	v_fmac_f32_e32 v113, v212, v186
	v_fmac_f32_e32 v113, v213, v187
	v_fmac_f32_e32 v113, v214, v188
	v_fmac_f32_e32 v113, v215, v189
	ds_read_b128 v[174:177], v171 offset:14464
	ds_read_b128 v[178:181], v171 offset:14480
	ds_read_b128 v[182:185], v171 offset:14496
	ds_read_b128 v[186:189], v171 offset:14512
	s_waitcnt lgkmcnt(4)
	v_fmac_f32_e32 v113, v216, v190
	v_fmac_f32_e32 v113, v217, v191
	v_fmac_f32_e32 v113, v218, v192
	v_fmac_f32_e32 v113, v219, v193
	v_fmac_f32_e32 v113, v220, v194
	v_fmac_f32_e32 v113, v221, v195
	v_fmac_f32_e32 v113, v222, v196
	v_fmac_f32_e32 v113, v223, v197
	v_fmac_f32_e32 v113, v224, v232
	v_fmac_f32_e32 v113, v225, v233
	v_fmac_f32_e32 v113, v226, v234
	v_fmac_f32_e32 v113, v227, v235
	v_fmac_f32_e32 v113, v228, v236
	v_fmac_f32_e32 v113, v229, v237
	v_fmac_f32_e32 v113, v230, v238
	v_fmac_f32_e32 v113, v231, v239
	ds_read_b128 v[190:193], v171 offset:14528
	ds_read_b128 v[194:197], v171 offset:14544
	ds_read_b128 v[232:235], v171 offset:14560
	ds_read_b128 v[236:239], v171 offset:14576
	s_waitcnt lgkmcnt(4)
	v_fmac_f32_e32 v110, v200, v174
	v_fmac_f32_e32 v110, v201, v175
	v_fmac_f32_e32 v110, v202, v176
	v_fmac_f32_e32 v110, v203, v177
	v_fmac_f32_e32 v110, v204, v178
	v_fmac_f32_e32 v110, v205, v179
	v_fmac_f32_e32 v110, v206, v180
	v_fmac_f32_e32 v110, v207, v181
	v_fmac_f32_e32 v110, v208, v182
	v_fmac_f32_e32 v110, v209, v183
	v_fmac_f32_e32 v110, v210, v184
	v_fmac_f32_e32 v110, v211, v185
	v_fmac_f32_e32 v110, v212, v186
	v_fmac_f32_e32 v110, v213, v187
	v_fmac_f32_e32 v110, v214, v188
	v_fmac_f32_e32 v110, v215, v189
	ds_read_b128 v[174:177], v171 offset:14976
	ds_read_b128 v[178:181], v171 offset:14992
	ds_read_b128 v[182:185], v171 offset:15008
	ds_read_b128 v[186:189], v171 offset:15024
	s_waitcnt lgkmcnt(4)
	v_fmac_f32_e32 v110, v216, v190
	v_fmac_f32_e32 v110, v217, v191
	v_fmac_f32_e32 v110, v218, v192
	v_fmac_f32_e32 v110, v219, v193
	v_fmac_f32_e32 v110, v220, v194
	v_fmac_f32_e32 v110, v221, v195
	v_fmac_f32_e32 v110, v222, v196
	v_fmac_f32_e32 v110, v223, v197
	v_fmac_f32_e32 v110, v224, v232
	v_fmac_f32_e32 v110, v225, v233
	v_fmac_f32_e32 v110, v226, v234
	v_fmac_f32_e32 v110, v227, v235
	v_fmac_f32_e32 v110, v228, v236
	v_fmac_f32_e32 v110, v229, v237
	v_fmac_f32_e32 v110, v230, v238
	v_fmac_f32_e32 v110, v231, v239
	ds_read_b128 v[190:193], v171 offset:15040
	ds_read_b128 v[194:197], v171 offset:15056
	ds_read_b128 v[232:235], v171 offset:15072
	ds_read_b128 v[236:239], v171 offset:15088
	s_waitcnt lgkmcnt(4)
	v_fmac_f32_e32 v111, v200, v174
	v_fmac_f32_e32 v111, v201, v175
	v_fmac_f32_e32 v111, v202, v176
	v_fmac_f32_e32 v111, v203, v177
	v_fmac_f32_e32 v111, v204, v178
	v_fmac_f32_e32 v111, v205, v179
	v_fmac_f32_e32 v111, v206, v180
	v_fmac_f32_e32 v111, v207, v181
	v_fmac_f32_e32 v111, v208, v182
	v_fmac_f32_e32 v111, v209, v183
	v_fmac_f32_e32 v111, v210, v184
	v_fmac_f32_e32 v111, v211, v185
	v_fmac_f32_e32 v111, v212, v186
	v_fmac_f32_e32 v111, v213, v187
	v_fmac_f32_e32 v111, v214, v188
	v_fmac_f32_e32 v111, v215, v189
	ds_read_b128 v[174:177], v171 offset:15488
	ds_read_b128 v[178:181], v171 offset:15504
	ds_read_b128 v[182:185], v171 offset:15520
	ds_read_b128 v[186:189], v171 offset:15536
	s_waitcnt lgkmcnt(4)
	v_fmac_f32_e32 v111, v216, v190
	v_fmac_f32_e32 v111, v217, v191
	v_fmac_f32_e32 v111, v218, v192
	v_fmac_f32_e32 v111, v219, v193
	v_fmac_f32_e32 v111, v220, v194
	v_fmac_f32_e32 v111, v221, v195
	v_fmac_f32_e32 v111, v222, v196
	v_fmac_f32_e32 v111, v223, v197
	v_fmac_f32_e32 v111, v224, v232
	v_fmac_f32_e32 v111, v225, v233
	v_fmac_f32_e32 v111, v226, v234
	v_fmac_f32_e32 v111, v227, v235
	v_fmac_f32_e32 v111, v228, v236
	v_fmac_f32_e32 v111, v229, v237
	v_fmac_f32_e32 v111, v230, v238
	v_fmac_f32_e32 v111, v231, v239
	ds_read_b128 v[190:193], v171 offset:15552
	ds_read_b128 v[194:197], v171 offset:15568
	ds_read_b128 v[232:235], v171 offset:15584
	ds_read_b128 v[236:239], v171 offset:15600
	s_waitcnt lgkmcnt(4)
	v_fmac_f32_e32 v34, v200, v174
	v_fmac_f32_e32 v34, v201, v175
	v_fmac_f32_e32 v34, v202, v176
	v_fmac_f32_e32 v34, v203, v177
	v_fmac_f32_e32 v34, v204, v178
	v_fmac_f32_e32 v34, v205, v179
	v_fmac_f32_e32 v34, v206, v180
	v_fmac_f32_e32 v34, v207, v181
	v_fmac_f32_e32 v34, v208, v182
	v_fmac_f32_e32 v34, v209, v183
	v_fmac_f32_e32 v34, v210, v184
	v_fmac_f32_e32 v34, v211, v185
	v_fmac_f32_e32 v34, v212, v186
	v_fmac_f32_e32 v34, v213, v187
	v_fmac_f32_e32 v34, v214, v188
	v_fmac_f32_e32 v34, v215, v189
	ds_read_b128 v[174:177], v171 offset:16000
	ds_read_b128 v[178:181], v171 offset:16016
	ds_read_b128 v[182:185], v171 offset:16032
	ds_read_b128 v[186:189], v171 offset:16048
	s_waitcnt lgkmcnt(4)
	v_fmac_f32_e32 v34, v216, v190
	v_fmac_f32_e32 v34, v217, v191
	v_fmac_f32_e32 v34, v218, v192
	v_fmac_f32_e32 v34, v219, v193
	v_fmac_f32_e32 v34, v220, v194
	v_fmac_f32_e32 v34, v221, v195
	v_fmac_f32_e32 v34, v222, v196
	v_fmac_f32_e32 v34, v223, v197
	v_fmac_f32_e32 v34, v224, v232
	v_fmac_f32_e32 v34, v225, v233
	v_fmac_f32_e32 v34, v226, v234
	v_fmac_f32_e32 v34, v227, v235
	v_fmac_f32_e32 v34, v228, v236
	v_fmac_f32_e32 v34, v229, v237
	v_fmac_f32_e32 v34, v230, v238
	v_fmac_f32_e32 v34, v231, v239
	ds_read_b128 v[190:193], v171 offset:16064
	ds_read_b128 v[194:197], v171 offset:16080
	ds_read_b128 v[232:235], v171 offset:16096
	ds_read_b128 v[236:239], v171 offset:16112
	s_waitcnt lgkmcnt(4)
	v_fmac_f32_e32 v35, v200, v174
	v_fmac_f32_e32 v35, v201, v175
	v_fmac_f32_e32 v35, v202, v176
	v_fmac_f32_e32 v35, v203, v177
	v_fmac_f32_e32 v35, v204, v178
	v_fmac_f32_e32 v35, v205, v179
	v_fmac_f32_e32 v35, v206, v180
	v_fmac_f32_e32 v35, v207, v181
	v_fmac_f32_e32 v35, v208, v182
	v_fmac_f32_e32 v35, v209, v183
	v_fmac_f32_e32 v35, v210, v184
	v_fmac_f32_e32 v35, v211, v185
	v_fmac_f32_e32 v35, v212, v186
	v_fmac_f32_e32 v35, v213, v187
	v_fmac_f32_e32 v35, v214, v188
	v_fmac_f32_e32 v35, v215, v189
	s_waitcnt lgkmcnt(0)
	v_fmac_f32_e32 v35, v216, v190
	v_fmac_f32_e32 v35, v217, v191
	v_fmac_f32_e32 v35, v218, v192
	v_fmac_f32_e32 v35, v219, v193
	v_fmac_f32_e32 v35, v220, v194
	v_fmac_f32_e32 v35, v221, v195
	v_fmac_f32_e32 v35, v222, v196
	v_fmac_f32_e32 v35, v223, v197
	v_fmac_f32_e32 v35, v224, v232
	v_fmac_f32_e32 v35, v225, v233
	v_fmac_f32_e32 v35, v226, v234
	v_fmac_f32_e32 v35, v227, v235
	v_fmac_f32_e32 v35, v228, v236
	v_fmac_f32_e32 v35, v229, v237
	v_fmac_f32_e32 v35, v230, v238
	v_fmac_f32_e32 v35, v231, v239
	s_movk_i32 s0, 0x100
	s_mov_b32 s1, 0
	s_waitcnt lgkmcnt(0)
	v_add_u32_e32 v25, 0x400, v114
	ds_write2_b32 v114, v82, v83 offset1:66
	ds_write2_b32 v114, v86, v87 offset0:132 offset1:198
	ds_write2_b32 v25, v84, v85 offset0:8 offset1:74
	ds_write2_b32 v25, v90, v91 offset0:140 offset1:206
	v_add_u32_e32 v25, 0x800, v114
	ds_write2_b32 v25, v88, v89 offset0:16 offset1:82
	ds_write2_b32 v25, v94, v95 offset0:148 offset1:214
	v_add_u32_e32 v25, 0xc00, v114
	ds_write2_b32 v25, v92, v93 offset0:24 offset1:90
	ds_write2_b32 v25, v100, v101 offset0:156 offset1:222
	v_add_u32_e32 v25, 0x1000, v114
	ds_write2_b32 v25, v98, v99 offset0:32 offset1:98
	ds_write2_b32 v25, v104, v105 offset0:164 offset1:230
	v_add_u32_e32 v25, 0x1400, v114
	ds_write2_b32 v25, v102, v103 offset0:40 offset1:106
	ds_write2_b32 v25, v108, v109 offset0:172 offset1:238
	v_add_u32_e32 v25, 0x1800, v114
	ds_write2_b32 v25, v106, v107 offset0:48 offset1:114
	ds_write2_b32 v25, v112, v113 offset0:180 offset1:246
	v_add_u32_e32 v25, 0x1c00, v114
	ds_write2_b32 v25, v110, v111 offset0:56 offset1:122
	ds_write2_b32 v25, v34, v35 offset0:188 offset1:254
	s_waitcnt lgkmcnt(0)
	s_add_i32 s0, s46, 0xffffd000
	ds_read2_b32 v[28:29], v116 offset1:33
	s_lshl_b32 s1, s0, 5
	s_waitcnt lgkmcnt(0)
	v_cvt_pk_bf16_f32 v28, v28, v29
	ds_read2_b32 v[30:31], v116 offset0:66 offset1:99
	s_and_b32 s1, s1, 0x3e0
	s_waitcnt lgkmcnt(0)
	v_cvt_pk_bf16_f32 v29, v30, v31
	ds_read2_b32 v[30:31], v116 offset0:132 offset1:165
	v_or_b32_e32 v25, s1, v115
	s_waitcnt lgkmcnt(0)
	v_cvt_pk_bf16_f32 v30, v30, v31
	ds_read2_b32 v[32:33], v116 offset0:198 offset1:231
	v_lshlrev_b32_e32 v96, 11, v25
	s_lshl_b32 s0, s0, 2
	s_waitcnt lgkmcnt(0)
	v_cvt_pk_bf16_f32 v31, v32, v33
	v_lshl_add_u64 v[32:33], s[4:5], 0, v[96:97]
	s_and_b32 s16, s0, 0x180
	v_lshl_add_u64 v[32:33], v[32:33], 0, s[16:17]
	v_mov_b32_e32 v25, v97
	v_lshl_add_u64 v[32:33], v[32:33], 0, v[24:25]
	ds_read2_b32 v[34:35], v116 offset0:8 offset1:41
	global_store_dwordx4 v[32:33], v[28:31], off offset:1024
	s_waitcnt lgkmcnt(0)
	s_nop 0
	v_cvt_pk_bf16_f32 v28, v34, v35
	ds_read2_b32 v[30:31], v116 offset0:74 offset1:107
	s_waitcnt lgkmcnt(0)
	v_cvt_pk_bf16_f32 v29, v30, v31
	ds_read2_b32 v[30:31], v116 offset0:140 offset1:173
	s_waitcnt lgkmcnt(0)
	v_cvt_pk_bf16_f32 v30, v30, v31
	ds_read2_b32 v[32:33], v116 offset0:206 offset1:239
	s_waitcnt lgkmcnt(0)
	v_cvt_pk_bf16_f32 v31, v32, v33
	v_or_b32_e32 v32, s1, v117
	v_lshlrev_b32_e32 v96, 11, v32
	v_lshl_add_u64 v[34:35], s[4:5], 0, v[96:97]
	v_lshl_add_u64 v[34:35], v[34:35], 0, s[16:17]
	v_lshl_add_u64 v[34:35], v[34:35], 0, v[24:25]
	ds_read2_b32 v[32:33], v116 offset0:16 offset1:49
	global_store_dwordx4 v[34:35], v[28:31], off offset:1024
	s_waitcnt lgkmcnt(0)
	s_nop 0
	v_cvt_pk_bf16_f32 v28, v32, v33
	ds_read2_b32 v[30:31], v116 offset0:82 offset1:115
	s_waitcnt lgkmcnt(0)
	v_cvt_pk_bf16_f32 v29, v30, v31
	ds_read2_b32 v[30:31], v116 offset0:148 offset1:181
	s_waitcnt lgkmcnt(0)
	v_cvt_pk_bf16_f32 v30, v30, v31
	ds_read2_b32 v[32:33], v116 offset0:214 offset1:247
	s_waitcnt lgkmcnt(0)
	v_cvt_pk_bf16_f32 v31, v32, v33
	v_or_b32_e32 v32, s1, v118
	v_lshlrev_b32_e32 v96, 11, v32
	v_lshl_add_u64 v[34:35], s[4:5], 0, v[96:97]
	v_lshl_add_u64 v[34:35], v[34:35], 0, s[16:17]
	v_lshl_add_u64 v[34:35], v[34:35], 0, v[24:25]
	ds_read2_b32 v[32:33], v116 offset0:24 offset1:57
	global_store_dwordx4 v[34:35], v[28:31], off offset:1024
	s_waitcnt lgkmcnt(0)
	s_nop 0
	v_cvt_pk_bf16_f32 v28, v32, v33
	ds_read2_b32 v[30:31], v116 offset0:90 offset1:123
	s_waitcnt lgkmcnt(0)
	v_cvt_pk_bf16_f32 v29, v30, v31
	ds_read2_b32 v[30:31], v116 offset0:156 offset1:189
	s_waitcnt lgkmcnt(0)
	v_cvt_pk_bf16_f32 v30, v30, v31
	v_or_b32_e32 v31, s1, v119
	v_lshlrev_b32_e32 v96, 11, v31
	v_lshl_add_u64 v[34:35], s[4:5], 0, v[96:97]
	ds_read2_b32 v[32:33], v116 offset0:222 offset1:255
	v_lshl_add_u64 v[34:35], v[34:35], 0, s[16:17]
	s_waitcnt lgkmcnt(0)
	v_cvt_pk_bf16_f32 v31, v32, v33
	v_lshl_add_u64 v[32:33], v[34:35], 0, v[24:25]
	global_store_dwordx4 v[32:33], v[28:31], off offset:1024
	s_waitcnt lgkmcnt(0)
	s_mov_b64 s[0:1], 0
